# combo v046 + scalar-address (saddr) LDS-DMA loads in GEMM K-loops
# baseline (speedup 1.0000x reference)
.LBB0_237:
	s_or_b64 exec, exec, s[2:3]
	s_ashr_i32 s3, s9, 2
	s_lshr_b32 s2, s30, 3
	s_lshl_b32 s36, s3, 2
	s_ashr_i32 s23, s22, 31
	s_and_b32 s7, s29, 56
	s_and_b32 s31, s2, 3
	s_sub_i32 s8, s8, s36
	s_lshl_b64 s[2:3], s[22:23], 19
	s_add_u32 s2, s16, s2
	s_addc_u32 s3, s17, s3
	s_ashr_i32 s9, s8, 31
	v_mov_b32_e32 v8, v190
	s_lshl_b64 s[22:23], s[8:9], 19
	s_mov_b32 s9, 0x1ffff80
	v_and_b32_e32 v0, 15, v8
	v_lshrrev_b32_e32 v2, 1, v8
	v_and_or_b32 v0, v2, s9, v0
	v_bfe_u32 v1, v8, 4, 2
	v_lshlrev_b32_e32 v132, 7, v0
	v_bfe_u32 v0, v8, 1, 3
	v_bitop3_b32 v0, v1, v0, 4 bitop3:0x36
	v_lshlrev_b32_e32 v133, 4, v0
	v_lshlrev_b32_e32 v0, 7, v8
	v_and_b32_e32 v134, 0x6780, v0
	v_ashrrev_i32_e32 v0, 3, v8
	v_bitop3_b32 v2, v2, v1, 7 bitop3:0x6c
	v_ashrrev_i32_e32 v1, 31, v0
	v_lshrrev_b32_e32 v9, 4, v8
	v_lshlrev_b64 v[0:1], 11, v[0:1]
	s_add_u32 s34, s25, s22
	v_lshlrev_b32_e32 v135, 4, v2
	v_xor_b32_e32 v4, v9, v8
	v_lshl_add_u64 v[2:3], s[2:3], 0, v[0:1]
	v_readfirstlane_b32 s2, v8
	s_addc_u32 s35, s26, s23
	v_lshlrev_b32_e32 v4, 4, v4
	s_lshl_b32 s2, s2, 4
	v_and_b32_e32 v144, 0x70, v4
	s_and_b32 s2, s2, 0xfffffc00
	v_lshl_add_u64 v[2:3], v[2:3], 0, v[144:145]
	s_mov_b32 m0, s2
	s_mov_b64 s[38:39], 0x20000
	v_lshl_add_u64 v[4:5], s[34:35], 0, v[0:1]
	s_waitcnt lgkmcnt(0)
	s_barrier
	global_load_lds_dwordx4 v[2:3], off
	v_lshl_add_u64 v[6:7], v[2:3], 0, s[38:39]
	s_add_i32 m0, s2, 0x2000
	s_mov_b64 s[34:35], 0x40000
	global_load_lds_dwordx4 v[6:7], off
	v_lshl_add_u64 v[6:7], v[2:3], 0, s[34:35]
	s_add_i32 m0, s2, 0x4000
	s_mov_b64 s[40:41], 0x60000
	global_load_lds_dwordx4 v[6:7], off
	v_lshl_add_u64 v[2:3], v[2:3], 0, s[40:41]
	s_add_i32 m0, s2, 0x6000
	v_lshl_add_u64 v[4:5], v[4:5], 0, v[144:145]
	global_load_lds_dwordx4 v[2:3], off
	s_add_i32 m0, s2, 0x8000
	v_lshl_add_u64 v[2:3], v[4:5], 0, s[38:39]
	global_load_lds_dwordx4 v[4:5], off
	s_add_i32 m0, s2, 0xa000
	s_add_i32 s7, s7, s36
	global_load_lds_dwordx4 v[2:3], off
	v_lshl_add_u64 v[2:3], v[4:5], 0, s[34:35]
	s_add_i32 m0, s2, 0xc000
	global_load_lds_dwordx4 v[2:3], off
	v_lshl_add_u64 v[2:3], v[4:5], 0, s[40:41]
	s_add_i32 m0, s2, 0xe000
	v_bitop3_b32 v4, v9, 7, v8 bitop3:0x48
	global_load_lds_dwordx4 v[2:3], off
	v_lshl_add_u64 v[2:3], s[22:23], 0, v[0:1]
	s_or_b32 s22, s7, s31
	s_ashr_i32 s23, s22, 31
	s_lshl_b64 s[22:23], s[22:23], 19
	s_waitcnt vmcnt(0)
	v_lshlrev_b32_e32 v4, 4, v4
	v_lshl_add_u64 v[0:1], s[22:23], 0, v[0:1]
	v_or_b32_e32 v2, v2, v4
	v_or_b32_e32 v0, v0, v4
	s_mov_b64 s[86:87], 0x20000
	v_lshl_add_u64 v[128:129], s[14:15], 0, v[2:3]
	v_lshl_add_u64 v[130:131], s[14:15], 0, v[0:1]
	s_mov_b64 s[22:23], 0
	s_mov_b32 s3, 0
	s_mov_b64 s[36:37], 0x3a20080
	s_mov_b64 s[38:39], 0x3a40080
	s_waitcnt vmcnt(0) lgkmcnt(0)
	s_barrier
	v_readlane_b32 s50, v255, 24
	v_readlane_b32 s51, v255, 25
	s_nop 1
	v_subrev_u32_e32 v244, s50, v130
	v_subrev_u32_e32 v245, s50, v128
	s_bitcmp1_b32 s2, 12
	s_cbranch_scc1 .Lkb_238
	s_add_i32 s7, s3, 0x10000
	s_and_b32 s9, s7, 0x10000
	s_add_i32 s9, s2, s9
	s_add_u32 s48, s50, s22
	s_addc_u32 s49, s51, s23
	s_add_u32 s98, s48, s44
	s_addc_u32 s99, s49, s45
	s_mov_b32 m0, s9
	s_mov_b64 s[34:35], 0x2100080
	global_load_lds_dwordx4 v244, s[98:99]
	s_add_u32 s98, s48, s46
	s_addc_u32 s99, s49, s47
	s_add_i32 m0, s9, 0x2000
	s_nop 0
	global_load_lds_dwordx4 v244, s[98:99]
	s_add_u32 s98, s48, s36
	s_addc_u32 s99, s49, s37
	s_add_i32 m0, s9, 0x4000
	s_add_u32 s48, s48, s38
	s_addc_u32 s49, s49, s39
	global_load_lds_dwordx4 v244, s[98:99]
	s_add_i32 m0, s9, 0x6000
	s_nop 0
	global_load_lds_dwordx4 v244, s[48:49]
	s_add_u32 s48, s50, s22
	s_addc_u32 s49, s51, s23
	s_add_u32 s98, s48, s34
	s_addc_u32 s99, s49, s35
	s_add_i32 m0, s9, 0x8000
	s_mov_b64 s[34:35], 0x2120080
	global_load_lds_dwordx4 v245, s[98:99]
	s_add_u32 s98, s48, s34
	s_addc_u32 s99, s49, s35
	s_add_i32 m0, s9, 0xa000
	s_mov_b64 s[34:35], 0x2140080
	global_load_lds_dwordx4 v245, s[98:99]
	s_add_u32 s98, s48, s34
	s_addc_u32 s99, s49, s35
	s_add_i32 m0, s9, 0xc000
	s_mov_b64 s[34:35], 0x2160080
	global_load_lds_dwordx4 v245, s[98:99]
	s_add_u32 s48, s48, s34
	s_addc_u32 s49, s49, s35
	s_add_i32 m0, s9, 0xe000
	s_nop 0
	global_load_lds_dwordx4 v245, s[48:49]
	s_and_b32 s3, s3, 0x10000
	v_or_b32_e32 v144, s3, v135
	v_add_u32_e32 v151, v144, v134
	v_add_u32_e32 v144, v144, v132
	ds_read_b128 v[136:139], v151 offset:32768
	ds_read_b128 v[140:143], v151 offset:34816
	ds_read_b128 v[146:149], v151 offset:36864
	ds_read_b128 v[154:157], v151 offset:38912
	ds_read_b128 v[158:161], v144
	ds_read_b128 v[162:165], v144 offset:2048
	ds_read_b128 v[166:169], v144 offset:4096
	ds_read_b128 v[170:173], v144 offset:6144
	ds_read_b128 v[174:177], v144 offset:8192
	ds_read_b128 v[178:181], v144 offset:10240
	ds_read_b128 v[182:185], v144 offset:12288
	ds_read_b128 v[186:189], v144 offset:14336
	s_waitcnt lgkmcnt(0)
	v_mfma_f32_16x16x32_bf16 v[124:127], v[136:139], v[158:161], 0
	v_mfma_f32_16x16x32_bf16 v[120:123], v[140:143], v[158:161], 0
	v_mfma_f32_16x16x32_bf16 v[116:119], v[146:149], v[158:161], 0
	v_mfma_f32_16x16x32_bf16 v[112:115], v[154:157], v[158:161], 0
	v_mfma_f32_16x16x32_bf16 v[108:111], v[136:139], v[162:165], 0
	v_mfma_f32_16x16x32_bf16 v[104:107], v[140:143], v[162:165], 0
	v_mfma_f32_16x16x32_bf16 v[100:103], v[146:149], v[162:165], 0
	v_mfma_f32_16x16x32_bf16 v[96:99], v[154:157], v[162:165], 0
	v_mfma_f32_16x16x32_bf16 v[92:95], v[136:139], v[166:169], 0
	v_mfma_f32_16x16x32_bf16 v[84:87], v[140:143], v[166:169], 0
	v_mfma_f32_16x16x32_bf16 v[80:83], v[146:149], v[166:169], 0
	v_mfma_f32_16x16x32_bf16 v[76:79], v[154:157], v[166:169], 0
	v_mfma_f32_16x16x32_bf16 v[72:75], v[136:139], v[170:173], 0
	v_mfma_f32_16x16x32_bf16 v[68:71], v[140:143], v[170:173], 0
	v_mfma_f32_16x16x32_bf16 v[64:67], v[146:149], v[170:173], 0
	v_mfma_f32_16x16x32_bf16 v[60:63], v[154:157], v[170:173], 0
	v_or_b32_e32 v144, s3, v133
	v_add_u32_e32 v151, v144, v134
	v_add_u32_e32 v144, v144, v132
	ds_read_b128 v[158:161], v151 offset:32768
	ds_read_b128 v[162:165], v151 offset:34816
	ds_read_b128 v[166:169], v151 offset:36864
	ds_read_b128 v[170:173], v151 offset:38912
	ds_read_b128 v[206:209], v144
	ds_read_b128 v[216:219], v144 offset:2048
	ds_read_b128 v[220:223], v144 offset:4096
	ds_read_b128 v[224:227], v144 offset:6144
	v_mfma_f32_16x16x32_bf16 v[56:59], v[136:139], v[174:177], 0
	v_mfma_f32_16x16x32_bf16 v[52:55], v[140:143], v[174:177], 0
	v_mfma_f32_16x16x32_bf16 v[48:51], v[146:149], v[174:177], 0
	v_mfma_f32_16x16x32_bf16 v[44:47], v[154:157], v[174:177], 0
	v_mfma_f32_16x16x32_bf16 v[40:43], v[136:139], v[178:181], 0
	v_mfma_f32_16x16x32_bf16 v[36:39], v[140:143], v[178:181], 0
	v_mfma_f32_16x16x32_bf16 v[32:35], v[146:149], v[178:181], 0
	v_mfma_f32_16x16x32_bf16 v[28:31], v[154:157], v[178:181], 0
	v_mfma_f32_16x16x32_bf16 v[24:27], v[136:139], v[182:185], 0
	v_mfma_f32_16x16x32_bf16 v[20:23], v[140:143], v[182:185], 0
	v_mfma_f32_16x16x32_bf16 v[16:19], v[146:149], v[182:185], 0
	v_mfma_f32_16x16x32_bf16 v[12:15], v[154:157], v[182:185], 0
	v_mfma_f32_16x16x32_bf16 v[8:11], v[136:139], v[186:189], 0
	v_mfma_f32_16x16x32_bf16 v[4:7], v[140:143], v[186:189], 0
	v_mfma_f32_16x16x32_bf16 v[0:3], v[146:149], v[186:189], 0
	v_mfma_f32_16x16x32_bf16 v[88:91], v[154:157], v[186:189], 0
	ds_read_b128 v[136:139], v144 offset:8192
	ds_read_b128 v[140:143], v144 offset:10240
	ds_read_b128 v[146:149], v144 offset:12288
	ds_read_b128 v[154:157], v144 offset:14336
	s_waitcnt lgkmcnt(0)
	v_mfma_f32_16x16x32_bf16 v[124:127], v[158:161], v[206:209], v[124:127]
	v_mfma_f32_16x16x32_bf16 v[120:123], v[162:165], v[206:209], v[120:123]
	v_mfma_f32_16x16x32_bf16 v[116:119], v[166:169], v[206:209], v[116:119]
	v_mfma_f32_16x16x32_bf16 v[112:115], v[170:173], v[206:209], v[112:115]
	v_mfma_f32_16x16x32_bf16 v[108:111], v[158:161], v[216:219], v[108:111]
	v_mfma_f32_16x16x32_bf16 v[104:107], v[162:165], v[216:219], v[104:107]
	v_mfma_f32_16x16x32_bf16 v[100:103], v[166:169], v[216:219], v[100:103]
	v_mfma_f32_16x16x32_bf16 v[96:99], v[170:173], v[216:219], v[96:99]
	v_mfma_f32_16x16x32_bf16 v[92:95], v[158:161], v[220:223], v[92:95]
	v_mfma_f32_16x16x32_bf16 v[84:87], v[162:165], v[220:223], v[84:87]
	v_mfma_f32_16x16x32_bf16 v[80:83], v[166:169], v[220:223], v[80:83]
	v_mfma_f32_16x16x32_bf16 v[76:79], v[170:173], v[220:223], v[76:79]
	v_mfma_f32_16x16x32_bf16 v[72:75], v[158:161], v[224:227], v[72:75]
	v_mfma_f32_16x16x32_bf16 v[68:71], v[162:165], v[224:227], v[68:71]
	v_mfma_f32_16x16x32_bf16 v[64:67], v[166:169], v[224:227], v[64:67]
	v_mfma_f32_16x16x32_bf16 v[60:63], v[170:173], v[224:227], v[60:63]
	v_mfma_f32_16x16x32_bf16 v[56:59], v[158:161], v[136:139], v[56:59]
	s_add_u32 s22, s22, 0x80
	s_addc_u32 s23, s23, 0
	v_mfma_f32_16x16x32_bf16 v[52:55], v[162:165], v[136:139], v[52:55]
	s_cmpk_eq_i32 s22, 0x780
	s_mov_b32 s3, s7
	s_waitcnt vmcnt(0)
	v_mfma_f32_16x16x32_bf16 v[48:51], v[166:169], v[136:139], v[48:51]
	s_barrier
	v_mfma_f32_16x16x32_bf16 v[44:47], v[170:173], v[136:139], v[44:47]
	v_mfma_f32_16x16x32_bf16 v[40:43], v[158:161], v[140:143], v[40:43]
	v_mfma_f32_16x16x32_bf16 v[36:39], v[162:165], v[140:143], v[36:39]
	v_mfma_f32_16x16x32_bf16 v[32:35], v[166:169], v[140:143], v[32:35]
	v_mfma_f32_16x16x32_bf16 v[28:31], v[170:173], v[140:143], v[28:31]
	v_mfma_f32_16x16x32_bf16 v[24:27], v[158:161], v[146:149], v[24:27]
	v_mfma_f32_16x16x32_bf16 v[20:23], v[162:165], v[146:149], v[20:23]
	v_mfma_f32_16x16x32_bf16 v[16:19], v[166:169], v[146:149], v[16:19]
	v_mfma_f32_16x16x32_bf16 v[12:15], v[170:173], v[146:149], v[12:15]
	v_mfma_f32_16x16x32_bf16 v[8:11], v[158:161], v[154:157], v[8:11]
	v_mfma_f32_16x16x32_bf16 v[4:7], v[162:165], v[154:157], v[4:7]
	v_mfma_f32_16x16x32_bf16 v[0:3], v[166:169], v[154:157], v[0:3]
	v_mfma_f32_16x16x32_bf16 v[88:91], v[170:173], v[154:157], v[88:91]
	s_cbranch_scc1 .Lkx_238
.LBB0_238:
	s_add_i32 s7, s3, 0x10000
	s_and_b32 s9, s7, 0x10000
	s_add_i32 s9, s2, s9
	s_add_u32 s48, s50, s22
	s_addc_u32 s49, s51, s23
	s_add_u32 s98, s48, s44
	s_addc_u32 s99, s49, s45
	s_mov_b32 m0, s9
	s_mov_b64 s[34:35], 0x2100080
	global_load_lds_dwordx4 v244, s[98:99]
	s_add_u32 s98, s48, s46
	s_addc_u32 s99, s49, s47
	s_add_i32 m0, s9, 0x2000
	s_nop 0
	global_load_lds_dwordx4 v244, s[98:99]
	s_add_u32 s98, s48, s36
	s_addc_u32 s99, s49, s37
	s_add_i32 m0, s9, 0x4000
	s_add_u32 s48, s48, s38
	s_addc_u32 s49, s49, s39
	global_load_lds_dwordx4 v244, s[98:99]
	s_add_i32 m0, s9, 0x6000
	s_nop 0
	global_load_lds_dwordx4 v244, s[48:49]
	s_add_u32 s48, s50, s22
	s_addc_u32 s49, s51, s23
	s_add_u32 s98, s48, s34
	s_addc_u32 s99, s49, s35
	s_add_i32 m0, s9, 0x8000
	s_mov_b64 s[34:35], 0x2120080
	global_load_lds_dwordx4 v245, s[98:99]
	s_add_u32 s98, s48, s34
	s_addc_u32 s99, s49, s35
	s_add_i32 m0, s9, 0xa000
	s_mov_b64 s[34:35], 0x2140080
	global_load_lds_dwordx4 v245, s[98:99]
	s_add_u32 s98, s48, s34
	s_addc_u32 s99, s49, s35
	s_add_i32 m0, s9, 0xc000
	s_mov_b64 s[34:35], 0x2160080
	global_load_lds_dwordx4 v245, s[98:99]
	s_add_u32 s48, s48, s34
	s_addc_u32 s49, s49, s35
	s_add_i32 m0, s9, 0xe000
	s_nop 0
	global_load_lds_dwordx4 v245, s[48:49]
	s_and_b32 s3, s3, 0x10000
	v_or_b32_e32 v144, s3, v135
	v_add_u32_e32 v151, v144, v134
	v_add_u32_e32 v144, v144, v132
	ds_read_b128 v[136:139], v151 offset:32768
	ds_read_b128 v[140:143], v151 offset:34816
	ds_read_b128 v[146:149], v151 offset:36864
	ds_read_b128 v[154:157], v151 offset:38912
	ds_read_b128 v[158:161], v144
	ds_read_b128 v[162:165], v144 offset:2048
	ds_read_b128 v[166:169], v144 offset:4096
	ds_read_b128 v[170:173], v144 offset:6144
	ds_read_b128 v[174:177], v144 offset:8192
	ds_read_b128 v[178:181], v144 offset:10240
	ds_read_b128 v[182:185], v144 offset:12288
	ds_read_b128 v[186:189], v144 offset:14336
	s_waitcnt lgkmcnt(0)
	v_mfma_f32_16x16x32_bf16 v[124:127], v[136:139], v[158:161], v[124:127]
	v_mfma_f32_16x16x32_bf16 v[120:123], v[140:143], v[158:161], v[120:123]
	v_mfma_f32_16x16x32_bf16 v[116:119], v[146:149], v[158:161], v[116:119]
	v_mfma_f32_16x16x32_bf16 v[112:115], v[154:157], v[158:161], v[112:115]
	v_mfma_f32_16x16x32_bf16 v[108:111], v[136:139], v[162:165], v[108:111]
	v_mfma_f32_16x16x32_bf16 v[104:107], v[140:143], v[162:165], v[104:107]
	v_mfma_f32_16x16x32_bf16 v[100:103], v[146:149], v[162:165], v[100:103]
	v_mfma_f32_16x16x32_bf16 v[96:99], v[154:157], v[162:165], v[96:99]
	v_mfma_f32_16x16x32_bf16 v[92:95], v[136:139], v[166:169], v[92:95]
	v_mfma_f32_16x16x32_bf16 v[84:87], v[140:143], v[166:169], v[84:87]
	v_mfma_f32_16x16x32_bf16 v[80:83], v[146:149], v[166:169], v[80:83]
	v_mfma_f32_16x16x32_bf16 v[76:79], v[154:157], v[166:169], v[76:79]
	v_mfma_f32_16x16x32_bf16 v[72:75], v[136:139], v[170:173], v[72:75]
	v_mfma_f32_16x16x32_bf16 v[68:71], v[140:143], v[170:173], v[68:71]
	v_mfma_f32_16x16x32_bf16 v[64:67], v[146:149], v[170:173], v[64:67]
	v_mfma_f32_16x16x32_bf16 v[60:63], v[154:157], v[170:173], v[60:63]
	v_or_b32_e32 v144, s3, v133
	v_add_u32_e32 v151, v144, v134
	v_add_u32_e32 v144, v144, v132
	ds_read_b128 v[158:161], v151 offset:32768
	ds_read_b128 v[162:165], v151 offset:34816
	ds_read_b128 v[166:169], v151 offset:36864
	ds_read_b128 v[170:173], v151 offset:38912
	ds_read_b128 v[206:209], v144
	ds_read_b128 v[216:219], v144 offset:2048
	ds_read_b128 v[220:223], v144 offset:4096
	ds_read_b128 v[224:227], v144 offset:6144
	v_mfma_f32_16x16x32_bf16 v[56:59], v[136:139], v[174:177], v[56:59]
	v_mfma_f32_16x16x32_bf16 v[52:55], v[140:143], v[174:177], v[52:55]
	v_mfma_f32_16x16x32_bf16 v[48:51], v[146:149], v[174:177], v[48:51]
	v_mfma_f32_16x16x32_bf16 v[44:47], v[154:157], v[174:177], v[44:47]
	v_mfma_f32_16x16x32_bf16 v[40:43], v[136:139], v[178:181], v[40:43]
	v_mfma_f32_16x16x32_bf16 v[36:39], v[140:143], v[178:181], v[36:39]
	v_mfma_f32_16x16x32_bf16 v[32:35], v[146:149], v[178:181], v[32:35]
	v_mfma_f32_16x16x32_bf16 v[28:31], v[154:157], v[178:181], v[28:31]
	v_mfma_f32_16x16x32_bf16 v[24:27], v[136:139], v[182:185], v[24:27]
	v_mfma_f32_16x16x32_bf16 v[20:23], v[140:143], v[182:185], v[20:23]
	v_mfma_f32_16x16x32_bf16 v[16:19], v[146:149], v[182:185], v[16:19]
	v_mfma_f32_16x16x32_bf16 v[12:15], v[154:157], v[182:185], v[12:15]
	v_mfma_f32_16x16x32_bf16 v[8:11], v[136:139], v[186:189], v[8:11]
	v_mfma_f32_16x16x32_bf16 v[4:7], v[140:143], v[186:189], v[4:7]
	v_mfma_f32_16x16x32_bf16 v[0:3], v[146:149], v[186:189], v[0:3]
	v_mfma_f32_16x16x32_bf16 v[88:91], v[154:157], v[186:189], v[88:91]
	ds_read_b128 v[136:139], v144 offset:8192
	ds_read_b128 v[140:143], v144 offset:10240
	ds_read_b128 v[146:149], v144 offset:12288
	ds_read_b128 v[154:157], v144 offset:14336
	s_waitcnt lgkmcnt(0)
	v_mfma_f32_16x16x32_bf16 v[124:127], v[158:161], v[206:209], v[124:127]
	v_mfma_f32_16x16x32_bf16 v[120:123], v[162:165], v[206:209], v[120:123]
	v_mfma_f32_16x16x32_bf16 v[116:119], v[166:169], v[206:209], v[116:119]
	v_mfma_f32_16x16x32_bf16 v[112:115], v[170:173], v[206:209], v[112:115]
	v_mfma_f32_16x16x32_bf16 v[108:111], v[158:161], v[216:219], v[108:111]
	v_mfma_f32_16x16x32_bf16 v[104:107], v[162:165], v[216:219], v[104:107]
	v_mfma_f32_16x16x32_bf16 v[100:103], v[166:169], v[216:219], v[100:103]
	v_mfma_f32_16x16x32_bf16 v[96:99], v[170:173], v[216:219], v[96:99]
	v_mfma_f32_16x16x32_bf16 v[92:95], v[158:161], v[220:223], v[92:95]
	v_mfma_f32_16x16x32_bf16 v[84:87], v[162:165], v[220:223], v[84:87]
	v_mfma_f32_16x16x32_bf16 v[80:83], v[166:169], v[220:223], v[80:83]
	v_mfma_f32_16x16x32_bf16 v[76:79], v[170:173], v[220:223], v[76:79]
	v_mfma_f32_16x16x32_bf16 v[72:75], v[158:161], v[224:227], v[72:75]
	v_mfma_f32_16x16x32_bf16 v[68:71], v[162:165], v[224:227], v[68:71]
	v_mfma_f32_16x16x32_bf16 v[64:67], v[166:169], v[224:227], v[64:67]
	v_mfma_f32_16x16x32_bf16 v[60:63], v[170:173], v[224:227], v[60:63]
	v_mfma_f32_16x16x32_bf16 v[56:59], v[158:161], v[136:139], v[56:59]
	s_add_u32 s22, s22, 0x80
	s_addc_u32 s23, s23, 0
	v_mfma_f32_16x16x32_bf16 v[52:55], v[162:165], v[136:139], v[52:55]
	s_cmpk_eq_i32 s22, 0x780
	s_mov_b32 s3, s7
	s_waitcnt vmcnt(0)
	v_mfma_f32_16x16x32_bf16 v[48:51], v[166:169], v[136:139], v[48:51]
	s_barrier
	v_mfma_f32_16x16x32_bf16 v[44:47], v[170:173], v[136:139], v[44:47]
	v_mfma_f32_16x16x32_bf16 v[40:43], v[158:161], v[140:143], v[40:43]
	v_mfma_f32_16x16x32_bf16 v[36:39], v[162:165], v[140:143], v[36:39]
	v_mfma_f32_16x16x32_bf16 v[32:35], v[166:169], v[140:143], v[32:35]
	v_mfma_f32_16x16x32_bf16 v[28:31], v[170:173], v[140:143], v[28:31]
	v_mfma_f32_16x16x32_bf16 v[24:27], v[158:161], v[146:149], v[24:27]
	v_mfma_f32_16x16x32_bf16 v[20:23], v[162:165], v[146:149], v[20:23]
	v_mfma_f32_16x16x32_bf16 v[16:19], v[166:169], v[146:149], v[16:19]
	v_mfma_f32_16x16x32_bf16 v[12:15], v[170:173], v[146:149], v[12:15]
	v_mfma_f32_16x16x32_bf16 v[8:11], v[158:161], v[154:157], v[8:11]
	v_mfma_f32_16x16x32_bf16 v[4:7], v[162:165], v[154:157], v[4:7]
	v_mfma_f32_16x16x32_bf16 v[0:3], v[166:169], v[154:157], v[0:3]
	v_mfma_f32_16x16x32_bf16 v[88:91], v[170:173], v[154:157], v[88:91]
	s_cbranch_scc0 .LBB0_238
	s_branch .Lkx_238
.Lkb_238:
	s_add_i32 s7, s3, 0x10000
	s_and_b32 s9, s7, 0x10000
	s_add_i32 s9, s2, s9
	s_and_b32 s3, s3, 0x10000
	v_or_b32_e32 v144, s3, v135
	v_add_u32_e32 v151, v144, v134
	v_add_u32_e32 v144, v144, v132
	ds_read_b128 v[136:139], v151 offset:32768
	ds_read_b128 v[140:143], v151 offset:34816
	ds_read_b128 v[146:149], v151 offset:36864
	ds_read_b128 v[154:157], v151 offset:38912
	ds_read_b128 v[158:161], v144
	ds_read_b128 v[162:165], v144 offset:2048
	ds_read_b128 v[166:169], v144 offset:4096
	ds_read_b128 v[170:173], v144 offset:6144
	ds_read_b128 v[174:177], v144 offset:8192
	ds_read_b128 v[178:181], v144 offset:10240
	ds_read_b128 v[182:185], v144 offset:12288
	ds_read_b128 v[186:189], v144 offset:14336
	s_waitcnt lgkmcnt(0)
	v_mfma_f32_16x16x32_bf16 v[124:127], v[136:139], v[158:161], 0
	v_mfma_f32_16x16x32_bf16 v[120:123], v[140:143], v[158:161], 0
	v_mfma_f32_16x16x32_bf16 v[116:119], v[146:149], v[158:161], 0
	v_mfma_f32_16x16x32_bf16 v[112:115], v[154:157], v[158:161], 0
	v_mfma_f32_16x16x32_bf16 v[108:111], v[136:139], v[162:165], 0
	v_mfma_f32_16x16x32_bf16 v[104:107], v[140:143], v[162:165], 0
	v_mfma_f32_16x16x32_bf16 v[100:103], v[146:149], v[162:165], 0
	v_mfma_f32_16x16x32_bf16 v[96:99], v[154:157], v[162:165], 0
	v_mfma_f32_16x16x32_bf16 v[92:95], v[136:139], v[166:169], 0
	v_mfma_f32_16x16x32_bf16 v[84:87], v[140:143], v[166:169], 0
	v_mfma_f32_16x16x32_bf16 v[80:83], v[146:149], v[166:169], 0
	v_mfma_f32_16x16x32_bf16 v[76:79], v[154:157], v[166:169], 0
	v_mfma_f32_16x16x32_bf16 v[72:75], v[136:139], v[170:173], 0
	v_mfma_f32_16x16x32_bf16 v[68:71], v[140:143], v[170:173], 0
	v_mfma_f32_16x16x32_bf16 v[64:67], v[146:149], v[170:173], 0
	v_mfma_f32_16x16x32_bf16 v[60:63], v[154:157], v[170:173], 0
	v_or_b32_e32 v144, s3, v133
	v_add_u32_e32 v151, v144, v134
	v_add_u32_e32 v144, v144, v132
	ds_read_b128 v[158:161], v151 offset:32768
	ds_read_b128 v[162:165], v151 offset:34816
	ds_read_b128 v[166:169], v151 offset:36864
	ds_read_b128 v[170:173], v151 offset:38912
	ds_read_b128 v[206:209], v144
	ds_read_b128 v[216:219], v144 offset:2048
	ds_read_b128 v[220:223], v144 offset:4096
	ds_read_b128 v[224:227], v144 offset:6144
	v_mfma_f32_16x16x32_bf16 v[56:59], v[136:139], v[174:177], 0
	v_mfma_f32_16x16x32_bf16 v[52:55], v[140:143], v[174:177], 0
	v_mfma_f32_16x16x32_bf16 v[48:51], v[146:149], v[174:177], 0
	v_mfma_f32_16x16x32_bf16 v[44:47], v[154:157], v[174:177], 0
	v_mfma_f32_16x16x32_bf16 v[40:43], v[136:139], v[178:181], 0
	v_mfma_f32_16x16x32_bf16 v[36:39], v[140:143], v[178:181], 0
	v_mfma_f32_16x16x32_bf16 v[32:35], v[146:149], v[178:181], 0
	v_mfma_f32_16x16x32_bf16 v[28:31], v[154:157], v[178:181], 0
	v_mfma_f32_16x16x32_bf16 v[24:27], v[136:139], v[182:185], 0
	v_mfma_f32_16x16x32_bf16 v[20:23], v[140:143], v[182:185], 0
	v_mfma_f32_16x16x32_bf16 v[16:19], v[146:149], v[182:185], 0
	v_mfma_f32_16x16x32_bf16 v[12:15], v[154:157], v[182:185], 0
	v_mfma_f32_16x16x32_bf16 v[8:11], v[136:139], v[186:189], 0
	v_mfma_f32_16x16x32_bf16 v[4:7], v[140:143], v[186:189], 0
	v_mfma_f32_16x16x32_bf16 v[0:3], v[146:149], v[186:189], 0
	v_mfma_f32_16x16x32_bf16 v[88:91], v[154:157], v[186:189], 0
	s_add_u32 s48, s50, s22
	s_addc_u32 s49, s51, s23
	s_add_u32 s98, s48, s44
	s_addc_u32 s99, s49, s45
	s_mov_b32 m0, s9
	s_mov_b64 s[34:35], 0x2100080
	global_load_lds_dwordx4 v244, s[98:99]
	s_add_u32 s98, s48, s46
	s_addc_u32 s99, s49, s47
	s_add_i32 m0, s9, 0x2000
	s_nop 0
	global_load_lds_dwordx4 v244, s[98:99]
	s_add_u32 s98, s48, s36
	s_addc_u32 s99, s49, s37
	s_add_i32 m0, s9, 0x4000
	s_add_u32 s48, s48, s38
	s_addc_u32 s49, s49, s39
	global_load_lds_dwordx4 v244, s[98:99]
	s_add_i32 m0, s9, 0x6000
	s_nop 0
	global_load_lds_dwordx4 v244, s[48:49]
	s_add_u32 s48, s50, s22
	s_addc_u32 s49, s51, s23
	s_add_u32 s98, s48, s34
	s_addc_u32 s99, s49, s35
	s_add_i32 m0, s9, 0x8000
	s_mov_b64 s[34:35], 0x2120080
	global_load_lds_dwordx4 v245, s[98:99]
	s_add_u32 s98, s48, s34
	s_addc_u32 s99, s49, s35
	s_add_i32 m0, s9, 0xa000
	s_mov_b64 s[34:35], 0x2140080
	global_load_lds_dwordx4 v245, s[98:99]
	s_add_u32 s98, s48, s34
	s_addc_u32 s99, s49, s35
	s_add_i32 m0, s9, 0xc000
	s_mov_b64 s[34:35], 0x2160080
	global_load_lds_dwordx4 v245, s[98:99]
	s_add_u32 s48, s48, s34
	s_addc_u32 s49, s49, s35
	s_add_i32 m0, s9, 0xe000
	s_nop 0
	global_load_lds_dwordx4 v245, s[48:49]
	ds_read_b128 v[136:139], v144 offset:8192
	ds_read_b128 v[140:143], v144 offset:10240
	ds_read_b128 v[146:149], v144 offset:12288
	ds_read_b128 v[154:157], v144 offset:14336
	s_waitcnt lgkmcnt(0)
	v_mfma_f32_16x16x32_bf16 v[124:127], v[158:161], v[206:209], v[124:127]
	v_mfma_f32_16x16x32_bf16 v[120:123], v[162:165], v[206:209], v[120:123]
	v_mfma_f32_16x16x32_bf16 v[116:119], v[166:169], v[206:209], v[116:119]
	v_mfma_f32_16x16x32_bf16 v[112:115], v[170:173], v[206:209], v[112:115]
	v_mfma_f32_16x16x32_bf16 v[108:111], v[158:161], v[216:219], v[108:111]
	v_mfma_f32_16x16x32_bf16 v[104:107], v[162:165], v[216:219], v[104:107]
	v_mfma_f32_16x16x32_bf16 v[100:103], v[166:169], v[216:219], v[100:103]
	v_mfma_f32_16x16x32_bf16 v[96:99], v[170:173], v[216:219], v[96:99]
	v_mfma_f32_16x16x32_bf16 v[92:95], v[158:161], v[220:223], v[92:95]
	v_mfma_f32_16x16x32_bf16 v[84:87], v[162:165], v[220:223], v[84:87]
	v_mfma_f32_16x16x32_bf16 v[80:83], v[166:169], v[220:223], v[80:83]
	v_mfma_f32_16x16x32_bf16 v[76:79], v[170:173], v[220:223], v[76:79]
	v_mfma_f32_16x16x32_bf16 v[72:75], v[158:161], v[224:227], v[72:75]
	v_mfma_f32_16x16x32_bf16 v[68:71], v[162:165], v[224:227], v[68:71]
	v_mfma_f32_16x16x32_bf16 v[64:67], v[166:169], v[224:227], v[64:67]
	v_mfma_f32_16x16x32_bf16 v[60:63], v[170:173], v[224:227], v[60:63]
	v_mfma_f32_16x16x32_bf16 v[56:59], v[158:161], v[136:139], v[56:59]
	s_add_u32 s22, s22, 0x80
	s_addc_u32 s23, s23, 0
	v_mfma_f32_16x16x32_bf16 v[52:55], v[162:165], v[136:139], v[52:55]
	s_cmpk_eq_i32 s22, 0x780
	s_mov_b32 s3, s7
	s_waitcnt vmcnt(0)
	v_mfma_f32_16x16x32_bf16 v[48:51], v[166:169], v[136:139], v[48:51]
	s_barrier
	v_mfma_f32_16x16x32_bf16 v[44:47], v[170:173], v[136:139], v[44:47]
	v_mfma_f32_16x16x32_bf16 v[40:43], v[158:161], v[140:143], v[40:43]
	v_mfma_f32_16x16x32_bf16 v[36:39], v[162:165], v[140:143], v[36:39]
	v_mfma_f32_16x16x32_bf16 v[32:35], v[166:169], v[140:143], v[32:35]
	v_mfma_f32_16x16x32_bf16 v[28:31], v[170:173], v[140:143], v[28:31]
	v_mfma_f32_16x16x32_bf16 v[24:27], v[158:161], v[146:149], v[24:27]
	v_mfma_f32_16x16x32_bf16 v[20:23], v[162:165], v[146:149], v[20:23]
	v_mfma_f32_16x16x32_bf16 v[16:19], v[166:169], v[146:149], v[16:19]
	v_mfma_f32_16x16x32_bf16 v[12:15], v[170:173], v[146:149], v[12:15]
	v_mfma_f32_16x16x32_bf16 v[8:11], v[158:161], v[154:157], v[8:11]
	v_mfma_f32_16x16x32_bf16 v[4:7], v[162:165], v[154:157], v[4:7]
	v_mfma_f32_16x16x32_bf16 v[0:3], v[166:169], v[154:157], v[0:3]
	v_mfma_f32_16x16x32_bf16 v[88:91], v[170:173], v[154:157], v[88:91]
	s_cbranch_scc1 .Lkx_238
.Lkb_238_l:
	s_add_i32 s7, s3, 0x10000
	s_and_b32 s9, s7, 0x10000
	s_add_i32 s9, s2, s9
	s_and_b32 s3, s3, 0x10000
	v_or_b32_e32 v144, s3, v135
	v_add_u32_e32 v151, v144, v134
	v_add_u32_e32 v144, v144, v132
	ds_read_b128 v[136:139], v151 offset:32768
	ds_read_b128 v[140:143], v151 offset:34816
	ds_read_b128 v[146:149], v151 offset:36864
	ds_read_b128 v[154:157], v151 offset:38912
	ds_read_b128 v[158:161], v144
	ds_read_b128 v[162:165], v144 offset:2048
	ds_read_b128 v[166:169], v144 offset:4096
	ds_read_b128 v[170:173], v144 offset:6144
	ds_read_b128 v[174:177], v144 offset:8192
	ds_read_b128 v[178:181], v144 offset:10240
	ds_read_b128 v[182:185], v144 offset:12288
	ds_read_b128 v[186:189], v144 offset:14336
	s_waitcnt lgkmcnt(0)
	v_mfma_f32_16x16x32_bf16 v[124:127], v[136:139], v[158:161], v[124:127]
	v_mfma_f32_16x16x32_bf16 v[120:123], v[140:143], v[158:161], v[120:123]
	v_mfma_f32_16x16x32_bf16 v[116:119], v[146:149], v[158:161], v[116:119]
	v_mfma_f32_16x16x32_bf16 v[112:115], v[154:157], v[158:161], v[112:115]
	v_mfma_f32_16x16x32_bf16 v[108:111], v[136:139], v[162:165], v[108:111]
	v_mfma_f32_16x16x32_bf16 v[104:107], v[140:143], v[162:165], v[104:107]
	v_mfma_f32_16x16x32_bf16 v[100:103], v[146:149], v[162:165], v[100:103]
	v_mfma_f32_16x16x32_bf16 v[96:99], v[154:157], v[162:165], v[96:99]
	v_mfma_f32_16x16x32_bf16 v[92:95], v[136:139], v[166:169], v[92:95]
	v_mfma_f32_16x16x32_bf16 v[84:87], v[140:143], v[166:169], v[84:87]
	v_mfma_f32_16x16x32_bf16 v[80:83], v[146:149], v[166:169], v[80:83]
	v_mfma_f32_16x16x32_bf16 v[76:79], v[154:157], v[166:169], v[76:79]
	v_mfma_f32_16x16x32_bf16 v[72:75], v[136:139], v[170:173], v[72:75]
	v_mfma_f32_16x16x32_bf16 v[68:71], v[140:143], v[170:173], v[68:71]
	v_mfma_f32_16x16x32_bf16 v[64:67], v[146:149], v[170:173], v[64:67]
	v_mfma_f32_16x16x32_bf16 v[60:63], v[154:157], v[170:173], v[60:63]
	v_or_b32_e32 v144, s3, v133
	v_add_u32_e32 v151, v144, v134
	v_add_u32_e32 v144, v144, v132
	ds_read_b128 v[158:161], v151 offset:32768
	ds_read_b128 v[162:165], v151 offset:34816
	ds_read_b128 v[166:169], v151 offset:36864
	ds_read_b128 v[170:173], v151 offset:38912
	ds_read_b128 v[206:209], v144
	ds_read_b128 v[216:219], v144 offset:2048
	ds_read_b128 v[220:223], v144 offset:4096
	ds_read_b128 v[224:227], v144 offset:6144
	v_mfma_f32_16x16x32_bf16 v[56:59], v[136:139], v[174:177], v[56:59]
	v_mfma_f32_16x16x32_bf16 v[52:55], v[140:143], v[174:177], v[52:55]
	v_mfma_f32_16x16x32_bf16 v[48:51], v[146:149], v[174:177], v[48:51]
	v_mfma_f32_16x16x32_bf16 v[44:47], v[154:157], v[174:177], v[44:47]
	v_mfma_f32_16x16x32_bf16 v[40:43], v[136:139], v[178:181], v[40:43]
	v_mfma_f32_16x16x32_bf16 v[36:39], v[140:143], v[178:181], v[36:39]
	v_mfma_f32_16x16x32_bf16 v[32:35], v[146:149], v[178:181], v[32:35]
	v_mfma_f32_16x16x32_bf16 v[28:31], v[154:157], v[178:181], v[28:31]
	v_mfma_f32_16x16x32_bf16 v[24:27], v[136:139], v[182:185], v[24:27]
	v_mfma_f32_16x16x32_bf16 v[20:23], v[140:143], v[182:185], v[20:23]
	v_mfma_f32_16x16x32_bf16 v[16:19], v[146:149], v[182:185], v[16:19]
	v_mfma_f32_16x16x32_bf16 v[12:15], v[154:157], v[182:185], v[12:15]
	v_mfma_f32_16x16x32_bf16 v[8:11], v[136:139], v[186:189], v[8:11]
	v_mfma_f32_16x16x32_bf16 v[4:7], v[140:143], v[186:189], v[4:7]
	v_mfma_f32_16x16x32_bf16 v[0:3], v[146:149], v[186:189], v[0:3]
	v_mfma_f32_16x16x32_bf16 v[88:91], v[154:157], v[186:189], v[88:91]
	s_add_u32 s48, s50, s22
	s_addc_u32 s49, s51, s23
	s_add_u32 s98, s48, s44
	s_addc_u32 s99, s49, s45
	s_mov_b32 m0, s9
	s_mov_b64 s[34:35], 0x2100080
	global_load_lds_dwordx4 v244, s[98:99]
	s_add_u32 s98, s48, s46
	s_addc_u32 s99, s49, s47
	s_add_i32 m0, s9, 0x2000
	s_nop 0
	global_load_lds_dwordx4 v244, s[98:99]
	s_add_u32 s98, s48, s36
	s_addc_u32 s99, s49, s37
	s_add_i32 m0, s9, 0x4000
	s_add_u32 s48, s48, s38
	s_addc_u32 s49, s49, s39
	global_load_lds_dwordx4 v244, s[98:99]
	s_add_i32 m0, s9, 0x6000
	s_nop 0
	global_load_lds_dwordx4 v244, s[48:49]
	s_add_u32 s48, s50, s22
	s_addc_u32 s49, s51, s23
	s_add_u32 s98, s48, s34
	s_addc_u32 s99, s49, s35
	s_add_i32 m0, s9, 0x8000
	s_mov_b64 s[34:35], 0x2120080
	global_load_lds_dwordx4 v245, s[98:99]
	s_add_u32 s98, s48, s34
	s_addc_u32 s99, s49, s35
	s_add_i32 m0, s9, 0xa000
	s_mov_b64 s[34:35], 0x2140080
	global_load_lds_dwordx4 v245, s[98:99]
	s_add_u32 s98, s48, s34
	s_addc_u32 s99, s49, s35
	s_add_i32 m0, s9, 0xc000
	s_mov_b64 s[34:35], 0x2160080
	global_load_lds_dwordx4 v245, s[98:99]
	s_add_u32 s48, s48, s34
	s_addc_u32 s49, s49, s35
	s_add_i32 m0, s9, 0xe000
	s_nop 0
	global_load_lds_dwordx4 v245, s[48:49]
	ds_read_b128 v[136:139], v144 offset:8192
	ds_read_b128 v[140:143], v144 offset:10240
	ds_read_b128 v[146:149], v144 offset:12288
	ds_read_b128 v[154:157], v144 offset:14336
	s_waitcnt lgkmcnt(0)
	v_mfma_f32_16x16x32_bf16 v[124:127], v[158:161], v[206:209], v[124:127]
	v_mfma_f32_16x16x32_bf16 v[120:123], v[162:165], v[206:209], v[120:123]
	v_mfma_f32_16x16x32_bf16 v[116:119], v[166:169], v[206:209], v[116:119]
	v_mfma_f32_16x16x32_bf16 v[112:115], v[170:173], v[206:209], v[112:115]
	v_mfma_f32_16x16x32_bf16 v[108:111], v[158:161], v[216:219], v[108:111]
	v_mfma_f32_16x16x32_bf16 v[104:107], v[162:165], v[216:219], v[104:107]
	v_mfma_f32_16x16x32_bf16 v[100:103], v[166:169], v[216:219], v[100:103]
	v_mfma_f32_16x16x32_bf16 v[96:99], v[170:173], v[216:219], v[96:99]
	v_mfma_f32_16x16x32_bf16 v[92:95], v[158:161], v[220:223], v[92:95]
	v_mfma_f32_16x16x32_bf16 v[84:87], v[162:165], v[220:223], v[84:87]
	v_mfma_f32_16x16x32_bf16 v[80:83], v[166:169], v[220:223], v[80:83]
	v_mfma_f32_16x16x32_bf16 v[76:79], v[170:173], v[220:223], v[76:79]
	v_mfma_f32_16x16x32_bf16 v[72:75], v[158:161], v[224:227], v[72:75]
	v_mfma_f32_16x16x32_bf16 v[68:71], v[162:165], v[224:227], v[68:71]
	v_mfma_f32_16x16x32_bf16 v[64:67], v[166:169], v[224:227], v[64:67]
	v_mfma_f32_16x16x32_bf16 v[60:63], v[170:173], v[224:227], v[60:63]
	v_mfma_f32_16x16x32_bf16 v[56:59], v[158:161], v[136:139], v[56:59]
	s_add_u32 s22, s22, 0x80
	s_addc_u32 s23, s23, 0
	v_mfma_f32_16x16x32_bf16 v[52:55], v[162:165], v[136:139], v[52:55]
	s_cmpk_eq_i32 s22, 0x780
	s_mov_b32 s3, s7
	s_waitcnt vmcnt(0)
	v_mfma_f32_16x16x32_bf16 v[48:51], v[166:169], v[136:139], v[48:51]
	s_barrier
	v_mfma_f32_16x16x32_bf16 v[44:47], v[170:173], v[136:139], v[44:47]
	v_mfma_f32_16x16x32_bf16 v[40:43], v[158:161], v[140:143], v[40:43]
	v_mfma_f32_16x16x32_bf16 v[36:39], v[162:165], v[140:143], v[36:39]
	v_mfma_f32_16x16x32_bf16 v[32:35], v[166:169], v[140:143], v[32:35]
	v_mfma_f32_16x16x32_bf16 v[28:31], v[170:173], v[140:143], v[28:31]
	v_mfma_f32_16x16x32_bf16 v[24:27], v[158:161], v[146:149], v[24:27]
	v_mfma_f32_16x16x32_bf16 v[20:23], v[162:165], v[146:149], v[20:23]
	v_mfma_f32_16x16x32_bf16 v[16:19], v[166:169], v[146:149], v[16:19]
	v_mfma_f32_16x16x32_bf16 v[12:15], v[170:173], v[146:149], v[12:15]
	v_mfma_f32_16x16x32_bf16 v[8:11], v[158:161], v[154:157], v[8:11]
	v_mfma_f32_16x16x32_bf16 v[4:7], v[162:165], v[154:157], v[4:7]
	v_mfma_f32_16x16x32_bf16 v[0:3], v[166:169], v[154:157], v[0:3]
	v_mfma_f32_16x16x32_bf16 v[88:91], v[170:173], v[154:157], v[88:91]
	s_cbranch_scc0 .Lkb_238_l

.LBB0_245:
	s_ashr_i32 s2, s28, 5
	s_lshr_b32 s3, s2, 30
	s_add_i32 s3, s2, s3
	s_and_b32 s31, s3, -4
	s_sub_i32 s18, s2, s31
	s_lshl_b32 s2, s28, 3
	s_and_b32 s2, s2, 56
	s_bfe_u32 s30, s28, 0x20003
	s_add_i32 s2, s31, s2
	s_or_b32 s22, s2, s30
	s_ashr_i32 s23, s22, 31
	s_and_b32 s29, s27, 56
	s_lshl_b64 s[2:3], s[22:23], 19
	s_add_u32 s2, s6, s2
	s_addc_u32 s3, s7, s3
	s_ashr_i32 s19, s18, 31
	v_mov_b32_e32 v6, v190
	s_lshl_b64 s[24:25], s[18:19], 19
	s_mov_b32 s19, 0x1ffff80
	v_and_b32_e32 v0, 15, v6
	v_lshrrev_b32_e32 v2, 1, v6
	v_and_or_b32 v0, v2, s19, v0
	s_waitcnt lgkmcnt(0)
	v_bfe_u32 v1, v6, 4, 2
	v_lshlrev_b32_e32 v132, 7, v0
	v_bfe_u32 v0, v6, 1, 3
	v_bitop3_b32 v0, v1, v0, 4 bitop3:0x36
	v_lshlrev_b32_e32 v133, 4, v0
	v_lshlrev_b32_e32 v0, 7, v6
	v_and_b32_e32 v134, 0x6780, v0
	v_ashrrev_i32_e32 v0, 3, v6
	v_bitop3_b32 v2, v2, v1, 7 bitop3:0x6c
	v_ashrrev_i32_e32 v1, 31, v0
	v_lshrrev_b32_e32 v7, 4, v6
	v_lshlrev_b64 v[0:1], 11, v[0:1]
	s_add_u32 s24, s0, s24
	v_lshlrev_b32_e32 v135, 4, v2
	v_xor_b32_e32 v4, v7, v6
	v_lshl_add_u64 v[2:3], s[2:3], 0, v[0:1]
	v_readfirstlane_b32 s2, v6
	s_addc_u32 s25, s26, s25
	v_lshlrev_b32_e32 v4, 4, v4
	s_lshl_b32 s2, s2, 4
	v_and_b32_e32 v144, 0x70, v4
	s_and_b32 s2, s2, 0xfffffc00
	v_lshl_add_u64 v[2:3], v[2:3], 0, v[144:145]
	v_lshl_add_u64 v[4:5], s[24:25], 0, v[0:1]
	s_mov_b32 m0, s2
	s_mov_b64 s[34:35], 0x20000
	v_lshl_add_u64 v[128:129], v[4:5], 0, v[144:145]
	s_waitcnt lgkmcnt(0)
	s_barrier
	global_load_lds_dwordx4 v[2:3], off
	v_lshl_add_u64 v[4:5], v[2:3], 0, s[34:35]
	s_add_i32 m0, s2, 0x2000
	s_mov_b64 s[24:25], 0x40000
	global_load_lds_dwordx4 v[4:5], off
	v_lshl_add_u64 v[4:5], v[2:3], 0, s[24:25]
	s_add_i32 m0, s2, 0x4000
	s_mov_b64 s[36:37], 0x60000
	global_load_lds_dwordx4 v[4:5], off
	v_lshl_add_u64 v[2:3], v[2:3], 0, s[36:37]
	s_add_i32 m0, s2, 0x6000
	s_add_i32 s29, s29, s31
	global_load_lds_dwordx4 v[2:3], off
	s_add_i32 m0, s2, 0x8000
	v_lshl_add_u64 v[2:3], v[128:129], 0, s[34:35]
	global_load_lds_dwordx4 v[128:129], off
	s_add_i32 m0, s2, 0xa000
	global_load_lds_dwordx4 v[2:3], off
	v_lshl_add_u64 v[2:3], v[128:129], 0, s[24:25]
	s_add_i32 m0, s2, 0xc000
	s_or_b32 s24, s29, s30
	global_load_lds_dwordx4 v[2:3], off
	v_lshl_add_u64 v[2:3], v[128:129], 0, s[36:37]
	s_add_i32 m0, s2, 0xe000
	s_ashr_i32 s25, s24, 31
	global_load_lds_dwordx4 v[2:3], off
	s_lshl_b64 s[24:25], s[24:25], 19
	s_waitcnt vmcnt(0)
	v_lshl_add_u64 v[0:1], s[24:25], 0, v[0:1]
	v_bitop3_b32 v2, v7, 7, v6 bitop3:0x48
	v_lshl_or_b32 v0, v2, 4, v0
	s_mov_b64 s[86:87], 0x20000
	v_lshl_add_u64 v[130:131], s[6:7], 0, v[0:1]
	s_mov_b64 s[24:25], 0
	s_mov_b32 s3, 0
	s_waitcnt vmcnt(0) lgkmcnt(0)
	s_barrier
	v_readlane_b32 s50, v255, 24
	v_readlane_b32 s51, v255, 25
	s_nop 1
	v_subrev_u32_e32 v244, s50, v130
	v_subrev_u32_e32 v245, s50, v128
	s_bitcmp1_b32 s2, 12
	s_cbranch_scc1 .Lkb_246
	s_add_i32 s19, s3, 0x10000
	s_and_b32 s23, s19, 0x10000
	s_add_i32 s23, s2, s23
	s_add_u32 s48, s50, s24
	s_addc_u32 s49, s51, s25
	s_add_u32 s98, s48, s10
	s_addc_u32 s99, s49, s11
	s_mov_b32 m0, s23
	s_nop 0
	global_load_lds_dwordx4 v244, s[98:99]
	s_add_u32 s98, s48, s4
	s_addc_u32 s99, s49, s5
	s_add_i32 m0, s23, 0x2000
	s_nop 0
	global_load_lds_dwordx4 v244, s[98:99]
	s_add_u32 s98, s48, s92
	s_addc_u32 s99, s49, s93
	s_add_i32 m0, s23, 0x4000
	s_add_u32 s48, s48, s94
	s_addc_u32 s49, s49, s95
	global_load_lds_dwordx4 v244, s[98:99]
	s_add_i32 m0, s23, 0x6000
	s_nop 0
	global_load_lds_dwordx4 v244, s[48:49]
	s_add_u32 s48, s50, s24
	s_addc_u32 s49, s51, s25
	s_add_u32 s98, s48, s10
	s_addc_u32 s99, s49, s11
	s_add_i32 m0, s23, 0x8000
	s_nop 0
	global_load_lds_dwordx4 v245, s[98:99]
	s_add_u32 s98, s48, s4
	s_addc_u32 s99, s49, s5
	s_add_i32 m0, s23, 0xa000
	s_nop 0
	global_load_lds_dwordx4 v245, s[98:99]
	s_add_u32 s98, s48, s92
	s_addc_u32 s99, s49, s93
	s_add_i32 m0, s23, 0xc000
	s_add_u32 s48, s48, s94
	s_addc_u32 s49, s49, s95
	global_load_lds_dwordx4 v245, s[98:99]
	s_add_i32 m0, s23, 0xe000
	s_nop 0
	global_load_lds_dwordx4 v245, s[48:49]
	s_and_b32 s3, s3, 0x10000
	v_or_b32_e32 v144, s3, v135
	v_add_u32_e32 v151, v144, v134
	v_add_u32_e32 v144, v144, v132
	ds_read_b128 v[136:139], v151 offset:32768
	ds_read_b128 v[140:143], v151 offset:34816
	ds_read_b128 v[146:149], v151 offset:36864
	ds_read_b128 v[154:157], v151 offset:38912
	ds_read_b128 v[158:161], v144
	ds_read_b128 v[162:165], v144 offset:2048
	ds_read_b128 v[166:169], v144 offset:4096
	ds_read_b128 v[170:173], v144 offset:6144
	ds_read_b128 v[174:177], v144 offset:8192
	ds_read_b128 v[178:181], v144 offset:10240
	ds_read_b128 v[182:185], v144 offset:12288
	ds_read_b128 v[186:189], v144 offset:14336
	s_waitcnt lgkmcnt(0)
	v_mfma_f32_16x16x32_bf16 v[124:127], v[136:139], v[158:161], 0
	v_mfma_f32_16x16x32_bf16 v[120:123], v[140:143], v[158:161], 0
	v_mfma_f32_16x16x32_bf16 v[116:119], v[146:149], v[158:161], 0
	v_mfma_f32_16x16x32_bf16 v[112:115], v[154:157], v[158:161], 0
	v_mfma_f32_16x16x32_bf16 v[108:111], v[136:139], v[162:165], 0
	v_mfma_f32_16x16x32_bf16 v[104:107], v[140:143], v[162:165], 0
	v_mfma_f32_16x16x32_bf16 v[100:103], v[146:149], v[162:165], 0
	v_mfma_f32_16x16x32_bf16 v[96:99], v[154:157], v[162:165], 0
	v_mfma_f32_16x16x32_bf16 v[92:95], v[136:139], v[166:169], 0
	v_mfma_f32_16x16x32_bf16 v[84:87], v[140:143], v[166:169], 0
	v_mfma_f32_16x16x32_bf16 v[80:83], v[146:149], v[166:169], 0
	v_mfma_f32_16x16x32_bf16 v[76:79], v[154:157], v[166:169], 0
	v_mfma_f32_16x16x32_bf16 v[72:75], v[136:139], v[170:173], 0
	v_mfma_f32_16x16x32_bf16 v[68:71], v[140:143], v[170:173], 0
	v_mfma_f32_16x16x32_bf16 v[64:67], v[146:149], v[170:173], 0
	v_mfma_f32_16x16x32_bf16 v[60:63], v[154:157], v[170:173], 0
	v_or_b32_e32 v144, s3, v133
	v_add_u32_e32 v151, v144, v134
	v_add_u32_e32 v144, v144, v132
	ds_read_b128 v[158:161], v151 offset:32768
	ds_read_b128 v[162:165], v151 offset:34816
	ds_read_b128 v[166:169], v151 offset:36864
	ds_read_b128 v[170:173], v151 offset:38912
	ds_read_b128 v[206:209], v144
	ds_read_b128 v[216:219], v144 offset:2048
	ds_read_b128 v[220:223], v144 offset:4096
	ds_read_b128 v[224:227], v144 offset:6144
	v_mfma_f32_16x16x32_bf16 v[56:59], v[136:139], v[174:177], 0
	v_mfma_f32_16x16x32_bf16 v[52:55], v[140:143], v[174:177], 0
	v_mfma_f32_16x16x32_bf16 v[48:51], v[146:149], v[174:177], 0
	v_mfma_f32_16x16x32_bf16 v[44:47], v[154:157], v[174:177], 0
	v_mfma_f32_16x16x32_bf16 v[40:43], v[136:139], v[178:181], 0
	v_mfma_f32_16x16x32_bf16 v[36:39], v[140:143], v[178:181], 0
	v_mfma_f32_16x16x32_bf16 v[32:35], v[146:149], v[178:181], 0
	v_mfma_f32_16x16x32_bf16 v[28:31], v[154:157], v[178:181], 0
	v_mfma_f32_16x16x32_bf16 v[24:27], v[136:139], v[182:185], 0
	v_mfma_f32_16x16x32_bf16 v[20:23], v[140:143], v[182:185], 0
	v_mfma_f32_16x16x32_bf16 v[16:19], v[146:149], v[182:185], 0
	v_mfma_f32_16x16x32_bf16 v[12:15], v[154:157], v[182:185], 0
	v_mfma_f32_16x16x32_bf16 v[8:11], v[136:139], v[186:189], 0
	v_mfma_f32_16x16x32_bf16 v[4:7], v[140:143], v[186:189], 0
	v_mfma_f32_16x16x32_bf16 v[0:3], v[146:149], v[186:189], 0
	v_mfma_f32_16x16x32_bf16 v[88:91], v[154:157], v[186:189], 0
	ds_read_b128 v[136:139], v144 offset:8192
	ds_read_b128 v[140:143], v144 offset:10240
	ds_read_b128 v[146:149], v144 offset:12288
	ds_read_b128 v[154:157], v144 offset:14336
	s_waitcnt lgkmcnt(0)
	v_mfma_f32_16x16x32_bf16 v[124:127], v[158:161], v[206:209], v[124:127]
	v_mfma_f32_16x16x32_bf16 v[120:123], v[162:165], v[206:209], v[120:123]
	v_mfma_f32_16x16x32_bf16 v[116:119], v[166:169], v[206:209], v[116:119]
	v_mfma_f32_16x16x32_bf16 v[112:115], v[170:173], v[206:209], v[112:115]
	v_mfma_f32_16x16x32_bf16 v[108:111], v[158:161], v[216:219], v[108:111]
	v_mfma_f32_16x16x32_bf16 v[104:107], v[162:165], v[216:219], v[104:107]
	v_mfma_f32_16x16x32_bf16 v[100:103], v[166:169], v[216:219], v[100:103]
	v_mfma_f32_16x16x32_bf16 v[96:99], v[170:173], v[216:219], v[96:99]
	v_mfma_f32_16x16x32_bf16 v[92:95], v[158:161], v[220:223], v[92:95]
	v_mfma_f32_16x16x32_bf16 v[84:87], v[162:165], v[220:223], v[84:87]
	v_mfma_f32_16x16x32_bf16 v[80:83], v[166:169], v[220:223], v[80:83]
	v_mfma_f32_16x16x32_bf16 v[76:79], v[170:173], v[220:223], v[76:79]
	v_mfma_f32_16x16x32_bf16 v[72:75], v[158:161], v[224:227], v[72:75]
	v_mfma_f32_16x16x32_bf16 v[68:71], v[162:165], v[224:227], v[68:71]
	v_mfma_f32_16x16x32_bf16 v[64:67], v[166:169], v[224:227], v[64:67]
	v_mfma_f32_16x16x32_bf16 v[60:63], v[170:173], v[224:227], v[60:63]
	v_mfma_f32_16x16x32_bf16 v[56:59], v[158:161], v[136:139], v[56:59]
	s_add_u32 s24, s24, 0x80
	s_addc_u32 s25, s25, 0
	v_mfma_f32_16x16x32_bf16 v[52:55], v[162:165], v[136:139], v[52:55]
	s_cmpk_eq_i32 s24, 0x780
	s_mov_b32 s3, s19
	s_waitcnt vmcnt(0)
	v_mfma_f32_16x16x32_bf16 v[48:51], v[166:169], v[136:139], v[48:51]
	s_barrier
	v_mfma_f32_16x16x32_bf16 v[44:47], v[170:173], v[136:139], v[44:47]
	v_mfma_f32_16x16x32_bf16 v[40:43], v[158:161], v[140:143], v[40:43]
	v_mfma_f32_16x16x32_bf16 v[36:39], v[162:165], v[140:143], v[36:39]
	v_mfma_f32_16x16x32_bf16 v[32:35], v[166:169], v[140:143], v[32:35]
	v_mfma_f32_16x16x32_bf16 v[28:31], v[170:173], v[140:143], v[28:31]
	v_mfma_f32_16x16x32_bf16 v[24:27], v[158:161], v[146:149], v[24:27]
	v_mfma_f32_16x16x32_bf16 v[20:23], v[162:165], v[146:149], v[20:23]
	v_mfma_f32_16x16x32_bf16 v[16:19], v[166:169], v[146:149], v[16:19]
	v_mfma_f32_16x16x32_bf16 v[12:15], v[170:173], v[146:149], v[12:15]
	v_mfma_f32_16x16x32_bf16 v[8:11], v[158:161], v[154:157], v[8:11]
	v_mfma_f32_16x16x32_bf16 v[4:7], v[162:165], v[154:157], v[4:7]
	v_mfma_f32_16x16x32_bf16 v[0:3], v[166:169], v[154:157], v[0:3]
	v_mfma_f32_16x16x32_bf16 v[88:91], v[170:173], v[154:157], v[88:91]
	s_cbranch_scc1 .Lkx_246
.LBB0_246:
	s_add_i32 s19, s3, 0x10000
	s_and_b32 s23, s19, 0x10000
	s_add_i32 s23, s2, s23
	s_add_u32 s48, s50, s24
	s_addc_u32 s49, s51, s25
	s_add_u32 s98, s48, s10
	s_addc_u32 s99, s49, s11
	s_mov_b32 m0, s23
	s_nop 0
	global_load_lds_dwordx4 v244, s[98:99]
	s_add_u32 s98, s48, s4
	s_addc_u32 s99, s49, s5
	s_add_i32 m0, s23, 0x2000
	s_nop 0
	global_load_lds_dwordx4 v244, s[98:99]
	s_add_u32 s98, s48, s92
	s_addc_u32 s99, s49, s93
	s_add_i32 m0, s23, 0x4000
	s_add_u32 s48, s48, s94
	s_addc_u32 s49, s49, s95
	global_load_lds_dwordx4 v244, s[98:99]
	s_add_i32 m0, s23, 0x6000
	s_nop 0
	global_load_lds_dwordx4 v244, s[48:49]
	s_add_u32 s48, s50, s24
	s_addc_u32 s49, s51, s25
	s_add_u32 s98, s48, s10
	s_addc_u32 s99, s49, s11
	s_add_i32 m0, s23, 0x8000
	s_nop 0
	global_load_lds_dwordx4 v245, s[98:99]
	s_add_u32 s98, s48, s4
	s_addc_u32 s99, s49, s5
	s_add_i32 m0, s23, 0xa000
	s_nop 0
	global_load_lds_dwordx4 v245, s[98:99]
	s_add_u32 s98, s48, s92
	s_addc_u32 s99, s49, s93
	s_add_i32 m0, s23, 0xc000
	s_add_u32 s48, s48, s94
	s_addc_u32 s49, s49, s95
	global_load_lds_dwordx4 v245, s[98:99]
	s_add_i32 m0, s23, 0xe000
	s_nop 0
	global_load_lds_dwordx4 v245, s[48:49]
	s_and_b32 s3, s3, 0x10000
	v_or_b32_e32 v144, s3, v135
	v_add_u32_e32 v151, v144, v134
	v_add_u32_e32 v144, v144, v132
	ds_read_b128 v[136:139], v151 offset:32768
	ds_read_b128 v[140:143], v151 offset:34816
	ds_read_b128 v[146:149], v151 offset:36864
	ds_read_b128 v[154:157], v151 offset:38912
	ds_read_b128 v[158:161], v144
	ds_read_b128 v[162:165], v144 offset:2048
	ds_read_b128 v[166:169], v144 offset:4096
	ds_read_b128 v[170:173], v144 offset:6144
	ds_read_b128 v[174:177], v144 offset:8192
	ds_read_b128 v[178:181], v144 offset:10240
	ds_read_b128 v[182:185], v144 offset:12288
	ds_read_b128 v[186:189], v144 offset:14336
	s_waitcnt lgkmcnt(0)
	v_mfma_f32_16x16x32_bf16 v[124:127], v[136:139], v[158:161], v[124:127]
	v_mfma_f32_16x16x32_bf16 v[120:123], v[140:143], v[158:161], v[120:123]
	v_mfma_f32_16x16x32_bf16 v[116:119], v[146:149], v[158:161], v[116:119]
	v_mfma_f32_16x16x32_bf16 v[112:115], v[154:157], v[158:161], v[112:115]
	v_mfma_f32_16x16x32_bf16 v[108:111], v[136:139], v[162:165], v[108:111]
	v_mfma_f32_16x16x32_bf16 v[104:107], v[140:143], v[162:165], v[104:107]
	v_mfma_f32_16x16x32_bf16 v[100:103], v[146:149], v[162:165], v[100:103]
	v_mfma_f32_16x16x32_bf16 v[96:99], v[154:157], v[162:165], v[96:99]
	v_mfma_f32_16x16x32_bf16 v[92:95], v[136:139], v[166:169], v[92:95]
	v_mfma_f32_16x16x32_bf16 v[84:87], v[140:143], v[166:169], v[84:87]
	v_mfma_f32_16x16x32_bf16 v[80:83], v[146:149], v[166:169], v[80:83]
	v_mfma_f32_16x16x32_bf16 v[76:79], v[154:157], v[166:169], v[76:79]
	v_mfma_f32_16x16x32_bf16 v[72:75], v[136:139], v[170:173], v[72:75]
	v_mfma_f32_16x16x32_bf16 v[68:71], v[140:143], v[170:173], v[68:71]
	v_mfma_f32_16x16x32_bf16 v[64:67], v[146:149], v[170:173], v[64:67]
	v_mfma_f32_16x16x32_bf16 v[60:63], v[154:157], v[170:173], v[60:63]
	v_or_b32_e32 v144, s3, v133
	v_add_u32_e32 v151, v144, v134
	v_add_u32_e32 v144, v144, v132
	ds_read_b128 v[158:161], v151 offset:32768
	ds_read_b128 v[162:165], v151 offset:34816
	ds_read_b128 v[166:169], v151 offset:36864
	ds_read_b128 v[170:173], v151 offset:38912
	ds_read_b128 v[206:209], v144
	ds_read_b128 v[216:219], v144 offset:2048
	ds_read_b128 v[220:223], v144 offset:4096
	ds_read_b128 v[224:227], v144 offset:6144
	v_mfma_f32_16x16x32_bf16 v[56:59], v[136:139], v[174:177], v[56:59]
	v_mfma_f32_16x16x32_bf16 v[52:55], v[140:143], v[174:177], v[52:55]
	v_mfma_f32_16x16x32_bf16 v[48:51], v[146:149], v[174:177], v[48:51]
	v_mfma_f32_16x16x32_bf16 v[44:47], v[154:157], v[174:177], v[44:47]
	v_mfma_f32_16x16x32_bf16 v[40:43], v[136:139], v[178:181], v[40:43]
	v_mfma_f32_16x16x32_bf16 v[36:39], v[140:143], v[178:181], v[36:39]
	v_mfma_f32_16x16x32_bf16 v[32:35], v[146:149], v[178:181], v[32:35]
	v_mfma_f32_16x16x32_bf16 v[28:31], v[154:157], v[178:181], v[28:31]
	v_mfma_f32_16x16x32_bf16 v[24:27], v[136:139], v[182:185], v[24:27]
	v_mfma_f32_16x16x32_bf16 v[20:23], v[140:143], v[182:185], v[20:23]
	v_mfma_f32_16x16x32_bf16 v[16:19], v[146:149], v[182:185], v[16:19]
	v_mfma_f32_16x16x32_bf16 v[12:15], v[154:157], v[182:185], v[12:15]
	v_mfma_f32_16x16x32_bf16 v[8:11], v[136:139], v[186:189], v[8:11]
	v_mfma_f32_16x16x32_bf16 v[4:7], v[140:143], v[186:189], v[4:7]
	v_mfma_f32_16x16x32_bf16 v[0:3], v[146:149], v[186:189], v[0:3]
	v_mfma_f32_16x16x32_bf16 v[88:91], v[154:157], v[186:189], v[88:91]
	ds_read_b128 v[136:139], v144 offset:8192
	ds_read_b128 v[140:143], v144 offset:10240
	ds_read_b128 v[146:149], v144 offset:12288
	ds_read_b128 v[154:157], v144 offset:14336
	s_waitcnt lgkmcnt(0)
	v_mfma_f32_16x16x32_bf16 v[124:127], v[158:161], v[206:209], v[124:127]
	v_mfma_f32_16x16x32_bf16 v[120:123], v[162:165], v[206:209], v[120:123]
	v_mfma_f32_16x16x32_bf16 v[116:119], v[166:169], v[206:209], v[116:119]
	v_mfma_f32_16x16x32_bf16 v[112:115], v[170:173], v[206:209], v[112:115]
	v_mfma_f32_16x16x32_bf16 v[108:111], v[158:161], v[216:219], v[108:111]
	v_mfma_f32_16x16x32_bf16 v[104:107], v[162:165], v[216:219], v[104:107]
	v_mfma_f32_16x16x32_bf16 v[100:103], v[166:169], v[216:219], v[100:103]
	v_mfma_f32_16x16x32_bf16 v[96:99], v[170:173], v[216:219], v[96:99]
	v_mfma_f32_16x16x32_bf16 v[92:95], v[158:161], v[220:223], v[92:95]
	v_mfma_f32_16x16x32_bf16 v[84:87], v[162:165], v[220:223], v[84:87]
	v_mfma_f32_16x16x32_bf16 v[80:83], v[166:169], v[220:223], v[80:83]
	v_mfma_f32_16x16x32_bf16 v[76:79], v[170:173], v[220:223], v[76:79]
	v_mfma_f32_16x16x32_bf16 v[72:75], v[158:161], v[224:227], v[72:75]
	v_mfma_f32_16x16x32_bf16 v[68:71], v[162:165], v[224:227], v[68:71]
	v_mfma_f32_16x16x32_bf16 v[64:67], v[166:169], v[224:227], v[64:67]
	v_mfma_f32_16x16x32_bf16 v[60:63], v[170:173], v[224:227], v[60:63]
	v_mfma_f32_16x16x32_bf16 v[56:59], v[158:161], v[136:139], v[56:59]
	s_add_u32 s24, s24, 0x80
	s_addc_u32 s25, s25, 0
	v_mfma_f32_16x16x32_bf16 v[52:55], v[162:165], v[136:139], v[52:55]
	s_cmpk_eq_i32 s24, 0x780
	s_mov_b32 s3, s19
	s_waitcnt vmcnt(0)
	v_mfma_f32_16x16x32_bf16 v[48:51], v[166:169], v[136:139], v[48:51]
	s_barrier
	v_mfma_f32_16x16x32_bf16 v[44:47], v[170:173], v[136:139], v[44:47]
	v_mfma_f32_16x16x32_bf16 v[40:43], v[158:161], v[140:143], v[40:43]
	v_mfma_f32_16x16x32_bf16 v[36:39], v[162:165], v[140:143], v[36:39]
	v_mfma_f32_16x16x32_bf16 v[32:35], v[166:169], v[140:143], v[32:35]
	v_mfma_f32_16x16x32_bf16 v[28:31], v[170:173], v[140:143], v[28:31]
	v_mfma_f32_16x16x32_bf16 v[24:27], v[158:161], v[146:149], v[24:27]
	v_mfma_f32_16x16x32_bf16 v[20:23], v[162:165], v[146:149], v[20:23]
	v_mfma_f32_16x16x32_bf16 v[16:19], v[166:169], v[146:149], v[16:19]
	v_mfma_f32_16x16x32_bf16 v[12:15], v[170:173], v[146:149], v[12:15]
	v_mfma_f32_16x16x32_bf16 v[8:11], v[158:161], v[154:157], v[8:11]
	v_mfma_f32_16x16x32_bf16 v[4:7], v[162:165], v[154:157], v[4:7]
	v_mfma_f32_16x16x32_bf16 v[0:3], v[166:169], v[154:157], v[0:3]
	v_mfma_f32_16x16x32_bf16 v[88:91], v[170:173], v[154:157], v[88:91]
	s_cbranch_scc0 .LBB0_246
	s_branch .Lkx_246
.Lkb_246:
	s_add_i32 s19, s3, 0x10000
	s_and_b32 s23, s19, 0x10000
	s_add_i32 s23, s2, s23
	s_and_b32 s3, s3, 0x10000
	v_or_b32_e32 v144, s3, v135
	v_add_u32_e32 v151, v144, v134
	v_add_u32_e32 v144, v144, v132
	ds_read_b128 v[136:139], v151 offset:32768
	ds_read_b128 v[140:143], v151 offset:34816
	ds_read_b128 v[146:149], v151 offset:36864
	ds_read_b128 v[154:157], v151 offset:38912
	ds_read_b128 v[158:161], v144
	ds_read_b128 v[162:165], v144 offset:2048
	ds_read_b128 v[166:169], v144 offset:4096
	ds_read_b128 v[170:173], v144 offset:6144
	ds_read_b128 v[174:177], v144 offset:8192
	ds_read_b128 v[178:181], v144 offset:10240
	ds_read_b128 v[182:185], v144 offset:12288
	ds_read_b128 v[186:189], v144 offset:14336
	s_waitcnt lgkmcnt(0)
	v_mfma_f32_16x16x32_bf16 v[124:127], v[136:139], v[158:161], 0
	v_mfma_f32_16x16x32_bf16 v[120:123], v[140:143], v[158:161], 0
	v_mfma_f32_16x16x32_bf16 v[116:119], v[146:149], v[158:161], 0
	v_mfma_f32_16x16x32_bf16 v[112:115], v[154:157], v[158:161], 0
	v_mfma_f32_16x16x32_bf16 v[108:111], v[136:139], v[162:165], 0
	v_mfma_f32_16x16x32_bf16 v[104:107], v[140:143], v[162:165], 0
	v_mfma_f32_16x16x32_bf16 v[100:103], v[146:149], v[162:165], 0
	v_mfma_f32_16x16x32_bf16 v[96:99], v[154:157], v[162:165], 0
	v_mfma_f32_16x16x32_bf16 v[92:95], v[136:139], v[166:169], 0
	v_mfma_f32_16x16x32_bf16 v[84:87], v[140:143], v[166:169], 0
	v_mfma_f32_16x16x32_bf16 v[80:83], v[146:149], v[166:169], 0
	v_mfma_f32_16x16x32_bf16 v[76:79], v[154:157], v[166:169], 0
	v_mfma_f32_16x16x32_bf16 v[72:75], v[136:139], v[170:173], 0
	v_mfma_f32_16x16x32_bf16 v[68:71], v[140:143], v[170:173], 0
	v_mfma_f32_16x16x32_bf16 v[64:67], v[146:149], v[170:173], 0
	v_mfma_f32_16x16x32_bf16 v[60:63], v[154:157], v[170:173], 0
	v_or_b32_e32 v144, s3, v133
	v_add_u32_e32 v151, v144, v134
	v_add_u32_e32 v144, v144, v132
	ds_read_b128 v[158:161], v151 offset:32768
	ds_read_b128 v[162:165], v151 offset:34816
	ds_read_b128 v[166:169], v151 offset:36864
	ds_read_b128 v[170:173], v151 offset:38912
	ds_read_b128 v[206:209], v144
	ds_read_b128 v[216:219], v144 offset:2048
	ds_read_b128 v[220:223], v144 offset:4096
	ds_read_b128 v[224:227], v144 offset:6144
	v_mfma_f32_16x16x32_bf16 v[56:59], v[136:139], v[174:177], 0
	v_mfma_f32_16x16x32_bf16 v[52:55], v[140:143], v[174:177], 0
	v_mfma_f32_16x16x32_bf16 v[48:51], v[146:149], v[174:177], 0
	v_mfma_f32_16x16x32_bf16 v[44:47], v[154:157], v[174:177], 0
	v_mfma_f32_16x16x32_bf16 v[40:43], v[136:139], v[178:181], 0
	v_mfma_f32_16x16x32_bf16 v[36:39], v[140:143], v[178:181], 0
	v_mfma_f32_16x16x32_bf16 v[32:35], v[146:149], v[178:181], 0
	v_mfma_f32_16x16x32_bf16 v[28:31], v[154:157], v[178:181], 0
	v_mfma_f32_16x16x32_bf16 v[24:27], v[136:139], v[182:185], 0
	v_mfma_f32_16x16x32_bf16 v[20:23], v[140:143], v[182:185], 0
	v_mfma_f32_16x16x32_bf16 v[16:19], v[146:149], v[182:185], 0
	v_mfma_f32_16x16x32_bf16 v[12:15], v[154:157], v[182:185], 0
	v_mfma_f32_16x16x32_bf16 v[8:11], v[136:139], v[186:189], 0
	v_mfma_f32_16x16x32_bf16 v[4:7], v[140:143], v[186:189], 0
	v_mfma_f32_16x16x32_bf16 v[0:3], v[146:149], v[186:189], 0
	v_mfma_f32_16x16x32_bf16 v[88:91], v[154:157], v[186:189], 0
	s_add_u32 s48, s50, s24
	s_addc_u32 s49, s51, s25
	s_add_u32 s98, s48, s10
	s_addc_u32 s99, s49, s11
	s_mov_b32 m0, s23
	s_nop 0
	global_load_lds_dwordx4 v244, s[98:99]
	s_add_u32 s98, s48, s4
	s_addc_u32 s99, s49, s5
	s_add_i32 m0, s23, 0x2000
	s_nop 0
	global_load_lds_dwordx4 v244, s[98:99]
	s_add_u32 s98, s48, s92
	s_addc_u32 s99, s49, s93
	s_add_i32 m0, s23, 0x4000
	s_add_u32 s48, s48, s94
	s_addc_u32 s49, s49, s95
	global_load_lds_dwordx4 v244, s[98:99]
	s_add_i32 m0, s23, 0x6000
	s_nop 0
	global_load_lds_dwordx4 v244, s[48:49]
	s_add_u32 s48, s50, s24
	s_addc_u32 s49, s51, s25
	s_add_u32 s98, s48, s10
	s_addc_u32 s99, s49, s11
	s_add_i32 m0, s23, 0x8000
	s_nop 0
	global_load_lds_dwordx4 v245, s[98:99]
	s_add_u32 s98, s48, s4
	s_addc_u32 s99, s49, s5
	s_add_i32 m0, s23, 0xa000
	s_nop 0
	global_load_lds_dwordx4 v245, s[98:99]
	s_add_u32 s98, s48, s92
	s_addc_u32 s99, s49, s93
	s_add_i32 m0, s23, 0xc000
	s_add_u32 s48, s48, s94
	s_addc_u32 s49, s49, s95
	global_load_lds_dwordx4 v245, s[98:99]
	s_add_i32 m0, s23, 0xe000
	s_nop 0
	global_load_lds_dwordx4 v245, s[48:49]
	ds_read_b128 v[136:139], v144 offset:8192
	ds_read_b128 v[140:143], v144 offset:10240
	ds_read_b128 v[146:149], v144 offset:12288
	ds_read_b128 v[154:157], v144 offset:14336
	s_waitcnt lgkmcnt(0)
	v_mfma_f32_16x16x32_bf16 v[124:127], v[158:161], v[206:209], v[124:127]
	v_mfma_f32_16x16x32_bf16 v[120:123], v[162:165], v[206:209], v[120:123]
	v_mfma_f32_16x16x32_bf16 v[116:119], v[166:169], v[206:209], v[116:119]
	v_mfma_f32_16x16x32_bf16 v[112:115], v[170:173], v[206:209], v[112:115]
	v_mfma_f32_16x16x32_bf16 v[108:111], v[158:161], v[216:219], v[108:111]
	v_mfma_f32_16x16x32_bf16 v[104:107], v[162:165], v[216:219], v[104:107]
	v_mfma_f32_16x16x32_bf16 v[100:103], v[166:169], v[216:219], v[100:103]
	v_mfma_f32_16x16x32_bf16 v[96:99], v[170:173], v[216:219], v[96:99]
	v_mfma_f32_16x16x32_bf16 v[92:95], v[158:161], v[220:223], v[92:95]
	v_mfma_f32_16x16x32_bf16 v[84:87], v[162:165], v[220:223], v[84:87]
	v_mfma_f32_16x16x32_bf16 v[80:83], v[166:169], v[220:223], v[80:83]
	v_mfma_f32_16x16x32_bf16 v[76:79], v[170:173], v[220:223], v[76:79]
	v_mfma_f32_16x16x32_bf16 v[72:75], v[158:161], v[224:227], v[72:75]
	v_mfma_f32_16x16x32_bf16 v[68:71], v[162:165], v[224:227], v[68:71]
	v_mfma_f32_16x16x32_bf16 v[64:67], v[166:169], v[224:227], v[64:67]
	v_mfma_f32_16x16x32_bf16 v[60:63], v[170:173], v[224:227], v[60:63]
	v_mfma_f32_16x16x32_bf16 v[56:59], v[158:161], v[136:139], v[56:59]
	s_add_u32 s24, s24, 0x80
	s_addc_u32 s25, s25, 0
	v_mfma_f32_16x16x32_bf16 v[52:55], v[162:165], v[136:139], v[52:55]
	s_cmpk_eq_i32 s24, 0x780
	s_mov_b32 s3, s19
	s_waitcnt vmcnt(0)
	v_mfma_f32_16x16x32_bf16 v[48:51], v[166:169], v[136:139], v[48:51]
	s_barrier
	v_mfma_f32_16x16x32_bf16 v[44:47], v[170:173], v[136:139], v[44:47]
	v_mfma_f32_16x16x32_bf16 v[40:43], v[158:161], v[140:143], v[40:43]
	v_mfma_f32_16x16x32_bf16 v[36:39], v[162:165], v[140:143], v[36:39]
	v_mfma_f32_16x16x32_bf16 v[32:35], v[166:169], v[140:143], v[32:35]
	v_mfma_f32_16x16x32_bf16 v[28:31], v[170:173], v[140:143], v[28:31]
	v_mfma_f32_16x16x32_bf16 v[24:27], v[158:161], v[146:149], v[24:27]
	v_mfma_f32_16x16x32_bf16 v[20:23], v[162:165], v[146:149], v[20:23]
	v_mfma_f32_16x16x32_bf16 v[16:19], v[166:169], v[146:149], v[16:19]
	v_mfma_f32_16x16x32_bf16 v[12:15], v[170:173], v[146:149], v[12:15]
	v_mfma_f32_16x16x32_bf16 v[8:11], v[158:161], v[154:157], v[8:11]
	v_mfma_f32_16x16x32_bf16 v[4:7], v[162:165], v[154:157], v[4:7]
	v_mfma_f32_16x16x32_bf16 v[0:3], v[166:169], v[154:157], v[0:3]
	v_mfma_f32_16x16x32_bf16 v[88:91], v[170:173], v[154:157], v[88:91]
	s_cbranch_scc1 .Lkx_246
.Lkb_246_l:
	s_add_i32 s19, s3, 0x10000
	s_and_b32 s23, s19, 0x10000
	s_add_i32 s23, s2, s23
	s_and_b32 s3, s3, 0x10000
	v_or_b32_e32 v144, s3, v135
	v_add_u32_e32 v151, v144, v134
	v_add_u32_e32 v144, v144, v132
	ds_read_b128 v[136:139], v151 offset:32768
	ds_read_b128 v[140:143], v151 offset:34816
	ds_read_b128 v[146:149], v151 offset:36864
	ds_read_b128 v[154:157], v151 offset:38912
	ds_read_b128 v[158:161], v144
	ds_read_b128 v[162:165], v144 offset:2048
	ds_read_b128 v[166:169], v144 offset:4096
	ds_read_b128 v[170:173], v144 offset:6144
	ds_read_b128 v[174:177], v144 offset:8192
	ds_read_b128 v[178:181], v144 offset:10240
	ds_read_b128 v[182:185], v144 offset:12288
	ds_read_b128 v[186:189], v144 offset:14336
	s_waitcnt lgkmcnt(0)
	v_mfma_f32_16x16x32_bf16 v[124:127], v[136:139], v[158:161], v[124:127]
	v_mfma_f32_16x16x32_bf16 v[120:123], v[140:143], v[158:161], v[120:123]
	v_mfma_f32_16x16x32_bf16 v[116:119], v[146:149], v[158:161], v[116:119]
	v_mfma_f32_16x16x32_bf16 v[112:115], v[154:157], v[158:161], v[112:115]
	v_mfma_f32_16x16x32_bf16 v[108:111], v[136:139], v[162:165], v[108:111]
	v_mfma_f32_16x16x32_bf16 v[104:107], v[140:143], v[162:165], v[104:107]
	v_mfma_f32_16x16x32_bf16 v[100:103], v[146:149], v[162:165], v[100:103]
	v_mfma_f32_16x16x32_bf16 v[96:99], v[154:157], v[162:165], v[96:99]
	v_mfma_f32_16x16x32_bf16 v[92:95], v[136:139], v[166:169], v[92:95]
	v_mfma_f32_16x16x32_bf16 v[84:87], v[140:143], v[166:169], v[84:87]
	v_mfma_f32_16x16x32_bf16 v[80:83], v[146:149], v[166:169], v[80:83]
	v_mfma_f32_16x16x32_bf16 v[76:79], v[154:157], v[166:169], v[76:79]
	v_mfma_f32_16x16x32_bf16 v[72:75], v[136:139], v[170:173], v[72:75]
	v_mfma_f32_16x16x32_bf16 v[68:71], v[140:143], v[170:173], v[68:71]
	v_mfma_f32_16x16x32_bf16 v[64:67], v[146:149], v[170:173], v[64:67]
	v_mfma_f32_16x16x32_bf16 v[60:63], v[154:157], v[170:173], v[60:63]
	v_or_b32_e32 v144, s3, v133
	v_add_u32_e32 v151, v144, v134
	v_add_u32_e32 v144, v144, v132
	ds_read_b128 v[158:161], v151 offset:32768
	ds_read_b128 v[162:165], v151 offset:34816
	ds_read_b128 v[166:169], v151 offset:36864
	ds_read_b128 v[170:173], v151 offset:38912
	ds_read_b128 v[206:209], v144
	ds_read_b128 v[216:219], v144 offset:2048
	ds_read_b128 v[220:223], v144 offset:4096
	ds_read_b128 v[224:227], v144 offset:6144
	v_mfma_f32_16x16x32_bf16 v[56:59], v[136:139], v[174:177], v[56:59]
	v_mfma_f32_16x16x32_bf16 v[52:55], v[140:143], v[174:177], v[52:55]
	v_mfma_f32_16x16x32_bf16 v[48:51], v[146:149], v[174:177], v[48:51]
	v_mfma_f32_16x16x32_bf16 v[44:47], v[154:157], v[174:177], v[44:47]
	v_mfma_f32_16x16x32_bf16 v[40:43], v[136:139], v[178:181], v[40:43]
	v_mfma_f32_16x16x32_bf16 v[36:39], v[140:143], v[178:181], v[36:39]
	v_mfma_f32_16x16x32_bf16 v[32:35], v[146:149], v[178:181], v[32:35]
	v_mfma_f32_16x16x32_bf16 v[28:31], v[154:157], v[178:181], v[28:31]
	v_mfma_f32_16x16x32_bf16 v[24:27], v[136:139], v[182:185], v[24:27]
	v_mfma_f32_16x16x32_bf16 v[20:23], v[140:143], v[182:185], v[20:23]
	v_mfma_f32_16x16x32_bf16 v[16:19], v[146:149], v[182:185], v[16:19]
	v_mfma_f32_16x16x32_bf16 v[12:15], v[154:157], v[182:185], v[12:15]
	v_mfma_f32_16x16x32_bf16 v[8:11], v[136:139], v[186:189], v[8:11]
	v_mfma_f32_16x16x32_bf16 v[4:7], v[140:143], v[186:189], v[4:7]
	v_mfma_f32_16x16x32_bf16 v[0:3], v[146:149], v[186:189], v[0:3]
	v_mfma_f32_16x16x32_bf16 v[88:91], v[154:157], v[186:189], v[88:91]
	s_add_u32 s48, s50, s24
	s_addc_u32 s49, s51, s25
	s_add_u32 s98, s48, s10
	s_addc_u32 s99, s49, s11
	s_mov_b32 m0, s23
	s_nop 0
	global_load_lds_dwordx4 v244, s[98:99]
	s_add_u32 s98, s48, s4
	s_addc_u32 s99, s49, s5
	s_add_i32 m0, s23, 0x2000
	s_nop 0
	global_load_lds_dwordx4 v244, s[98:99]
	s_add_u32 s98, s48, s92
	s_addc_u32 s99, s49, s93
	s_add_i32 m0, s23, 0x4000
	s_add_u32 s48, s48, s94
	s_addc_u32 s49, s49, s95
	global_load_lds_dwordx4 v244, s[98:99]
	s_add_i32 m0, s23, 0x6000
	s_nop 0
	global_load_lds_dwordx4 v244, s[48:49]
	s_add_u32 s48, s50, s24
	s_addc_u32 s49, s51, s25
	s_add_u32 s98, s48, s10
	s_addc_u32 s99, s49, s11
	s_add_i32 m0, s23, 0x8000
	s_nop 0
	global_load_lds_dwordx4 v245, s[98:99]
	s_add_u32 s98, s48, s4
	s_addc_u32 s99, s49, s5
	s_add_i32 m0, s23, 0xa000
	s_nop 0
	global_load_lds_dwordx4 v245, s[98:99]
	s_add_u32 s98, s48, s92
	s_addc_u32 s99, s49, s93
	s_add_i32 m0, s23, 0xc000
	s_add_u32 s48, s48, s94
	s_addc_u32 s49, s49, s95
	global_load_lds_dwordx4 v245, s[98:99]
	s_add_i32 m0, s23, 0xe000
	s_nop 0
	global_load_lds_dwordx4 v245, s[48:49]
	ds_read_b128 v[136:139], v144 offset:8192
	ds_read_b128 v[140:143], v144 offset:10240
	ds_read_b128 v[146:149], v144 offset:12288
	ds_read_b128 v[154:157], v144 offset:14336
	s_waitcnt lgkmcnt(0)
	v_mfma_f32_16x16x32_bf16 v[124:127], v[158:161], v[206:209], v[124:127]
	v_mfma_f32_16x16x32_bf16 v[120:123], v[162:165], v[206:209], v[120:123]
	v_mfma_f32_16x16x32_bf16 v[116:119], v[166:169], v[206:209], v[116:119]
	v_mfma_f32_16x16x32_bf16 v[112:115], v[170:173], v[206:209], v[112:115]
	v_mfma_f32_16x16x32_bf16 v[108:111], v[158:161], v[216:219], v[108:111]
	v_mfma_f32_16x16x32_bf16 v[104:107], v[162:165], v[216:219], v[104:107]
	v_mfma_f32_16x16x32_bf16 v[100:103], v[166:169], v[216:219], v[100:103]
	v_mfma_f32_16x16x32_bf16 v[96:99], v[170:173], v[216:219], v[96:99]
	v_mfma_f32_16x16x32_bf16 v[92:95], v[158:161], v[220:223], v[92:95]
	v_mfma_f32_16x16x32_bf16 v[84:87], v[162:165], v[220:223], v[84:87]
	v_mfma_f32_16x16x32_bf16 v[80:83], v[166:169], v[220:223], v[80:83]
	v_mfma_f32_16x16x32_bf16 v[76:79], v[170:173], v[220:223], v[76:79]
	v_mfma_f32_16x16x32_bf16 v[72:75], v[158:161], v[224:227], v[72:75]
	v_mfma_f32_16x16x32_bf16 v[68:71], v[162:165], v[224:227], v[68:71]
	v_mfma_f32_16x16x32_bf16 v[64:67], v[166:169], v[224:227], v[64:67]
	v_mfma_f32_16x16x32_bf16 v[60:63], v[170:173], v[224:227], v[60:63]
	v_mfma_f32_16x16x32_bf16 v[56:59], v[158:161], v[136:139], v[56:59]
	s_add_u32 s24, s24, 0x80
	s_addc_u32 s25, s25, 0
	v_mfma_f32_16x16x32_bf16 v[52:55], v[162:165], v[136:139], v[52:55]
	s_cmpk_eq_i32 s24, 0x780
	s_mov_b32 s3, s19
	s_waitcnt vmcnt(0)
	v_mfma_f32_16x16x32_bf16 v[48:51], v[166:169], v[136:139], v[48:51]
	s_barrier
	v_mfma_f32_16x16x32_bf16 v[44:47], v[170:173], v[136:139], v[44:47]
	v_mfma_f32_16x16x32_bf16 v[40:43], v[158:161], v[140:143], v[40:43]
	v_mfma_f32_16x16x32_bf16 v[36:39], v[162:165], v[140:143], v[36:39]
	v_mfma_f32_16x16x32_bf16 v[32:35], v[166:169], v[140:143], v[32:35]
	v_mfma_f32_16x16x32_bf16 v[28:31], v[170:173], v[140:143], v[28:31]
	v_mfma_f32_16x16x32_bf16 v[24:27], v[158:161], v[146:149], v[24:27]
	v_mfma_f32_16x16x32_bf16 v[20:23], v[162:165], v[146:149], v[20:23]
	v_mfma_f32_16x16x32_bf16 v[16:19], v[166:169], v[146:149], v[16:19]
	v_mfma_f32_16x16x32_bf16 v[12:15], v[170:173], v[146:149], v[12:15]
	v_mfma_f32_16x16x32_bf16 v[8:11], v[158:161], v[154:157], v[8:11]
	v_mfma_f32_16x16x32_bf16 v[4:7], v[162:165], v[154:157], v[4:7]
	v_mfma_f32_16x16x32_bf16 v[0:3], v[166:169], v[154:157], v[0:3]
	v_mfma_f32_16x16x32_bf16 v[88:91], v[170:173], v[154:157], v[88:91]
	s_cbranch_scc0 .Lkb_246_l

.LBB0_419:
	v_and_b32_e32 v5, 15, v3
	v_lshrrev_b32_e32 v6, 1, v3
	s_mov_b32 s3, 0x1ffff80
	s_lshr_b32 s2, s57, 3
	v_and_or_b32 v5, v6, s3, v5
	s_and_b32 s3, s36, 56
	s_and_b32 s2, s2, 3
	s_add_i32 s3, s3, s61
	s_add_i32 s2, s3, s2
	v_and_b32_e32 v4, 3, v4
	v_lshlrev_b32_e32 v136, 7, v5
	v_bfe_u32 v5, v3, 1, 3
	s_ashr_i32 s3, s2, 31
	v_bitop3_b32 v6, v6, v4, 7 bitop3:0x6c
	v_bitop3_b32 v4, v4, v5, 4 bitop3:0x36
	v_lshlrev_b64 v[0:1], 11, v[0:1]
	v_lshlrev_b32_e32 v2, 4, v2
	s_lshl_b64 s[2:3], s[2:3], 19
	v_lshlrev_b32_e32 v137, 4, v4
	v_lshlrev_b32_e32 v3, 7, v3
	s_waitcnt vmcnt(0)
	v_lshl_add_u64 v[4:5], s[26:27], 0, v[0:1]
	v_and_b32_e32 v144, 0x70, v2
	v_lshl_add_u64 v[0:1], s[2:3], 0, v[0:1]
	v_and_b32_e32 v138, 0x6780, v3
	v_lshl_add_u64 v[2:3], v[4:5], 0, v[144:145]
	v_or_b32_e32 v0, v0, v144
	v_lshlrev_b32_e32 v139, 4, v6
	v_lshl_add_u64 v[132:133], s[14:15], 0, v[2:3]
	v_lshl_add_u64 v[134:135], s[14:15], 0, v[0:1]
	s_mov_b64 s[26:27], 0
	s_mov_b32 s2, 0
	s_mov_b64 s[38:39], 0x3a20080
	s_mov_b64 s[40:41], 0x3a40080
	s_waitcnt vmcnt(0) lgkmcnt(0)
	s_barrier
	v_readlane_b32 s50, v255, 24
	v_readlane_b32 s51, v255, 25
	s_nop 1
	v_subrev_u32_e32 v244, s50, v134
	v_subrev_u32_e32 v245, s50, v132
	s_bitcmp1_b32 s0, 12
	s_cbranch_scc1 .Lkb_420
	s_add_i32 s3, s2, 0x10000
	s_and_b32 s7, s3, 0x10000
	s_add_i32 s7, s0, s7
	s_add_u32 s48, s50, s26
	s_addc_u32 s49, s51, s27
	s_add_u32 s98, s48, s64
	s_addc_u32 s99, s49, s65
	s_mov_b32 m0, s7
	s_mov_b64 s[62:63], 0x1080080
	global_load_lds_dwordx4 v244, s[98:99]
	s_add_u32 s98, s48, s68
	s_addc_u32 s99, s49, s69
	s_add_i32 m0, s7, 0x2000
	s_nop 0
	global_load_lds_dwordx4 v244, s[98:99]
	s_add_u32 s98, s48, s38
	s_addc_u32 s99, s49, s39
	s_add_i32 m0, s7, 0x4000
	s_add_u32 s48, s48, s40
	s_addc_u32 s49, s49, s41
	global_load_lds_dwordx4 v244, s[98:99]
	s_add_i32 m0, s7, 0x6000
	s_nop 0
	global_load_lds_dwordx4 v244, s[48:49]
	s_add_u32 s48, s50, s26
	s_addc_u32 s49, s51, s27
	s_add_u32 s98, s48, s62
	s_addc_u32 s99, s49, s63
	s_add_i32 m0, s7, 0x8000
	s_mov_b64 s[62:63], 0x10a0080
	global_load_lds_dwordx4 v245, s[98:99]
	s_add_u32 s98, s48, s62
	s_addc_u32 s99, s49, s63
	s_add_i32 m0, s7, 0xa000
	s_mov_b64 s[62:63], 0x10c0080
	global_load_lds_dwordx4 v245, s[98:99]
	s_add_u32 s98, s48, s62
	s_addc_u32 s99, s49, s63
	s_add_i32 m0, s7, 0xc000
	s_mov_b64 s[62:63], 0x10e0080
	global_load_lds_dwordx4 v245, s[98:99]
	s_add_u32 s48, s48, s62
	s_addc_u32 s49, s49, s63
	s_add_i32 m0, s7, 0xe000
	s_nop 0
	global_load_lds_dwordx4 v245, s[48:49]
	s_and_b32 s2, s2, 0x10000
	v_or_b32_e32 v129, s2, v139
	v_add_u32_e32 v144, v129, v138
	v_add_u32_e32 v129, v129, v136
	ds_read_b128 v[140:143], v144 offset:32768
	ds_read_b128 v[146:149], v144 offset:34816
	ds_read_b128 v[154:157], v144 offset:36864
	ds_read_b128 v[158:161], v144 offset:38912
	ds_read_b128 v[162:165], v129
	ds_read_b128 v[166:169], v129 offset:2048
	ds_read_b128 v[170:173], v129 offset:4096
	ds_read_b128 v[174:177], v129 offset:6144
	ds_read_b128 v[178:181], v129 offset:8192
	ds_read_b128 v[182:185], v129 offset:10240
	ds_read_b128 v[186:189], v129 offset:12288
	ds_read_b128 v[206:209], v129 offset:14336
	s_waitcnt lgkmcnt(0)
	v_mfma_f32_16x16x32_bf16 v[124:127], v[140:143], v[162:165], 0
	v_mfma_f32_16x16x32_bf16 v[120:123], v[146:149], v[162:165], 0
	v_mfma_f32_16x16x32_bf16 v[116:119], v[154:157], v[162:165], 0
	v_mfma_f32_16x16x32_bf16 v[112:115], v[158:161], v[162:165], 0
	v_mfma_f32_16x16x32_bf16 v[108:111], v[140:143], v[166:169], 0
	v_mfma_f32_16x16x32_bf16 v[104:107], v[146:149], v[166:169], 0
	v_mfma_f32_16x16x32_bf16 v[100:103], v[154:157], v[166:169], 0
	v_mfma_f32_16x16x32_bf16 v[96:99], v[158:161], v[166:169], 0
	v_mfma_f32_16x16x32_bf16 v[92:95], v[140:143], v[170:173], 0
	v_mfma_f32_16x16x32_bf16 v[84:87], v[146:149], v[170:173], 0
	v_mfma_f32_16x16x32_bf16 v[80:83], v[154:157], v[170:173], 0
	v_mfma_f32_16x16x32_bf16 v[76:79], v[158:161], v[170:173], 0
	v_mfma_f32_16x16x32_bf16 v[72:75], v[140:143], v[174:177], 0
	v_mfma_f32_16x16x32_bf16 v[68:71], v[146:149], v[174:177], 0
	v_mfma_f32_16x16x32_bf16 v[64:67], v[154:157], v[174:177], 0
	v_mfma_f32_16x16x32_bf16 v[60:63], v[158:161], v[174:177], 0
	v_or_b32_e32 v129, s2, v137
	v_add_u32_e32 v144, v129, v138
	v_add_u32_e32 v129, v129, v136
	ds_read_b128 v[162:165], v144 offset:32768
	ds_read_b128 v[166:169], v144 offset:34816
	ds_read_b128 v[170:173], v144 offset:36864
	ds_read_b128 v[174:177], v144 offset:38912
	ds_read_b128 v[216:219], v129
	ds_read_b128 v[220:223], v129 offset:2048
	ds_read_b128 v[224:227], v129 offset:4096
	ds_read_b128 v[228:231], v129 offset:6144
	v_mfma_f32_16x16x32_bf16 v[56:59], v[140:143], v[178:181], 0
	v_mfma_f32_16x16x32_bf16 v[52:55], v[146:149], v[178:181], 0
	v_mfma_f32_16x16x32_bf16 v[48:51], v[154:157], v[178:181], 0
	v_mfma_f32_16x16x32_bf16 v[44:47], v[158:161], v[178:181], 0
	v_mfma_f32_16x16x32_bf16 v[40:43], v[140:143], v[182:185], 0
	v_mfma_f32_16x16x32_bf16 v[36:39], v[146:149], v[182:185], 0
	v_mfma_f32_16x16x32_bf16 v[32:35], v[154:157], v[182:185], 0
	v_mfma_f32_16x16x32_bf16 v[28:31], v[158:161], v[182:185], 0
	v_mfma_f32_16x16x32_bf16 v[24:27], v[140:143], v[186:189], 0
	v_mfma_f32_16x16x32_bf16 v[20:23], v[146:149], v[186:189], 0
	v_mfma_f32_16x16x32_bf16 v[16:19], v[154:157], v[186:189], 0
	v_mfma_f32_16x16x32_bf16 v[12:15], v[158:161], v[186:189], 0
	v_mfma_f32_16x16x32_bf16 v[8:11], v[140:143], v[206:209], 0
	v_mfma_f32_16x16x32_bf16 v[4:7], v[146:149], v[206:209], 0
	v_mfma_f32_16x16x32_bf16 v[0:3], v[154:157], v[206:209], 0
	v_mfma_f32_16x16x32_bf16 v[88:91], v[158:161], v[206:209], 0
	ds_read_b128 v[140:143], v129 offset:8192
	ds_read_b128 v[146:149], v129 offset:10240
	ds_read_b128 v[154:157], v129 offset:12288
	ds_read_b128 v[158:161], v129 offset:14336
	s_waitcnt lgkmcnt(0)
	v_mfma_f32_16x16x32_bf16 v[124:127], v[162:165], v[216:219], v[124:127]
	v_mfma_f32_16x16x32_bf16 v[120:123], v[166:169], v[216:219], v[120:123]
	v_mfma_f32_16x16x32_bf16 v[116:119], v[170:173], v[216:219], v[116:119]
	v_mfma_f32_16x16x32_bf16 v[112:115], v[174:177], v[216:219], v[112:115]
	v_mfma_f32_16x16x32_bf16 v[108:111], v[162:165], v[220:223], v[108:111]
	v_mfma_f32_16x16x32_bf16 v[104:107], v[166:169], v[220:223], v[104:107]
	v_mfma_f32_16x16x32_bf16 v[100:103], v[170:173], v[220:223], v[100:103]
	v_mfma_f32_16x16x32_bf16 v[96:99], v[174:177], v[220:223], v[96:99]
	v_mfma_f32_16x16x32_bf16 v[92:95], v[162:165], v[224:227], v[92:95]
	v_mfma_f32_16x16x32_bf16 v[84:87], v[166:169], v[224:227], v[84:87]
	v_mfma_f32_16x16x32_bf16 v[80:83], v[170:173], v[224:227], v[80:83]
	v_mfma_f32_16x16x32_bf16 v[76:79], v[174:177], v[224:227], v[76:79]
	v_mfma_f32_16x16x32_bf16 v[72:75], v[162:165], v[228:231], v[72:75]
	v_mfma_f32_16x16x32_bf16 v[68:71], v[166:169], v[228:231], v[68:71]
	v_mfma_f32_16x16x32_bf16 v[64:67], v[170:173], v[228:231], v[64:67]
	v_mfma_f32_16x16x32_bf16 v[60:63], v[174:177], v[228:231], v[60:63]
	v_mfma_f32_16x16x32_bf16 v[56:59], v[162:165], v[140:143], v[56:59]
	s_add_u32 s26, s26, 0x80
	s_addc_u32 s27, s27, 0
	v_mfma_f32_16x16x32_bf16 v[52:55], v[166:169], v[140:143], v[52:55]
	s_cmpk_eq_i32 s26, 0x780
	s_mov_b32 s2, s3
	s_waitcnt vmcnt(0)
	v_mfma_f32_16x16x32_bf16 v[48:51], v[170:173], v[140:143], v[48:51]
	s_barrier
	v_mfma_f32_16x16x32_bf16 v[44:47], v[174:177], v[140:143], v[44:47]
	v_mfma_f32_16x16x32_bf16 v[40:43], v[162:165], v[146:149], v[40:43]
	v_mfma_f32_16x16x32_bf16 v[36:39], v[166:169], v[146:149], v[36:39]
	v_mfma_f32_16x16x32_bf16 v[32:35], v[170:173], v[146:149], v[32:35]
	v_mfma_f32_16x16x32_bf16 v[28:31], v[174:177], v[146:149], v[28:31]
	v_mfma_f32_16x16x32_bf16 v[24:27], v[162:165], v[154:157], v[24:27]
	v_mfma_f32_16x16x32_bf16 v[20:23], v[166:169], v[154:157], v[20:23]
	v_mfma_f32_16x16x32_bf16 v[16:19], v[170:173], v[154:157], v[16:19]
	v_mfma_f32_16x16x32_bf16 v[12:15], v[174:177], v[154:157], v[12:15]
	v_mfma_f32_16x16x32_bf16 v[8:11], v[162:165], v[158:161], v[8:11]
	v_mfma_f32_16x16x32_bf16 v[4:7], v[166:169], v[158:161], v[4:7]
	v_mfma_f32_16x16x32_bf16 v[0:3], v[170:173], v[158:161], v[0:3]
	v_mfma_f32_16x16x32_bf16 v[88:91], v[174:177], v[158:161], v[88:91]
	s_cbranch_scc1 .Lkx_420
.LBB0_420:
	s_add_i32 s3, s2, 0x10000
	s_and_b32 s7, s3, 0x10000
	s_add_i32 s7, s0, s7
	s_add_u32 s48, s50, s26
	s_addc_u32 s49, s51, s27
	s_add_u32 s98, s48, s64
	s_addc_u32 s99, s49, s65
	s_mov_b32 m0, s7
	s_mov_b64 s[62:63], 0x1080080
	global_load_lds_dwordx4 v244, s[98:99]
	s_add_u32 s98, s48, s68
	s_addc_u32 s99, s49, s69
	s_add_i32 m0, s7, 0x2000
	s_nop 0
	global_load_lds_dwordx4 v244, s[98:99]
	s_add_u32 s98, s48, s38
	s_addc_u32 s99, s49, s39
	s_add_i32 m0, s7, 0x4000
	s_add_u32 s48, s48, s40
	s_addc_u32 s49, s49, s41
	global_load_lds_dwordx4 v244, s[98:99]
	s_add_i32 m0, s7, 0x6000
	s_nop 0
	global_load_lds_dwordx4 v244, s[48:49]
	s_add_u32 s48, s50, s26
	s_addc_u32 s49, s51, s27
	s_add_u32 s98, s48, s62
	s_addc_u32 s99, s49, s63
	s_add_i32 m0, s7, 0x8000
	s_mov_b64 s[62:63], 0x10a0080
	global_load_lds_dwordx4 v245, s[98:99]
	s_add_u32 s98, s48, s62
	s_addc_u32 s99, s49, s63
	s_add_i32 m0, s7, 0xa000
	s_mov_b64 s[62:63], 0x10c0080
	global_load_lds_dwordx4 v245, s[98:99]
	s_add_u32 s98, s48, s62
	s_addc_u32 s99, s49, s63
	s_add_i32 m0, s7, 0xc000
	s_mov_b64 s[62:63], 0x10e0080
	global_load_lds_dwordx4 v245, s[98:99]
	s_add_u32 s48, s48, s62
	s_addc_u32 s49, s49, s63
	s_add_i32 m0, s7, 0xe000
	s_nop 0
	global_load_lds_dwordx4 v245, s[48:49]
	s_and_b32 s2, s2, 0x10000
	v_or_b32_e32 v129, s2, v139
	v_add_u32_e32 v144, v129, v138
	v_add_u32_e32 v129, v129, v136
	ds_read_b128 v[140:143], v144 offset:32768
	ds_read_b128 v[146:149], v144 offset:34816
	ds_read_b128 v[154:157], v144 offset:36864
	ds_read_b128 v[158:161], v144 offset:38912
	ds_read_b128 v[162:165], v129
	ds_read_b128 v[166:169], v129 offset:2048
	ds_read_b128 v[170:173], v129 offset:4096
	ds_read_b128 v[174:177], v129 offset:6144
	ds_read_b128 v[178:181], v129 offset:8192
	ds_read_b128 v[182:185], v129 offset:10240
	ds_read_b128 v[186:189], v129 offset:12288
	ds_read_b128 v[206:209], v129 offset:14336
	s_waitcnt lgkmcnt(0)
	v_mfma_f32_16x16x32_bf16 v[124:127], v[140:143], v[162:165], v[124:127]
	v_mfma_f32_16x16x32_bf16 v[120:123], v[146:149], v[162:165], v[120:123]
	v_mfma_f32_16x16x32_bf16 v[116:119], v[154:157], v[162:165], v[116:119]
	v_mfma_f32_16x16x32_bf16 v[112:115], v[158:161], v[162:165], v[112:115]
	v_mfma_f32_16x16x32_bf16 v[108:111], v[140:143], v[166:169], v[108:111]
	v_mfma_f32_16x16x32_bf16 v[104:107], v[146:149], v[166:169], v[104:107]
	v_mfma_f32_16x16x32_bf16 v[100:103], v[154:157], v[166:169], v[100:103]
	v_mfma_f32_16x16x32_bf16 v[96:99], v[158:161], v[166:169], v[96:99]
	v_mfma_f32_16x16x32_bf16 v[92:95], v[140:143], v[170:173], v[92:95]
	v_mfma_f32_16x16x32_bf16 v[84:87], v[146:149], v[170:173], v[84:87]
	v_mfma_f32_16x16x32_bf16 v[80:83], v[154:157], v[170:173], v[80:83]
	v_mfma_f32_16x16x32_bf16 v[76:79], v[158:161], v[170:173], v[76:79]
	v_mfma_f32_16x16x32_bf16 v[72:75], v[140:143], v[174:177], v[72:75]
	v_mfma_f32_16x16x32_bf16 v[68:71], v[146:149], v[174:177], v[68:71]
	v_mfma_f32_16x16x32_bf16 v[64:67], v[154:157], v[174:177], v[64:67]
	v_mfma_f32_16x16x32_bf16 v[60:63], v[158:161], v[174:177], v[60:63]
	v_or_b32_e32 v129, s2, v137
	v_add_u32_e32 v144, v129, v138
	v_add_u32_e32 v129, v129, v136
	ds_read_b128 v[162:165], v144 offset:32768
	ds_read_b128 v[166:169], v144 offset:34816
	ds_read_b128 v[170:173], v144 offset:36864
	ds_read_b128 v[174:177], v144 offset:38912
	ds_read_b128 v[216:219], v129
	ds_read_b128 v[220:223], v129 offset:2048
	ds_read_b128 v[224:227], v129 offset:4096
	ds_read_b128 v[228:231], v129 offset:6144
	v_mfma_f32_16x16x32_bf16 v[56:59], v[140:143], v[178:181], v[56:59]
	v_mfma_f32_16x16x32_bf16 v[52:55], v[146:149], v[178:181], v[52:55]
	v_mfma_f32_16x16x32_bf16 v[48:51], v[154:157], v[178:181], v[48:51]
	v_mfma_f32_16x16x32_bf16 v[44:47], v[158:161], v[178:181], v[44:47]
	v_mfma_f32_16x16x32_bf16 v[40:43], v[140:143], v[182:185], v[40:43]
	v_mfma_f32_16x16x32_bf16 v[36:39], v[146:149], v[182:185], v[36:39]
	v_mfma_f32_16x16x32_bf16 v[32:35], v[154:157], v[182:185], v[32:35]
	v_mfma_f32_16x16x32_bf16 v[28:31], v[158:161], v[182:185], v[28:31]
	v_mfma_f32_16x16x32_bf16 v[24:27], v[140:143], v[186:189], v[24:27]
	v_mfma_f32_16x16x32_bf16 v[20:23], v[146:149], v[186:189], v[20:23]
	v_mfma_f32_16x16x32_bf16 v[16:19], v[154:157], v[186:189], v[16:19]
	v_mfma_f32_16x16x32_bf16 v[12:15], v[158:161], v[186:189], v[12:15]
	v_mfma_f32_16x16x32_bf16 v[8:11], v[140:143], v[206:209], v[8:11]
	v_mfma_f32_16x16x32_bf16 v[4:7], v[146:149], v[206:209], v[4:7]
	v_mfma_f32_16x16x32_bf16 v[0:3], v[154:157], v[206:209], v[0:3]
	v_mfma_f32_16x16x32_bf16 v[88:91], v[158:161], v[206:209], v[88:91]
	ds_read_b128 v[140:143], v129 offset:8192
	ds_read_b128 v[146:149], v129 offset:10240
	ds_read_b128 v[154:157], v129 offset:12288
	ds_read_b128 v[158:161], v129 offset:14336
	s_waitcnt lgkmcnt(0)
	v_mfma_f32_16x16x32_bf16 v[124:127], v[162:165], v[216:219], v[124:127]
	v_mfma_f32_16x16x32_bf16 v[120:123], v[166:169], v[216:219], v[120:123]
	v_mfma_f32_16x16x32_bf16 v[116:119], v[170:173], v[216:219], v[116:119]
	v_mfma_f32_16x16x32_bf16 v[112:115], v[174:177], v[216:219], v[112:115]
	v_mfma_f32_16x16x32_bf16 v[108:111], v[162:165], v[220:223], v[108:111]
	v_mfma_f32_16x16x32_bf16 v[104:107], v[166:169], v[220:223], v[104:107]
	v_mfma_f32_16x16x32_bf16 v[100:103], v[170:173], v[220:223], v[100:103]
	v_mfma_f32_16x16x32_bf16 v[96:99], v[174:177], v[220:223], v[96:99]
	v_mfma_f32_16x16x32_bf16 v[92:95], v[162:165], v[224:227], v[92:95]
	v_mfma_f32_16x16x32_bf16 v[84:87], v[166:169], v[224:227], v[84:87]
	v_mfma_f32_16x16x32_bf16 v[80:83], v[170:173], v[224:227], v[80:83]
	v_mfma_f32_16x16x32_bf16 v[76:79], v[174:177], v[224:227], v[76:79]
	v_mfma_f32_16x16x32_bf16 v[72:75], v[162:165], v[228:231], v[72:75]
	v_mfma_f32_16x16x32_bf16 v[68:71], v[166:169], v[228:231], v[68:71]
	v_mfma_f32_16x16x32_bf16 v[64:67], v[170:173], v[228:231], v[64:67]
	v_mfma_f32_16x16x32_bf16 v[60:63], v[174:177], v[228:231], v[60:63]
	v_mfma_f32_16x16x32_bf16 v[56:59], v[162:165], v[140:143], v[56:59]
	s_add_u32 s26, s26, 0x80
	s_addc_u32 s27, s27, 0
	v_mfma_f32_16x16x32_bf16 v[52:55], v[166:169], v[140:143], v[52:55]
	s_cmpk_eq_i32 s26, 0x780
	s_mov_b32 s2, s3
	s_waitcnt vmcnt(0)
	v_mfma_f32_16x16x32_bf16 v[48:51], v[170:173], v[140:143], v[48:51]
	s_barrier
	v_mfma_f32_16x16x32_bf16 v[44:47], v[174:177], v[140:143], v[44:47]
	v_mfma_f32_16x16x32_bf16 v[40:43], v[162:165], v[146:149], v[40:43]
	v_mfma_f32_16x16x32_bf16 v[36:39], v[166:169], v[146:149], v[36:39]
	v_mfma_f32_16x16x32_bf16 v[32:35], v[170:173], v[146:149], v[32:35]
	v_mfma_f32_16x16x32_bf16 v[28:31], v[174:177], v[146:149], v[28:31]
	v_mfma_f32_16x16x32_bf16 v[24:27], v[162:165], v[154:157], v[24:27]
	v_mfma_f32_16x16x32_bf16 v[20:23], v[166:169], v[154:157], v[20:23]
	v_mfma_f32_16x16x32_bf16 v[16:19], v[170:173], v[154:157], v[16:19]
	v_mfma_f32_16x16x32_bf16 v[12:15], v[174:177], v[154:157], v[12:15]
	v_mfma_f32_16x16x32_bf16 v[8:11], v[162:165], v[158:161], v[8:11]
	v_mfma_f32_16x16x32_bf16 v[4:7], v[166:169], v[158:161], v[4:7]
	v_mfma_f32_16x16x32_bf16 v[0:3], v[170:173], v[158:161], v[0:3]
	v_mfma_f32_16x16x32_bf16 v[88:91], v[174:177], v[158:161], v[88:91]
	s_cbranch_scc0 .LBB0_420
	s_branch .Lkx_420
.Lkb_420:
	s_add_i32 s3, s2, 0x10000
	s_and_b32 s7, s3, 0x10000
	s_add_i32 s7, s0, s7
	s_and_b32 s2, s2, 0x10000
	v_or_b32_e32 v129, s2, v139
	v_add_u32_e32 v144, v129, v138
	v_add_u32_e32 v129, v129, v136
	ds_read_b128 v[140:143], v144 offset:32768
	ds_read_b128 v[146:149], v144 offset:34816
	ds_read_b128 v[154:157], v144 offset:36864
	ds_read_b128 v[158:161], v144 offset:38912
	ds_read_b128 v[162:165], v129
	ds_read_b128 v[166:169], v129 offset:2048
	ds_read_b128 v[170:173], v129 offset:4096
	ds_read_b128 v[174:177], v129 offset:6144
	ds_read_b128 v[178:181], v129 offset:8192
	ds_read_b128 v[182:185], v129 offset:10240
	ds_read_b128 v[186:189], v129 offset:12288
	ds_read_b128 v[206:209], v129 offset:14336
	s_waitcnt lgkmcnt(0)
	v_mfma_f32_16x16x32_bf16 v[124:127], v[140:143], v[162:165], 0
	v_mfma_f32_16x16x32_bf16 v[120:123], v[146:149], v[162:165], 0
	v_mfma_f32_16x16x32_bf16 v[116:119], v[154:157], v[162:165], 0
	v_mfma_f32_16x16x32_bf16 v[112:115], v[158:161], v[162:165], 0
	v_mfma_f32_16x16x32_bf16 v[108:111], v[140:143], v[166:169], 0
	v_mfma_f32_16x16x32_bf16 v[104:107], v[146:149], v[166:169], 0
	v_mfma_f32_16x16x32_bf16 v[100:103], v[154:157], v[166:169], 0
	v_mfma_f32_16x16x32_bf16 v[96:99], v[158:161], v[166:169], 0
	v_mfma_f32_16x16x32_bf16 v[92:95], v[140:143], v[170:173], 0
	v_mfma_f32_16x16x32_bf16 v[84:87], v[146:149], v[170:173], 0
	v_mfma_f32_16x16x32_bf16 v[80:83], v[154:157], v[170:173], 0
	v_mfma_f32_16x16x32_bf16 v[76:79], v[158:161], v[170:173], 0
	v_mfma_f32_16x16x32_bf16 v[72:75], v[140:143], v[174:177], 0
	v_mfma_f32_16x16x32_bf16 v[68:71], v[146:149], v[174:177], 0
	v_mfma_f32_16x16x32_bf16 v[64:67], v[154:157], v[174:177], 0
	v_mfma_f32_16x16x32_bf16 v[60:63], v[158:161], v[174:177], 0
	v_or_b32_e32 v129, s2, v137
	v_add_u32_e32 v144, v129, v138
	v_add_u32_e32 v129, v129, v136
	ds_read_b128 v[162:165], v144 offset:32768
	ds_read_b128 v[166:169], v144 offset:34816
	ds_read_b128 v[170:173], v144 offset:36864
	ds_read_b128 v[174:177], v144 offset:38912
	ds_read_b128 v[216:219], v129
	ds_read_b128 v[220:223], v129 offset:2048
	ds_read_b128 v[224:227], v129 offset:4096
	ds_read_b128 v[228:231], v129 offset:6144
	v_mfma_f32_16x16x32_bf16 v[56:59], v[140:143], v[178:181], 0
	v_mfma_f32_16x16x32_bf16 v[52:55], v[146:149], v[178:181], 0
	v_mfma_f32_16x16x32_bf16 v[48:51], v[154:157], v[178:181], 0
	v_mfma_f32_16x16x32_bf16 v[44:47], v[158:161], v[178:181], 0
	v_mfma_f32_16x16x32_bf16 v[40:43], v[140:143], v[182:185], 0
	v_mfma_f32_16x16x32_bf16 v[36:39], v[146:149], v[182:185], 0
	v_mfma_f32_16x16x32_bf16 v[32:35], v[154:157], v[182:185], 0
	v_mfma_f32_16x16x32_bf16 v[28:31], v[158:161], v[182:185], 0
	v_mfma_f32_16x16x32_bf16 v[24:27], v[140:143], v[186:189], 0
	v_mfma_f32_16x16x32_bf16 v[20:23], v[146:149], v[186:189], 0
	v_mfma_f32_16x16x32_bf16 v[16:19], v[154:157], v[186:189], 0
	v_mfma_f32_16x16x32_bf16 v[12:15], v[158:161], v[186:189], 0
	v_mfma_f32_16x16x32_bf16 v[8:11], v[140:143], v[206:209], 0
	v_mfma_f32_16x16x32_bf16 v[4:7], v[146:149], v[206:209], 0
	v_mfma_f32_16x16x32_bf16 v[0:3], v[154:157], v[206:209], 0
	v_mfma_f32_16x16x32_bf16 v[88:91], v[158:161], v[206:209], 0
	s_add_u32 s48, s50, s26
	s_addc_u32 s49, s51, s27
	s_add_u32 s98, s48, s64
	s_addc_u32 s99, s49, s65
	s_mov_b32 m0, s7
	s_mov_b64 s[62:63], 0x1080080
	global_load_lds_dwordx4 v244, s[98:99]
	s_add_u32 s98, s48, s68
	s_addc_u32 s99, s49, s69
	s_add_i32 m0, s7, 0x2000
	s_nop 0
	global_load_lds_dwordx4 v244, s[98:99]
	s_add_u32 s98, s48, s38
	s_addc_u32 s99, s49, s39
	s_add_i32 m0, s7, 0x4000
	s_add_u32 s48, s48, s40
	s_addc_u32 s49, s49, s41
	global_load_lds_dwordx4 v244, s[98:99]
	s_add_i32 m0, s7, 0x6000
	s_nop 0
	global_load_lds_dwordx4 v244, s[48:49]
	s_add_u32 s48, s50, s26
	s_addc_u32 s49, s51, s27
	s_add_u32 s98, s48, s62
	s_addc_u32 s99, s49, s63
	s_add_i32 m0, s7, 0x8000
	s_mov_b64 s[62:63], 0x10a0080
	global_load_lds_dwordx4 v245, s[98:99]
	s_add_u32 s98, s48, s62
	s_addc_u32 s99, s49, s63
	s_add_i32 m0, s7, 0xa000
	s_mov_b64 s[62:63], 0x10c0080
	global_load_lds_dwordx4 v245, s[98:99]
	s_add_u32 s98, s48, s62
	s_addc_u32 s99, s49, s63
	s_add_i32 m0, s7, 0xc000
	s_mov_b64 s[62:63], 0x10e0080
	global_load_lds_dwordx4 v245, s[98:99]
	s_add_u32 s48, s48, s62
	s_addc_u32 s49, s49, s63
	s_add_i32 m0, s7, 0xe000
	s_nop 0
	global_load_lds_dwordx4 v245, s[48:49]
	ds_read_b128 v[140:143], v129 offset:8192
	ds_read_b128 v[146:149], v129 offset:10240
	ds_read_b128 v[154:157], v129 offset:12288
	ds_read_b128 v[158:161], v129 offset:14336
	s_waitcnt lgkmcnt(0)
	v_mfma_f32_16x16x32_bf16 v[124:127], v[162:165], v[216:219], v[124:127]
	v_mfma_f32_16x16x32_bf16 v[120:123], v[166:169], v[216:219], v[120:123]
	v_mfma_f32_16x16x32_bf16 v[116:119], v[170:173], v[216:219], v[116:119]
	v_mfma_f32_16x16x32_bf16 v[112:115], v[174:177], v[216:219], v[112:115]
	v_mfma_f32_16x16x32_bf16 v[108:111], v[162:165], v[220:223], v[108:111]
	v_mfma_f32_16x16x32_bf16 v[104:107], v[166:169], v[220:223], v[104:107]
	v_mfma_f32_16x16x32_bf16 v[100:103], v[170:173], v[220:223], v[100:103]
	v_mfma_f32_16x16x32_bf16 v[96:99], v[174:177], v[220:223], v[96:99]
	v_mfma_f32_16x16x32_bf16 v[92:95], v[162:165], v[224:227], v[92:95]
	v_mfma_f32_16x16x32_bf16 v[84:87], v[166:169], v[224:227], v[84:87]
	v_mfma_f32_16x16x32_bf16 v[80:83], v[170:173], v[224:227], v[80:83]
	v_mfma_f32_16x16x32_bf16 v[76:79], v[174:177], v[224:227], v[76:79]
	v_mfma_f32_16x16x32_bf16 v[72:75], v[162:165], v[228:231], v[72:75]
	v_mfma_f32_16x16x32_bf16 v[68:71], v[166:169], v[228:231], v[68:71]
	v_mfma_f32_16x16x32_bf16 v[64:67], v[170:173], v[228:231], v[64:67]
	v_mfma_f32_16x16x32_bf16 v[60:63], v[174:177], v[228:231], v[60:63]
	v_mfma_f32_16x16x32_bf16 v[56:59], v[162:165], v[140:143], v[56:59]
	s_add_u32 s26, s26, 0x80
	s_addc_u32 s27, s27, 0
	v_mfma_f32_16x16x32_bf16 v[52:55], v[166:169], v[140:143], v[52:55]
	s_cmpk_eq_i32 s26, 0x780
	s_mov_b32 s2, s3
	s_waitcnt vmcnt(0)
	v_mfma_f32_16x16x32_bf16 v[48:51], v[170:173], v[140:143], v[48:51]
	s_barrier
	v_mfma_f32_16x16x32_bf16 v[44:47], v[174:177], v[140:143], v[44:47]
	v_mfma_f32_16x16x32_bf16 v[40:43], v[162:165], v[146:149], v[40:43]
	v_mfma_f32_16x16x32_bf16 v[36:39], v[166:169], v[146:149], v[36:39]
	v_mfma_f32_16x16x32_bf16 v[32:35], v[170:173], v[146:149], v[32:35]
	v_mfma_f32_16x16x32_bf16 v[28:31], v[174:177], v[146:149], v[28:31]
	v_mfma_f32_16x16x32_bf16 v[24:27], v[162:165], v[154:157], v[24:27]
	v_mfma_f32_16x16x32_bf16 v[20:23], v[166:169], v[154:157], v[20:23]
	v_mfma_f32_16x16x32_bf16 v[16:19], v[170:173], v[154:157], v[16:19]
	v_mfma_f32_16x16x32_bf16 v[12:15], v[174:177], v[154:157], v[12:15]
	v_mfma_f32_16x16x32_bf16 v[8:11], v[162:165], v[158:161], v[8:11]
	v_mfma_f32_16x16x32_bf16 v[4:7], v[166:169], v[158:161], v[4:7]
	v_mfma_f32_16x16x32_bf16 v[0:3], v[170:173], v[158:161], v[0:3]
	v_mfma_f32_16x16x32_bf16 v[88:91], v[174:177], v[158:161], v[88:91]
	s_cbranch_scc1 .Lkx_420
.Lkb_420_l:
	s_add_i32 s3, s2, 0x10000
	s_and_b32 s7, s3, 0x10000
	s_add_i32 s7, s0, s7
	s_and_b32 s2, s2, 0x10000
	v_or_b32_e32 v129, s2, v139
	v_add_u32_e32 v144, v129, v138
	v_add_u32_e32 v129, v129, v136
	ds_read_b128 v[140:143], v144 offset:32768
	ds_read_b128 v[146:149], v144 offset:34816
	ds_read_b128 v[154:157], v144 offset:36864
	ds_read_b128 v[158:161], v144 offset:38912
	ds_read_b128 v[162:165], v129
	ds_read_b128 v[166:169], v129 offset:2048
	ds_read_b128 v[170:173], v129 offset:4096
	ds_read_b128 v[174:177], v129 offset:6144
	ds_read_b128 v[178:181], v129 offset:8192
	ds_read_b128 v[182:185], v129 offset:10240
	ds_read_b128 v[186:189], v129 offset:12288
	ds_read_b128 v[206:209], v129 offset:14336
	s_waitcnt lgkmcnt(0)
	v_mfma_f32_16x16x32_bf16 v[124:127], v[140:143], v[162:165], v[124:127]
	v_mfma_f32_16x16x32_bf16 v[120:123], v[146:149], v[162:165], v[120:123]
	v_mfma_f32_16x16x32_bf16 v[116:119], v[154:157], v[162:165], v[116:119]
	v_mfma_f32_16x16x32_bf16 v[112:115], v[158:161], v[162:165], v[112:115]
	v_mfma_f32_16x16x32_bf16 v[108:111], v[140:143], v[166:169], v[108:111]
	v_mfma_f32_16x16x32_bf16 v[104:107], v[146:149], v[166:169], v[104:107]
	v_mfma_f32_16x16x32_bf16 v[100:103], v[154:157], v[166:169], v[100:103]
	v_mfma_f32_16x16x32_bf16 v[96:99], v[158:161], v[166:169], v[96:99]
	v_mfma_f32_16x16x32_bf16 v[92:95], v[140:143], v[170:173], v[92:95]
	v_mfma_f32_16x16x32_bf16 v[84:87], v[146:149], v[170:173], v[84:87]
	v_mfma_f32_16x16x32_bf16 v[80:83], v[154:157], v[170:173], v[80:83]
	v_mfma_f32_16x16x32_bf16 v[76:79], v[158:161], v[170:173], v[76:79]
	v_mfma_f32_16x16x32_bf16 v[72:75], v[140:143], v[174:177], v[72:75]
	v_mfma_f32_16x16x32_bf16 v[68:71], v[146:149], v[174:177], v[68:71]
	v_mfma_f32_16x16x32_bf16 v[64:67], v[154:157], v[174:177], v[64:67]
	v_mfma_f32_16x16x32_bf16 v[60:63], v[158:161], v[174:177], v[60:63]
	v_or_b32_e32 v129, s2, v137
	v_add_u32_e32 v144, v129, v138
	v_add_u32_e32 v129, v129, v136
	ds_read_b128 v[162:165], v144 offset:32768
	ds_read_b128 v[166:169], v144 offset:34816
	ds_read_b128 v[170:173], v144 offset:36864
	ds_read_b128 v[174:177], v144 offset:38912
	ds_read_b128 v[216:219], v129
	ds_read_b128 v[220:223], v129 offset:2048
	ds_read_b128 v[224:227], v129 offset:4096
	ds_read_b128 v[228:231], v129 offset:6144
	v_mfma_f32_16x16x32_bf16 v[56:59], v[140:143], v[178:181], v[56:59]
	v_mfma_f32_16x16x32_bf16 v[52:55], v[146:149], v[178:181], v[52:55]
	v_mfma_f32_16x16x32_bf16 v[48:51], v[154:157], v[178:181], v[48:51]
	v_mfma_f32_16x16x32_bf16 v[44:47], v[158:161], v[178:181], v[44:47]
	v_mfma_f32_16x16x32_bf16 v[40:43], v[140:143], v[182:185], v[40:43]
	v_mfma_f32_16x16x32_bf16 v[36:39], v[146:149], v[182:185], v[36:39]
	v_mfma_f32_16x16x32_bf16 v[32:35], v[154:157], v[182:185], v[32:35]
	v_mfma_f32_16x16x32_bf16 v[28:31], v[158:161], v[182:185], v[28:31]
	v_mfma_f32_16x16x32_bf16 v[24:27], v[140:143], v[186:189], v[24:27]
	v_mfma_f32_16x16x32_bf16 v[20:23], v[146:149], v[186:189], v[20:23]
	v_mfma_f32_16x16x32_bf16 v[16:19], v[154:157], v[186:189], v[16:19]
	v_mfma_f32_16x16x32_bf16 v[12:15], v[158:161], v[186:189], v[12:15]
	v_mfma_f32_16x16x32_bf16 v[8:11], v[140:143], v[206:209], v[8:11]
	v_mfma_f32_16x16x32_bf16 v[4:7], v[146:149], v[206:209], v[4:7]
	v_mfma_f32_16x16x32_bf16 v[0:3], v[154:157], v[206:209], v[0:3]
	v_mfma_f32_16x16x32_bf16 v[88:91], v[158:161], v[206:209], v[88:91]
	s_add_u32 s48, s50, s26
	s_addc_u32 s49, s51, s27
	s_add_u32 s98, s48, s64
	s_addc_u32 s99, s49, s65
	s_mov_b32 m0, s7
	s_mov_b64 s[62:63], 0x1080080
	global_load_lds_dwordx4 v244, s[98:99]
	s_add_u32 s98, s48, s68
	s_addc_u32 s99, s49, s69
	s_add_i32 m0, s7, 0x2000
	s_nop 0
	global_load_lds_dwordx4 v244, s[98:99]
	s_add_u32 s98, s48, s38
	s_addc_u32 s99, s49, s39
	s_add_i32 m0, s7, 0x4000
	s_add_u32 s48, s48, s40
	s_addc_u32 s49, s49, s41
	global_load_lds_dwordx4 v244, s[98:99]
	s_add_i32 m0, s7, 0x6000
	s_nop 0
	global_load_lds_dwordx4 v244, s[48:49]
	s_add_u32 s48, s50, s26
	s_addc_u32 s49, s51, s27
	s_add_u32 s98, s48, s62
	s_addc_u32 s99, s49, s63
	s_add_i32 m0, s7, 0x8000
	s_mov_b64 s[62:63], 0x10a0080
	global_load_lds_dwordx4 v245, s[98:99]
	s_add_u32 s98, s48, s62
	s_addc_u32 s99, s49, s63
	s_add_i32 m0, s7, 0xa000
	s_mov_b64 s[62:63], 0x10c0080
	global_load_lds_dwordx4 v245, s[98:99]
	s_add_u32 s98, s48, s62
	s_addc_u32 s99, s49, s63
	s_add_i32 m0, s7, 0xc000
	s_mov_b64 s[62:63], 0x10e0080
	global_load_lds_dwordx4 v245, s[98:99]
	s_add_u32 s48, s48, s62
	s_addc_u32 s49, s49, s63
	s_add_i32 m0, s7, 0xe000
	s_nop 0
	global_load_lds_dwordx4 v245, s[48:49]
	ds_read_b128 v[140:143], v129 offset:8192
	ds_read_b128 v[146:149], v129 offset:10240
	ds_read_b128 v[154:157], v129 offset:12288
	ds_read_b128 v[158:161], v129 offset:14336
	s_waitcnt lgkmcnt(0)
	v_mfma_f32_16x16x32_bf16 v[124:127], v[162:165], v[216:219], v[124:127]
	v_mfma_f32_16x16x32_bf16 v[120:123], v[166:169], v[216:219], v[120:123]
	v_mfma_f32_16x16x32_bf16 v[116:119], v[170:173], v[216:219], v[116:119]
	v_mfma_f32_16x16x32_bf16 v[112:115], v[174:177], v[216:219], v[112:115]
	v_mfma_f32_16x16x32_bf16 v[108:111], v[162:165], v[220:223], v[108:111]
	v_mfma_f32_16x16x32_bf16 v[104:107], v[166:169], v[220:223], v[104:107]
	v_mfma_f32_16x16x32_bf16 v[100:103], v[170:173], v[220:223], v[100:103]
	v_mfma_f32_16x16x32_bf16 v[96:99], v[174:177], v[220:223], v[96:99]
	v_mfma_f32_16x16x32_bf16 v[92:95], v[162:165], v[224:227], v[92:95]
	v_mfma_f32_16x16x32_bf16 v[84:87], v[166:169], v[224:227], v[84:87]
	v_mfma_f32_16x16x32_bf16 v[80:83], v[170:173], v[224:227], v[80:83]
	v_mfma_f32_16x16x32_bf16 v[76:79], v[174:177], v[224:227], v[76:79]
	v_mfma_f32_16x16x32_bf16 v[72:75], v[162:165], v[228:231], v[72:75]
	v_mfma_f32_16x16x32_bf16 v[68:71], v[166:169], v[228:231], v[68:71]
	v_mfma_f32_16x16x32_bf16 v[64:67], v[170:173], v[228:231], v[64:67]
	v_mfma_f32_16x16x32_bf16 v[60:63], v[174:177], v[228:231], v[60:63]
	v_mfma_f32_16x16x32_bf16 v[56:59], v[162:165], v[140:143], v[56:59]
	s_add_u32 s26, s26, 0x80
	s_addc_u32 s27, s27, 0
	v_mfma_f32_16x16x32_bf16 v[52:55], v[166:169], v[140:143], v[52:55]
	s_cmpk_eq_i32 s26, 0x780
	s_mov_b32 s2, s3
	s_waitcnt vmcnt(0)
	v_mfma_f32_16x16x32_bf16 v[48:51], v[170:173], v[140:143], v[48:51]
	s_barrier
	v_mfma_f32_16x16x32_bf16 v[44:47], v[174:177], v[140:143], v[44:47]
	v_mfma_f32_16x16x32_bf16 v[40:43], v[162:165], v[146:149], v[40:43]
	v_mfma_f32_16x16x32_bf16 v[36:39], v[166:169], v[146:149], v[36:39]
	v_mfma_f32_16x16x32_bf16 v[32:35], v[170:173], v[146:149], v[32:35]
	v_mfma_f32_16x16x32_bf16 v[28:31], v[174:177], v[146:149], v[28:31]
	v_mfma_f32_16x16x32_bf16 v[24:27], v[162:165], v[154:157], v[24:27]
	v_mfma_f32_16x16x32_bf16 v[20:23], v[166:169], v[154:157], v[20:23]
	v_mfma_f32_16x16x32_bf16 v[16:19], v[170:173], v[154:157], v[16:19]
	v_mfma_f32_16x16x32_bf16 v[12:15], v[174:177], v[154:157], v[12:15]
	v_mfma_f32_16x16x32_bf16 v[8:11], v[162:165], v[158:161], v[8:11]
	v_mfma_f32_16x16x32_bf16 v[4:7], v[166:169], v[158:161], v[4:7]
	v_mfma_f32_16x16x32_bf16 v[0:3], v[170:173], v[158:161], v[0:3]
	v_mfma_f32_16x16x32_bf16 v[88:91], v[174:177], v[158:161], v[88:91]
	s_cbranch_scc0 .Lkb_420_l

.LBB0_499:
	s_ashr_i32 s2, s34, 5
	s_lshr_b32 s3, s2, 30
	s_add_i32 s3, s2, s3
	s_and_b32 s36, s3, -4
	s_sub_i32 s35, s2, s36
	s_lshl_b32 s2, s34, 3
	s_and_b32 s2, s2, 56
	s_bfe_u32 s27, s34, 0x20003
	s_add_i32 s2, s36, s2
	s_or_b32 s2, s2, s27
	s_and_b32 s26, s31, 56
	s_mul_i32 s6, s2, 0x160000
	s_mul_hi_i32 s3, s2, 0x160000
	s_add_u32 s6, s29, s6
	s_addc_u32 s7, s30, s3
	s_mul_i32 s3, s35, 0x160000
	s_ashr_i32 s9, s3, 31
	s_waitcnt vmcnt(0) lgkmcnt(0)
	v_mov_b32_e32 v4, v190
	s_add_u32 s8, s0, s3
	s_mov_b32 s3, 0x1ffff80
	v_and_b32_e32 v0, 15, v4
	v_lshrrev_b32_e32 v2, 1, v4
	v_and_or_b32 v0, v2, s3, v0
	v_bfe_u32 v1, v4, 4, 2
	v_lshlrev_b32_e32 v132, 7, v0
	v_bfe_u32 v0, v4, 1, 3
	v_lshrrev_b32_e32 v5, 4, v4
	v_bitop3_b32 v2, v2, v1, 7 bitop3:0x6c
	v_bitop3_b32 v0, v1, v0, 4 bitop3:0x36
	v_lshlrev_b32_e32 v135, 4, v2
	v_lshlrev_b32_e32 v133, 4, v0
	v_lshlrev_b32_e32 v0, 7, v4
	v_xor_b32_e32 v2, v5, v4
	v_readfirstlane_b32 s3, v4
	s_addc_u32 s9, s28, s9
	v_and_b32_e32 v134, 0x6780, v0
	v_ashrrev_i32_e32 v6, 3, v4
	v_mov_b64_e32 v[0:1], s[6:7]
	v_lshlrev_b32_e32 v2, 4, v2
	s_lshl_b32 s3, s3, 4
	v_mad_i64_i32 v[0:1], s[6:7], v6, s33, v[0:1]
	v_and_b32_e32 v144, 0x70, v2
	v_mov_b64_e32 v[2:3], s[8:9]
	s_and_b32 s3, s3, 0xfffffc00
	v_lshl_add_u64 v[0:1], v[0:1], 0, v[144:145]
	v_mad_i64_i32 v[2:3], s[6:7], v6, s33, v[2:3]
	s_mov_b32 m0, s3
	v_lshl_add_u64 v[128:129], v[2:3], 0, v[144:145]
	s_barrier
	global_load_lds_dwordx4 v[0:1], off
	v_lshl_add_u64 v[2:3], v[0:1], 0, s[54:55]
	s_add_i32 m0, s3, 0x2000
	s_add_i32 s26, s26, s36
	global_load_lds_dwordx4 v[2:3], off
	v_lshl_add_u64 v[2:3], v[0:1], 0, s[56:57]
	s_add_i32 m0, s3, 0x4000
	v_lshl_add_u64 v[0:1], v[0:1], 0, s[62:63]
	global_load_lds_dwordx4 v[2:3], off
	s_add_i32 m0, s3, 0x6000
	s_or_b32 s8, s26, s27
	global_load_lds_dwordx4 v[0:1], off
	s_add_i32 m0, s3, 0x8000
	v_lshl_add_u64 v[0:1], v[128:129], 0, s[54:55]
	global_load_lds_dwordx4 v[128:129], off
	s_add_i32 m0, s3, 0xa000
	v_bitop3_b32 v2, v5, 7, v4 bitop3:0x48
	global_load_lds_dwordx4 v[0:1], off
	v_lshl_add_u64 v[0:1], v[128:129], 0, s[56:57]
	s_add_i32 m0, s3, 0xc000
	global_load_lds_dwordx4 v[0:1], off
	v_lshl_add_u64 v[0:1], v[128:129], 0, s[62:63]
	s_add_i32 m0, s3, 0xe000
	global_load_lds_dwordx4 v[0:1], off
	v_mad_i64_i32 v[0:1], s[6:7], v6, s33, 0
	s_waitcnt vmcnt(0)
	v_mad_i64_i32 v[0:1], s[6:7], s8, v210, v[0:1]
	v_lshl_or_b32 v0, v2, 4, v0
	v_lshl_add_u64 v[130:131], s[14:15], 0, v[0:1]
	s_mov_b64 s[6:7], 0
	s_mov_b32 s8, 0
	s_waitcnt vmcnt(0) lgkmcnt(0)
	s_barrier
	v_readlane_b32 s50, v255, 24
	v_readlane_b32 s51, v255, 25
	s_nop 1
	v_subrev_u32_e32 v244, s50, v130
	v_subrev_u32_e32 v245, s50, v128
	s_bitcmp1_b32 s3, 12
	s_cbranch_scc1 .Lkb_500
	s_add_i32 s9, s8, 0x10000
	s_and_b32 s26, s9, 0x10000
	s_add_i32 s36, s3, s26
	s_add_u32 s48, s50, s6
	s_addc_u32 s49, s51, s7
	s_mov_b64 s[26:27], 0x59e0080
	s_add_u32 s98, s48, s26
	s_addc_u32 s99, s49, s27
	s_mov_b32 m0, s36
	s_mov_b64 s[26:27], 0x5a38080
	global_load_lds_dwordx4 v244, s[98:99]
	s_add_u32 s98, s48, s26
	s_addc_u32 s99, s49, s27
	s_add_i32 m0, s36, 0x2000
	s_mov_b64 s[26:27], 0x5a90080
	global_load_lds_dwordx4 v244, s[98:99]
	s_add_u32 s98, s48, s26
	s_addc_u32 s99, s49, s27
	s_add_i32 m0, s36, 0x4000
	s_mov_b64 s[26:27], 0x5ae8080
	global_load_lds_dwordx4 v244, s[98:99]
	s_add_u32 s48, s48, s26
	s_addc_u32 s49, s49, s27
	s_add_i32 m0, s36, 0x6000
	s_mov_b64 s[26:27], 0x58080
	global_load_lds_dwordx4 v244, s[48:49]
	s_add_u32 s48, s50, s6
	s_addc_u32 s49, s51, s7
	s_add_u32 s98, s48, s10
	s_addc_u32 s99, s49, s11
	s_add_i32 m0, s36, 0x8000
	s_nop 0
	global_load_lds_dwordx4 v245, s[98:99]
	s_add_u32 s98, s48, s26
	s_addc_u32 s99, s49, s27
	s_add_i32 m0, s36, 0xa000
	s_mov_b64 s[26:27], 0xb0080
	global_load_lds_dwordx4 v245, s[98:99]
	s_add_u32 s98, s48, s26
	s_addc_u32 s99, s49, s27
	s_add_i32 m0, s36, 0xc000
	s_mov_b64 s[26:27], 0x108080
	global_load_lds_dwordx4 v245, s[98:99]
	s_add_u32 s48, s48, s26
	s_addc_u32 s49, s49, s27
	s_add_i32 m0, s36, 0xe000
	s_nop 0
	global_load_lds_dwordx4 v245, s[48:49]
	s_and_b32 s8, s8, 0x10000
	v_or_b32_e32 v144, s8, v135
	v_add_u32_e32 v151, v144, v134
	v_add_u32_e32 v144, v144, v132
	ds_read_b128 v[136:139], v151 offset:32768
	ds_read_b128 v[140:143], v151 offset:34816
	ds_read_b128 v[146:149], v151 offset:36864
	ds_read_b128 v[154:157], v151 offset:38912
	ds_read_b128 v[158:161], v144
	ds_read_b128 v[162:165], v144 offset:2048
	ds_read_b128 v[166:169], v144 offset:4096
	ds_read_b128 v[170:173], v144 offset:6144
	ds_read_b128 v[174:177], v144 offset:8192
	ds_read_b128 v[178:181], v144 offset:10240
	ds_read_b128 v[182:185], v144 offset:12288
	ds_read_b128 v[186:189], v144 offset:14336
	s_waitcnt lgkmcnt(0)
	v_mfma_f32_16x16x32_bf16 v[124:127], v[136:139], v[158:161], 0
	v_mfma_f32_16x16x32_bf16 v[120:123], v[140:143], v[158:161], 0
	v_mfma_f32_16x16x32_bf16 v[116:119], v[146:149], v[158:161], 0
	v_mfma_f32_16x16x32_bf16 v[112:115], v[154:157], v[158:161], 0
	v_mfma_f32_16x16x32_bf16 v[108:111], v[136:139], v[162:165], 0
	v_mfma_f32_16x16x32_bf16 v[104:107], v[140:143], v[162:165], 0
	v_mfma_f32_16x16x32_bf16 v[100:103], v[146:149], v[162:165], 0
	v_mfma_f32_16x16x32_bf16 v[96:99], v[154:157], v[162:165], 0
	v_mfma_f32_16x16x32_bf16 v[92:95], v[136:139], v[166:169], 0
	v_mfma_f32_16x16x32_bf16 v[84:87], v[140:143], v[166:169], 0
	v_mfma_f32_16x16x32_bf16 v[80:83], v[146:149], v[166:169], 0
	v_mfma_f32_16x16x32_bf16 v[76:79], v[154:157], v[166:169], 0
	v_mfma_f32_16x16x32_bf16 v[72:75], v[136:139], v[170:173], 0
	v_mfma_f32_16x16x32_bf16 v[68:71], v[140:143], v[170:173], 0
	v_mfma_f32_16x16x32_bf16 v[64:67], v[146:149], v[170:173], 0
	v_mfma_f32_16x16x32_bf16 v[60:63], v[154:157], v[170:173], 0
	v_or_b32_e32 v144, s8, v133
	v_add_u32_e32 v151, v144, v134
	v_add_u32_e32 v144, v144, v132
	ds_read_b128 v[158:161], v151 offset:32768
	ds_read_b128 v[162:165], v151 offset:34816
	ds_read_b128 v[166:169], v151 offset:36864
	ds_read_b128 v[170:173], v151 offset:38912
	ds_read_b128 v[206:209], v144
	ds_read_b128 v[216:219], v144 offset:2048
	ds_read_b128 v[220:223], v144 offset:4096
	ds_read_b128 v[224:227], v144 offset:6144
	v_mfma_f32_16x16x32_bf16 v[56:59], v[136:139], v[174:177], 0
	v_mfma_f32_16x16x32_bf16 v[52:55], v[140:143], v[174:177], 0
	v_mfma_f32_16x16x32_bf16 v[48:51], v[146:149], v[174:177], 0
	v_mfma_f32_16x16x32_bf16 v[44:47], v[154:157], v[174:177], 0
	v_mfma_f32_16x16x32_bf16 v[40:43], v[136:139], v[178:181], 0
	v_mfma_f32_16x16x32_bf16 v[36:39], v[140:143], v[178:181], 0
	v_mfma_f32_16x16x32_bf16 v[32:35], v[146:149], v[178:181], 0
	v_mfma_f32_16x16x32_bf16 v[28:31], v[154:157], v[178:181], 0
	v_mfma_f32_16x16x32_bf16 v[24:27], v[136:139], v[182:185], 0
	v_mfma_f32_16x16x32_bf16 v[20:23], v[140:143], v[182:185], 0
	v_mfma_f32_16x16x32_bf16 v[16:19], v[146:149], v[182:185], 0
	v_mfma_f32_16x16x32_bf16 v[12:15], v[154:157], v[182:185], 0
	v_mfma_f32_16x16x32_bf16 v[8:11], v[136:139], v[186:189], 0
	v_mfma_f32_16x16x32_bf16 v[4:7], v[140:143], v[186:189], 0
	v_mfma_f32_16x16x32_bf16 v[0:3], v[146:149], v[186:189], 0
	v_mfma_f32_16x16x32_bf16 v[88:91], v[154:157], v[186:189], 0
	ds_read_b128 v[136:139], v144 offset:8192
	ds_read_b128 v[140:143], v144 offset:10240
	ds_read_b128 v[146:149], v144 offset:12288
	ds_read_b128 v[154:157], v144 offset:14336
	s_waitcnt lgkmcnt(0)
	v_mfma_f32_16x16x32_bf16 v[124:127], v[158:161], v[206:209], v[124:127]
	v_mfma_f32_16x16x32_bf16 v[120:123], v[162:165], v[206:209], v[120:123]
	v_mfma_f32_16x16x32_bf16 v[116:119], v[166:169], v[206:209], v[116:119]
	v_mfma_f32_16x16x32_bf16 v[112:115], v[170:173], v[206:209], v[112:115]
	v_mfma_f32_16x16x32_bf16 v[108:111], v[158:161], v[216:219], v[108:111]
	v_mfma_f32_16x16x32_bf16 v[104:107], v[162:165], v[216:219], v[104:107]
	v_mfma_f32_16x16x32_bf16 v[100:103], v[166:169], v[216:219], v[100:103]
	v_mfma_f32_16x16x32_bf16 v[96:99], v[170:173], v[216:219], v[96:99]
	v_mfma_f32_16x16x32_bf16 v[92:95], v[158:161], v[220:223], v[92:95]
	v_mfma_f32_16x16x32_bf16 v[84:87], v[162:165], v[220:223], v[84:87]
	v_mfma_f32_16x16x32_bf16 v[80:83], v[166:169], v[220:223], v[80:83]
	v_mfma_f32_16x16x32_bf16 v[76:79], v[170:173], v[220:223], v[76:79]
	v_mfma_f32_16x16x32_bf16 v[72:75], v[158:161], v[224:227], v[72:75]
	v_mfma_f32_16x16x32_bf16 v[68:71], v[162:165], v[224:227], v[68:71]
	v_mfma_f32_16x16x32_bf16 v[64:67], v[166:169], v[224:227], v[64:67]
	v_mfma_f32_16x16x32_bf16 v[60:63], v[170:173], v[224:227], v[60:63]
	v_mfma_f32_16x16x32_bf16 v[56:59], v[158:161], v[136:139], v[56:59]
	s_add_u32 s6, s6, 0x80
	s_addc_u32 s7, s7, 0
	v_mfma_f32_16x16x32_bf16 v[52:55], v[162:165], v[136:139], v[52:55]
	s_cmpk_eq_i32 s6, 0x1580
	s_mov_b32 s8, s9
	s_waitcnt vmcnt(0)
	v_mfma_f32_16x16x32_bf16 v[48:51], v[166:169], v[136:139], v[48:51]
	s_barrier
	v_mfma_f32_16x16x32_bf16 v[44:47], v[170:173], v[136:139], v[44:47]
	v_mfma_f32_16x16x32_bf16 v[40:43], v[158:161], v[140:143], v[40:43]
	v_mfma_f32_16x16x32_bf16 v[36:39], v[162:165], v[140:143], v[36:39]
	v_mfma_f32_16x16x32_bf16 v[32:35], v[166:169], v[140:143], v[32:35]
	v_mfma_f32_16x16x32_bf16 v[28:31], v[170:173], v[140:143], v[28:31]
	v_mfma_f32_16x16x32_bf16 v[24:27], v[158:161], v[146:149], v[24:27]
	v_mfma_f32_16x16x32_bf16 v[20:23], v[162:165], v[146:149], v[20:23]
	v_mfma_f32_16x16x32_bf16 v[16:19], v[166:169], v[146:149], v[16:19]
	v_mfma_f32_16x16x32_bf16 v[12:15], v[170:173], v[146:149], v[12:15]
	v_mfma_f32_16x16x32_bf16 v[8:11], v[158:161], v[154:157], v[8:11]
	v_mfma_f32_16x16x32_bf16 v[4:7], v[162:165], v[154:157], v[4:7]
	v_mfma_f32_16x16x32_bf16 v[0:3], v[166:169], v[154:157], v[0:3]
	v_mfma_f32_16x16x32_bf16 v[88:91], v[170:173], v[154:157], v[88:91]
	s_cbranch_scc1 .Lkx_500
.LBB0_500:
	s_add_i32 s9, s8, 0x10000
	s_and_b32 s26, s9, 0x10000
	s_add_i32 s36, s3, s26
	s_add_u32 s48, s50, s6
	s_addc_u32 s49, s51, s7
	s_mov_b64 s[26:27], 0x59e0080
	s_add_u32 s98, s48, s26
	s_addc_u32 s99, s49, s27
	s_mov_b32 m0, s36
	s_mov_b64 s[26:27], 0x5a38080
	global_load_lds_dwordx4 v244, s[98:99]
	s_add_u32 s98, s48, s26
	s_addc_u32 s99, s49, s27
	s_add_i32 m0, s36, 0x2000
	s_mov_b64 s[26:27], 0x5a90080
	global_load_lds_dwordx4 v244, s[98:99]
	s_add_u32 s98, s48, s26
	s_addc_u32 s99, s49, s27
	s_add_i32 m0, s36, 0x4000
	s_mov_b64 s[26:27], 0x5ae8080
	global_load_lds_dwordx4 v244, s[98:99]
	s_add_u32 s48, s48, s26
	s_addc_u32 s49, s49, s27
	s_add_i32 m0, s36, 0x6000
	s_mov_b64 s[26:27], 0x58080
	global_load_lds_dwordx4 v244, s[48:49]
	s_add_u32 s48, s50, s6
	s_addc_u32 s49, s51, s7
	s_add_u32 s98, s48, s10
	s_addc_u32 s99, s49, s11
	s_add_i32 m0, s36, 0x8000
	s_nop 0
	global_load_lds_dwordx4 v245, s[98:99]
	s_add_u32 s98, s48, s26
	s_addc_u32 s99, s49, s27
	s_add_i32 m0, s36, 0xa000
	s_mov_b64 s[26:27], 0xb0080
	global_load_lds_dwordx4 v245, s[98:99]
	s_add_u32 s98, s48, s26
	s_addc_u32 s99, s49, s27
	s_add_i32 m0, s36, 0xc000
	s_mov_b64 s[26:27], 0x108080
	global_load_lds_dwordx4 v245, s[98:99]
	s_add_u32 s48, s48, s26
	s_addc_u32 s49, s49, s27
	s_add_i32 m0, s36, 0xe000
	s_nop 0
	global_load_lds_dwordx4 v245, s[48:49]
	s_and_b32 s8, s8, 0x10000
	v_or_b32_e32 v144, s8, v135
	v_add_u32_e32 v151, v144, v134
	v_add_u32_e32 v144, v144, v132
	ds_read_b128 v[136:139], v151 offset:32768
	ds_read_b128 v[140:143], v151 offset:34816
	ds_read_b128 v[146:149], v151 offset:36864
	ds_read_b128 v[154:157], v151 offset:38912
	ds_read_b128 v[158:161], v144
	ds_read_b128 v[162:165], v144 offset:2048
	ds_read_b128 v[166:169], v144 offset:4096
	ds_read_b128 v[170:173], v144 offset:6144
	ds_read_b128 v[174:177], v144 offset:8192
	ds_read_b128 v[178:181], v144 offset:10240
	ds_read_b128 v[182:185], v144 offset:12288
	ds_read_b128 v[186:189], v144 offset:14336
	s_waitcnt lgkmcnt(0)
	v_mfma_f32_16x16x32_bf16 v[124:127], v[136:139], v[158:161], v[124:127]
	v_mfma_f32_16x16x32_bf16 v[120:123], v[140:143], v[158:161], v[120:123]
	v_mfma_f32_16x16x32_bf16 v[116:119], v[146:149], v[158:161], v[116:119]
	v_mfma_f32_16x16x32_bf16 v[112:115], v[154:157], v[158:161], v[112:115]
	v_mfma_f32_16x16x32_bf16 v[108:111], v[136:139], v[162:165], v[108:111]
	v_mfma_f32_16x16x32_bf16 v[104:107], v[140:143], v[162:165], v[104:107]
	v_mfma_f32_16x16x32_bf16 v[100:103], v[146:149], v[162:165], v[100:103]
	v_mfma_f32_16x16x32_bf16 v[96:99], v[154:157], v[162:165], v[96:99]
	v_mfma_f32_16x16x32_bf16 v[92:95], v[136:139], v[166:169], v[92:95]
	v_mfma_f32_16x16x32_bf16 v[84:87], v[140:143], v[166:169], v[84:87]
	v_mfma_f32_16x16x32_bf16 v[80:83], v[146:149], v[166:169], v[80:83]
	v_mfma_f32_16x16x32_bf16 v[76:79], v[154:157], v[166:169], v[76:79]
	v_mfma_f32_16x16x32_bf16 v[72:75], v[136:139], v[170:173], v[72:75]
	v_mfma_f32_16x16x32_bf16 v[68:71], v[140:143], v[170:173], v[68:71]
	v_mfma_f32_16x16x32_bf16 v[64:67], v[146:149], v[170:173], v[64:67]
	v_mfma_f32_16x16x32_bf16 v[60:63], v[154:157], v[170:173], v[60:63]
	v_or_b32_e32 v144, s8, v133
	v_add_u32_e32 v151, v144, v134
	v_add_u32_e32 v144, v144, v132
	ds_read_b128 v[158:161], v151 offset:32768
	ds_read_b128 v[162:165], v151 offset:34816
	ds_read_b128 v[166:169], v151 offset:36864
	ds_read_b128 v[170:173], v151 offset:38912
	ds_read_b128 v[206:209], v144
	ds_read_b128 v[216:219], v144 offset:2048
	ds_read_b128 v[220:223], v144 offset:4096
	ds_read_b128 v[224:227], v144 offset:6144
	v_mfma_f32_16x16x32_bf16 v[56:59], v[136:139], v[174:177], v[56:59]
	v_mfma_f32_16x16x32_bf16 v[52:55], v[140:143], v[174:177], v[52:55]
	v_mfma_f32_16x16x32_bf16 v[48:51], v[146:149], v[174:177], v[48:51]
	v_mfma_f32_16x16x32_bf16 v[44:47], v[154:157], v[174:177], v[44:47]
	v_mfma_f32_16x16x32_bf16 v[40:43], v[136:139], v[178:181], v[40:43]
	v_mfma_f32_16x16x32_bf16 v[36:39], v[140:143], v[178:181], v[36:39]
	v_mfma_f32_16x16x32_bf16 v[32:35], v[146:149], v[178:181], v[32:35]
	v_mfma_f32_16x16x32_bf16 v[28:31], v[154:157], v[178:181], v[28:31]
	v_mfma_f32_16x16x32_bf16 v[24:27], v[136:139], v[182:185], v[24:27]
	v_mfma_f32_16x16x32_bf16 v[20:23], v[140:143], v[182:185], v[20:23]
	v_mfma_f32_16x16x32_bf16 v[16:19], v[146:149], v[182:185], v[16:19]
	v_mfma_f32_16x16x32_bf16 v[12:15], v[154:157], v[182:185], v[12:15]
	v_mfma_f32_16x16x32_bf16 v[8:11], v[136:139], v[186:189], v[8:11]
	v_mfma_f32_16x16x32_bf16 v[4:7], v[140:143], v[186:189], v[4:7]
	v_mfma_f32_16x16x32_bf16 v[0:3], v[146:149], v[186:189], v[0:3]
	v_mfma_f32_16x16x32_bf16 v[88:91], v[154:157], v[186:189], v[88:91]
	ds_read_b128 v[136:139], v144 offset:8192
	ds_read_b128 v[140:143], v144 offset:10240
	ds_read_b128 v[146:149], v144 offset:12288
	ds_read_b128 v[154:157], v144 offset:14336
	s_waitcnt lgkmcnt(0)
	v_mfma_f32_16x16x32_bf16 v[124:127], v[158:161], v[206:209], v[124:127]
	v_mfma_f32_16x16x32_bf16 v[120:123], v[162:165], v[206:209], v[120:123]
	v_mfma_f32_16x16x32_bf16 v[116:119], v[166:169], v[206:209], v[116:119]
	v_mfma_f32_16x16x32_bf16 v[112:115], v[170:173], v[206:209], v[112:115]
	v_mfma_f32_16x16x32_bf16 v[108:111], v[158:161], v[216:219], v[108:111]
	v_mfma_f32_16x16x32_bf16 v[104:107], v[162:165], v[216:219], v[104:107]
	v_mfma_f32_16x16x32_bf16 v[100:103], v[166:169], v[216:219], v[100:103]
	v_mfma_f32_16x16x32_bf16 v[96:99], v[170:173], v[216:219], v[96:99]
	v_mfma_f32_16x16x32_bf16 v[92:95], v[158:161], v[220:223], v[92:95]
	v_mfma_f32_16x16x32_bf16 v[84:87], v[162:165], v[220:223], v[84:87]
	v_mfma_f32_16x16x32_bf16 v[80:83], v[166:169], v[220:223], v[80:83]
	v_mfma_f32_16x16x32_bf16 v[76:79], v[170:173], v[220:223], v[76:79]
	v_mfma_f32_16x16x32_bf16 v[72:75], v[158:161], v[224:227], v[72:75]
	v_mfma_f32_16x16x32_bf16 v[68:71], v[162:165], v[224:227], v[68:71]
	v_mfma_f32_16x16x32_bf16 v[64:67], v[166:169], v[224:227], v[64:67]
	v_mfma_f32_16x16x32_bf16 v[60:63], v[170:173], v[224:227], v[60:63]
	v_mfma_f32_16x16x32_bf16 v[56:59], v[158:161], v[136:139], v[56:59]
	s_add_u32 s6, s6, 0x80
	s_addc_u32 s7, s7, 0
	v_mfma_f32_16x16x32_bf16 v[52:55], v[162:165], v[136:139], v[52:55]
	s_cmpk_eq_i32 s6, 0x1580
	s_mov_b32 s8, s9
	s_waitcnt vmcnt(0)
	v_mfma_f32_16x16x32_bf16 v[48:51], v[166:169], v[136:139], v[48:51]
	s_barrier
	v_mfma_f32_16x16x32_bf16 v[44:47], v[170:173], v[136:139], v[44:47]
	v_mfma_f32_16x16x32_bf16 v[40:43], v[158:161], v[140:143], v[40:43]
	v_mfma_f32_16x16x32_bf16 v[36:39], v[162:165], v[140:143], v[36:39]
	v_mfma_f32_16x16x32_bf16 v[32:35], v[166:169], v[140:143], v[32:35]
	v_mfma_f32_16x16x32_bf16 v[28:31], v[170:173], v[140:143], v[28:31]
	v_mfma_f32_16x16x32_bf16 v[24:27], v[158:161], v[146:149], v[24:27]
	v_mfma_f32_16x16x32_bf16 v[20:23], v[162:165], v[146:149], v[20:23]
	v_mfma_f32_16x16x32_bf16 v[16:19], v[166:169], v[146:149], v[16:19]
	v_mfma_f32_16x16x32_bf16 v[12:15], v[170:173], v[146:149], v[12:15]
	v_mfma_f32_16x16x32_bf16 v[8:11], v[158:161], v[154:157], v[8:11]
	v_mfma_f32_16x16x32_bf16 v[4:7], v[162:165], v[154:157], v[4:7]
	v_mfma_f32_16x16x32_bf16 v[0:3], v[166:169], v[154:157], v[0:3]
	v_mfma_f32_16x16x32_bf16 v[88:91], v[170:173], v[154:157], v[88:91]
	s_cbranch_scc0 .LBB0_500
	s_branch .Lkx_500
.Lkb_500:
	s_add_i32 s9, s8, 0x10000
	s_and_b32 s26, s9, 0x10000
	s_add_i32 s36, s3, s26
	s_and_b32 s8, s8, 0x10000
	v_or_b32_e32 v144, s8, v135
	v_add_u32_e32 v151, v144, v134
	v_add_u32_e32 v144, v144, v132
	ds_read_b128 v[136:139], v151 offset:32768
	ds_read_b128 v[140:143], v151 offset:34816
	ds_read_b128 v[146:149], v151 offset:36864
	ds_read_b128 v[154:157], v151 offset:38912
	ds_read_b128 v[158:161], v144
	ds_read_b128 v[162:165], v144 offset:2048
	ds_read_b128 v[166:169], v144 offset:4096
	ds_read_b128 v[170:173], v144 offset:6144
	ds_read_b128 v[174:177], v144 offset:8192
	ds_read_b128 v[178:181], v144 offset:10240
	ds_read_b128 v[182:185], v144 offset:12288
	ds_read_b128 v[186:189], v144 offset:14336
	s_waitcnt lgkmcnt(0)
	v_mfma_f32_16x16x32_bf16 v[124:127], v[136:139], v[158:161], 0
	v_mfma_f32_16x16x32_bf16 v[120:123], v[140:143], v[158:161], 0
	v_mfma_f32_16x16x32_bf16 v[116:119], v[146:149], v[158:161], 0
	v_mfma_f32_16x16x32_bf16 v[112:115], v[154:157], v[158:161], 0
	v_mfma_f32_16x16x32_bf16 v[108:111], v[136:139], v[162:165], 0
	v_mfma_f32_16x16x32_bf16 v[104:107], v[140:143], v[162:165], 0
	v_mfma_f32_16x16x32_bf16 v[100:103], v[146:149], v[162:165], 0
	v_mfma_f32_16x16x32_bf16 v[96:99], v[154:157], v[162:165], 0
	v_mfma_f32_16x16x32_bf16 v[92:95], v[136:139], v[166:169], 0
	v_mfma_f32_16x16x32_bf16 v[84:87], v[140:143], v[166:169], 0
	v_mfma_f32_16x16x32_bf16 v[80:83], v[146:149], v[166:169], 0
	v_mfma_f32_16x16x32_bf16 v[76:79], v[154:157], v[166:169], 0
	v_mfma_f32_16x16x32_bf16 v[72:75], v[136:139], v[170:173], 0
	v_mfma_f32_16x16x32_bf16 v[68:71], v[140:143], v[170:173], 0
	v_mfma_f32_16x16x32_bf16 v[64:67], v[146:149], v[170:173], 0
	v_mfma_f32_16x16x32_bf16 v[60:63], v[154:157], v[170:173], 0
	v_or_b32_e32 v144, s8, v133
	v_add_u32_e32 v151, v144, v134
	v_add_u32_e32 v144, v144, v132
	ds_read_b128 v[158:161], v151 offset:32768
	ds_read_b128 v[162:165], v151 offset:34816
	ds_read_b128 v[166:169], v151 offset:36864
	ds_read_b128 v[170:173], v151 offset:38912
	ds_read_b128 v[206:209], v144
	ds_read_b128 v[216:219], v144 offset:2048
	ds_read_b128 v[220:223], v144 offset:4096
	ds_read_b128 v[224:227], v144 offset:6144
	v_mfma_f32_16x16x32_bf16 v[56:59], v[136:139], v[174:177], 0
	v_mfma_f32_16x16x32_bf16 v[52:55], v[140:143], v[174:177], 0
	v_mfma_f32_16x16x32_bf16 v[48:51], v[146:149], v[174:177], 0
	v_mfma_f32_16x16x32_bf16 v[44:47], v[154:157], v[174:177], 0
	v_mfma_f32_16x16x32_bf16 v[40:43], v[136:139], v[178:181], 0
	v_mfma_f32_16x16x32_bf16 v[36:39], v[140:143], v[178:181], 0
	v_mfma_f32_16x16x32_bf16 v[32:35], v[146:149], v[178:181], 0
	v_mfma_f32_16x16x32_bf16 v[28:31], v[154:157], v[178:181], 0
	v_mfma_f32_16x16x32_bf16 v[24:27], v[136:139], v[182:185], 0
	v_mfma_f32_16x16x32_bf16 v[20:23], v[140:143], v[182:185], 0
	v_mfma_f32_16x16x32_bf16 v[16:19], v[146:149], v[182:185], 0
	v_mfma_f32_16x16x32_bf16 v[12:15], v[154:157], v[182:185], 0
	v_mfma_f32_16x16x32_bf16 v[8:11], v[136:139], v[186:189], 0
	v_mfma_f32_16x16x32_bf16 v[4:7], v[140:143], v[186:189], 0
	v_mfma_f32_16x16x32_bf16 v[0:3], v[146:149], v[186:189], 0
	v_mfma_f32_16x16x32_bf16 v[88:91], v[154:157], v[186:189], 0
	s_add_u32 s48, s50, s6
	s_addc_u32 s49, s51, s7
	s_mov_b64 s[26:27], 0x59e0080
	s_add_u32 s98, s48, s26
	s_addc_u32 s99, s49, s27
	s_mov_b32 m0, s36
	s_mov_b64 s[26:27], 0x5a38080
	global_load_lds_dwordx4 v244, s[98:99]
	s_add_u32 s98, s48, s26
	s_addc_u32 s99, s49, s27
	s_add_i32 m0, s36, 0x2000
	s_mov_b64 s[26:27], 0x5a90080
	global_load_lds_dwordx4 v244, s[98:99]
	s_add_u32 s98, s48, s26
	s_addc_u32 s99, s49, s27
	s_add_i32 m0, s36, 0x4000
	s_mov_b64 s[26:27], 0x5ae8080
	global_load_lds_dwordx4 v244, s[98:99]
	s_add_u32 s48, s48, s26
	s_addc_u32 s49, s49, s27
	s_add_i32 m0, s36, 0x6000
	s_mov_b64 s[26:27], 0x58080
	global_load_lds_dwordx4 v244, s[48:49]
	s_add_u32 s48, s50, s6
	s_addc_u32 s49, s51, s7
	s_add_u32 s98, s48, s10
	s_addc_u32 s99, s49, s11
	s_add_i32 m0, s36, 0x8000
	s_nop 0
	global_load_lds_dwordx4 v245, s[98:99]
	s_add_u32 s98, s48, s26
	s_addc_u32 s99, s49, s27
	s_add_i32 m0, s36, 0xa000
	s_mov_b64 s[26:27], 0xb0080
	global_load_lds_dwordx4 v245, s[98:99]
	s_add_u32 s98, s48, s26
	s_addc_u32 s99, s49, s27
	s_add_i32 m0, s36, 0xc000
	s_mov_b64 s[26:27], 0x108080
	global_load_lds_dwordx4 v245, s[98:99]
	s_add_u32 s48, s48, s26
	s_addc_u32 s49, s49, s27
	s_add_i32 m0, s36, 0xe000
	s_nop 0
	global_load_lds_dwordx4 v245, s[48:49]
	ds_read_b128 v[136:139], v144 offset:8192
	ds_read_b128 v[140:143], v144 offset:10240
	ds_read_b128 v[146:149], v144 offset:12288
	ds_read_b128 v[154:157], v144 offset:14336
	s_waitcnt lgkmcnt(0)
	v_mfma_f32_16x16x32_bf16 v[124:127], v[158:161], v[206:209], v[124:127]
	v_mfma_f32_16x16x32_bf16 v[120:123], v[162:165], v[206:209], v[120:123]
	v_mfma_f32_16x16x32_bf16 v[116:119], v[166:169], v[206:209], v[116:119]
	v_mfma_f32_16x16x32_bf16 v[112:115], v[170:173], v[206:209], v[112:115]
	v_mfma_f32_16x16x32_bf16 v[108:111], v[158:161], v[216:219], v[108:111]
	v_mfma_f32_16x16x32_bf16 v[104:107], v[162:165], v[216:219], v[104:107]
	v_mfma_f32_16x16x32_bf16 v[100:103], v[166:169], v[216:219], v[100:103]
	v_mfma_f32_16x16x32_bf16 v[96:99], v[170:173], v[216:219], v[96:99]
	v_mfma_f32_16x16x32_bf16 v[92:95], v[158:161], v[220:223], v[92:95]
	v_mfma_f32_16x16x32_bf16 v[84:87], v[162:165], v[220:223], v[84:87]
	v_mfma_f32_16x16x32_bf16 v[80:83], v[166:169], v[220:223], v[80:83]
	v_mfma_f32_16x16x32_bf16 v[76:79], v[170:173], v[220:223], v[76:79]
	v_mfma_f32_16x16x32_bf16 v[72:75], v[158:161], v[224:227], v[72:75]
	v_mfma_f32_16x16x32_bf16 v[68:71], v[162:165], v[224:227], v[68:71]
	v_mfma_f32_16x16x32_bf16 v[64:67], v[166:169], v[224:227], v[64:67]
	v_mfma_f32_16x16x32_bf16 v[60:63], v[170:173], v[224:227], v[60:63]
	v_mfma_f32_16x16x32_bf16 v[56:59], v[158:161], v[136:139], v[56:59]
	s_add_u32 s6, s6, 0x80
	s_addc_u32 s7, s7, 0
	v_mfma_f32_16x16x32_bf16 v[52:55], v[162:165], v[136:139], v[52:55]
	s_cmpk_eq_i32 s6, 0x1580
	s_mov_b32 s8, s9
	s_waitcnt vmcnt(0)
	v_mfma_f32_16x16x32_bf16 v[48:51], v[166:169], v[136:139], v[48:51]
	s_barrier
	v_mfma_f32_16x16x32_bf16 v[44:47], v[170:173], v[136:139], v[44:47]
	v_mfma_f32_16x16x32_bf16 v[40:43], v[158:161], v[140:143], v[40:43]
	v_mfma_f32_16x16x32_bf16 v[36:39], v[162:165], v[140:143], v[36:39]
	v_mfma_f32_16x16x32_bf16 v[32:35], v[166:169], v[140:143], v[32:35]
	v_mfma_f32_16x16x32_bf16 v[28:31], v[170:173], v[140:143], v[28:31]
	v_mfma_f32_16x16x32_bf16 v[24:27], v[158:161], v[146:149], v[24:27]
	v_mfma_f32_16x16x32_bf16 v[20:23], v[162:165], v[146:149], v[20:23]
	v_mfma_f32_16x16x32_bf16 v[16:19], v[166:169], v[146:149], v[16:19]
	v_mfma_f32_16x16x32_bf16 v[12:15], v[170:173], v[146:149], v[12:15]
	v_mfma_f32_16x16x32_bf16 v[8:11], v[158:161], v[154:157], v[8:11]
	v_mfma_f32_16x16x32_bf16 v[4:7], v[162:165], v[154:157], v[4:7]
	v_mfma_f32_16x16x32_bf16 v[0:3], v[166:169], v[154:157], v[0:3]
	v_mfma_f32_16x16x32_bf16 v[88:91], v[170:173], v[154:157], v[88:91]
	s_cbranch_scc1 .Lkx_500
.Lkb_500_l:
	s_add_i32 s9, s8, 0x10000
	s_and_b32 s26, s9, 0x10000
	s_add_i32 s36, s3, s26
	s_and_b32 s8, s8, 0x10000
	v_or_b32_e32 v144, s8, v135
	v_add_u32_e32 v151, v144, v134
	v_add_u32_e32 v144, v144, v132
	ds_read_b128 v[136:139], v151 offset:32768
	ds_read_b128 v[140:143], v151 offset:34816
	ds_read_b128 v[146:149], v151 offset:36864
	ds_read_b128 v[154:157], v151 offset:38912
	ds_read_b128 v[158:161], v144
	ds_read_b128 v[162:165], v144 offset:2048
	ds_read_b128 v[166:169], v144 offset:4096
	ds_read_b128 v[170:173], v144 offset:6144
	ds_read_b128 v[174:177], v144 offset:8192
	ds_read_b128 v[178:181], v144 offset:10240
	ds_read_b128 v[182:185], v144 offset:12288
	ds_read_b128 v[186:189], v144 offset:14336
	s_waitcnt lgkmcnt(0)
	v_mfma_f32_16x16x32_bf16 v[124:127], v[136:139], v[158:161], v[124:127]
	v_mfma_f32_16x16x32_bf16 v[120:123], v[140:143], v[158:161], v[120:123]
	v_mfma_f32_16x16x32_bf16 v[116:119], v[146:149], v[158:161], v[116:119]
	v_mfma_f32_16x16x32_bf16 v[112:115], v[154:157], v[158:161], v[112:115]
	v_mfma_f32_16x16x32_bf16 v[108:111], v[136:139], v[162:165], v[108:111]
	v_mfma_f32_16x16x32_bf16 v[104:107], v[140:143], v[162:165], v[104:107]
	v_mfma_f32_16x16x32_bf16 v[100:103], v[146:149], v[162:165], v[100:103]
	v_mfma_f32_16x16x32_bf16 v[96:99], v[154:157], v[162:165], v[96:99]
	v_mfma_f32_16x16x32_bf16 v[92:95], v[136:139], v[166:169], v[92:95]
	v_mfma_f32_16x16x32_bf16 v[84:87], v[140:143], v[166:169], v[84:87]
	v_mfma_f32_16x16x32_bf16 v[80:83], v[146:149], v[166:169], v[80:83]
	v_mfma_f32_16x16x32_bf16 v[76:79], v[154:157], v[166:169], v[76:79]
	v_mfma_f32_16x16x32_bf16 v[72:75], v[136:139], v[170:173], v[72:75]
	v_mfma_f32_16x16x32_bf16 v[68:71], v[140:143], v[170:173], v[68:71]
	v_mfma_f32_16x16x32_bf16 v[64:67], v[146:149], v[170:173], v[64:67]
	v_mfma_f32_16x16x32_bf16 v[60:63], v[154:157], v[170:173], v[60:63]
	v_or_b32_e32 v144, s8, v133
	v_add_u32_e32 v151, v144, v134
	v_add_u32_e32 v144, v144, v132
	ds_read_b128 v[158:161], v151 offset:32768
	ds_read_b128 v[162:165], v151 offset:34816
	ds_read_b128 v[166:169], v151 offset:36864
	ds_read_b128 v[170:173], v151 offset:38912
	ds_read_b128 v[206:209], v144
	ds_read_b128 v[216:219], v144 offset:2048
	ds_read_b128 v[220:223], v144 offset:4096
	ds_read_b128 v[224:227], v144 offset:6144
	v_mfma_f32_16x16x32_bf16 v[56:59], v[136:139], v[174:177], v[56:59]
	v_mfma_f32_16x16x32_bf16 v[52:55], v[140:143], v[174:177], v[52:55]
	v_mfma_f32_16x16x32_bf16 v[48:51], v[146:149], v[174:177], v[48:51]
	v_mfma_f32_16x16x32_bf16 v[44:47], v[154:157], v[174:177], v[44:47]
	v_mfma_f32_16x16x32_bf16 v[40:43], v[136:139], v[178:181], v[40:43]
	v_mfma_f32_16x16x32_bf16 v[36:39], v[140:143], v[178:181], v[36:39]
	v_mfma_f32_16x16x32_bf16 v[32:35], v[146:149], v[178:181], v[32:35]
	v_mfma_f32_16x16x32_bf16 v[28:31], v[154:157], v[178:181], v[28:31]
	v_mfma_f32_16x16x32_bf16 v[24:27], v[136:139], v[182:185], v[24:27]
	v_mfma_f32_16x16x32_bf16 v[20:23], v[140:143], v[182:185], v[20:23]
	v_mfma_f32_16x16x32_bf16 v[16:19], v[146:149], v[182:185], v[16:19]
	v_mfma_f32_16x16x32_bf16 v[12:15], v[154:157], v[182:185], v[12:15]
	v_mfma_f32_16x16x32_bf16 v[8:11], v[136:139], v[186:189], v[8:11]
	v_mfma_f32_16x16x32_bf16 v[4:7], v[140:143], v[186:189], v[4:7]
	v_mfma_f32_16x16x32_bf16 v[0:3], v[146:149], v[186:189], v[0:3]
	v_mfma_f32_16x16x32_bf16 v[88:91], v[154:157], v[186:189], v[88:91]
	s_add_u32 s48, s50, s6
	s_addc_u32 s49, s51, s7
	s_mov_b64 s[26:27], 0x59e0080
	s_add_u32 s98, s48, s26
	s_addc_u32 s99, s49, s27
	s_mov_b32 m0, s36
	s_mov_b64 s[26:27], 0x5a38080
	global_load_lds_dwordx4 v244, s[98:99]
	s_add_u32 s98, s48, s26
	s_addc_u32 s99, s49, s27
	s_add_i32 m0, s36, 0x2000
	s_mov_b64 s[26:27], 0x5a90080
	global_load_lds_dwordx4 v244, s[98:99]
	s_add_u32 s98, s48, s26
	s_addc_u32 s99, s49, s27
	s_add_i32 m0, s36, 0x4000
	s_mov_b64 s[26:27], 0x5ae8080
	global_load_lds_dwordx4 v244, s[98:99]
	s_add_u32 s48, s48, s26
	s_addc_u32 s49, s49, s27
	s_add_i32 m0, s36, 0x6000
	s_mov_b64 s[26:27], 0x58080
	global_load_lds_dwordx4 v244, s[48:49]
	s_add_u32 s48, s50, s6
	s_addc_u32 s49, s51, s7
	s_add_u32 s98, s48, s10
	s_addc_u32 s99, s49, s11
	s_add_i32 m0, s36, 0x8000
	s_nop 0
	global_load_lds_dwordx4 v245, s[98:99]
	s_add_u32 s98, s48, s26
	s_addc_u32 s99, s49, s27
	s_add_i32 m0, s36, 0xa000
	s_mov_b64 s[26:27], 0xb0080
	global_load_lds_dwordx4 v245, s[98:99]
	s_add_u32 s98, s48, s26
	s_addc_u32 s99, s49, s27
	s_add_i32 m0, s36, 0xc000
	s_mov_b64 s[26:27], 0x108080
	global_load_lds_dwordx4 v245, s[98:99]
	s_add_u32 s48, s48, s26
	s_addc_u32 s49, s49, s27
	s_add_i32 m0, s36, 0xe000
	s_nop 0
	global_load_lds_dwordx4 v245, s[48:49]
	ds_read_b128 v[136:139], v144 offset:8192
	ds_read_b128 v[140:143], v144 offset:10240
	ds_read_b128 v[146:149], v144 offset:12288
	ds_read_b128 v[154:157], v144 offset:14336
	s_waitcnt lgkmcnt(0)
	v_mfma_f32_16x16x32_bf16 v[124:127], v[158:161], v[206:209], v[124:127]
	v_mfma_f32_16x16x32_bf16 v[120:123], v[162:165], v[206:209], v[120:123]
	v_mfma_f32_16x16x32_bf16 v[116:119], v[166:169], v[206:209], v[116:119]
	v_mfma_f32_16x16x32_bf16 v[112:115], v[170:173], v[206:209], v[112:115]
	v_mfma_f32_16x16x32_bf16 v[108:111], v[158:161], v[216:219], v[108:111]
	v_mfma_f32_16x16x32_bf16 v[104:107], v[162:165], v[216:219], v[104:107]
	v_mfma_f32_16x16x32_bf16 v[100:103], v[166:169], v[216:219], v[100:103]
	v_mfma_f32_16x16x32_bf16 v[96:99], v[170:173], v[216:219], v[96:99]
	v_mfma_f32_16x16x32_bf16 v[92:95], v[158:161], v[220:223], v[92:95]
	v_mfma_f32_16x16x32_bf16 v[84:87], v[162:165], v[220:223], v[84:87]
	v_mfma_f32_16x16x32_bf16 v[80:83], v[166:169], v[220:223], v[80:83]
	v_mfma_f32_16x16x32_bf16 v[76:79], v[170:173], v[220:223], v[76:79]
	v_mfma_f32_16x16x32_bf16 v[72:75], v[158:161], v[224:227], v[72:75]
	v_mfma_f32_16x16x32_bf16 v[68:71], v[162:165], v[224:227], v[68:71]
	v_mfma_f32_16x16x32_bf16 v[64:67], v[166:169], v[224:227], v[64:67]
	v_mfma_f32_16x16x32_bf16 v[60:63], v[170:173], v[224:227], v[60:63]
	v_mfma_f32_16x16x32_bf16 v[56:59], v[158:161], v[136:139], v[56:59]
	s_add_u32 s6, s6, 0x80
	s_addc_u32 s7, s7, 0
	v_mfma_f32_16x16x32_bf16 v[52:55], v[162:165], v[136:139], v[52:55]
	s_cmpk_eq_i32 s6, 0x1580
	s_mov_b32 s8, s9
	s_waitcnt vmcnt(0)
	v_mfma_f32_16x16x32_bf16 v[48:51], v[166:169], v[136:139], v[48:51]
	s_barrier
	v_mfma_f32_16x16x32_bf16 v[44:47], v[170:173], v[136:139], v[44:47]
	v_mfma_f32_16x16x32_bf16 v[40:43], v[158:161], v[140:143], v[40:43]
	v_mfma_f32_16x16x32_bf16 v[36:39], v[162:165], v[140:143], v[36:39]
	v_mfma_f32_16x16x32_bf16 v[32:35], v[166:169], v[140:143], v[32:35]
	v_mfma_f32_16x16x32_bf16 v[28:31], v[170:173], v[140:143], v[28:31]
	v_mfma_f32_16x16x32_bf16 v[24:27], v[158:161], v[146:149], v[24:27]
	v_mfma_f32_16x16x32_bf16 v[20:23], v[162:165], v[146:149], v[20:23]
	v_mfma_f32_16x16x32_bf16 v[16:19], v[166:169], v[146:149], v[16:19]
	v_mfma_f32_16x16x32_bf16 v[12:15], v[170:173], v[146:149], v[12:15]
	v_mfma_f32_16x16x32_bf16 v[8:11], v[158:161], v[154:157], v[8:11]
	v_mfma_f32_16x16x32_bf16 v[4:7], v[162:165], v[154:157], v[4:7]
	v_mfma_f32_16x16x32_bf16 v[0:3], v[166:169], v[154:157], v[0:3]
	v_mfma_f32_16x16x32_bf16 v[88:91], v[170:173], v[154:157], v[88:91]
	s_cbranch_scc0 .Lkb_500_l

.LBB0_669:
	v_lshlrev_b64 v[132:133], 10, v[0:1]
	v_and_b32_e32 v0, 15, v2
	v_and_b32_e32 v1, 3, v3
	v_lshrrev_b32_e32 v3, 1, v2
	s_mov_b32 s2, 0x1ffff80
	v_and_or_b32 v0, v3, s2, v0
	v_lshlrev_b32_e32 v134, 7, v0
	v_bfe_u32 v0, v2, 1, 3
	v_bitop3_b32 v0, v1, v0, 4 bitop3:0x36
	v_lshlrev_b32_e32 v135, 4, v0
	v_lshlrev_b32_e32 v0, 7, v2
	s_waitcnt vmcnt(0)
	v_bitop3_b32 v3, v3, v1, 7 bitop3:0x6c
	v_and_b32_e32 v136, 0x6780, v0
	v_lshlrev_b32_e32 v137, 4, v3
	s_mov_b64 s[34:35], 0
	s_mov_b32 s2, 0
	s_waitcnt vmcnt(0) lgkmcnt(0)
	s_barrier
	v_readlane_b32 s50, v255, 24
	v_readlane_b32 s51, v255, 25
	s_nop 1
	v_subrev_u32_e32 v244, s50, v128
	v_subrev_u32_e32 v245, s50, v130
	s_bitcmp1_b32 s0, 12
	s_cbranch_scc1 .Lkb_670
	s_add_i32 s3, s2, 0x10000
	s_and_b32 s23, s3, 0x10000
	s_add_i32 s23, s0, s23
	s_add_u32 s48, s50, s34
	s_addc_u32 s49, s51, s35
	s_add_u32 s98, s48, s10
	s_addc_u32 s99, s49, s11
	s_mov_b32 m0, s23
	s_nop 0
	global_load_lds_dwordx4 v244, s[98:99]
	s_add_u32 s98, s48, s4
	s_addc_u32 s99, s49, s5
	s_add_i32 m0, s23, 0x2000
	s_nop 0
	global_load_lds_dwordx4 v244, s[98:99]
	s_add_u32 s98, s48, s92
	s_addc_u32 s99, s49, s93
	s_add_i32 m0, s23, 0x4000
	s_add_u32 s48, s48, s94
	s_addc_u32 s49, s49, s95
	global_load_lds_dwordx4 v244, s[98:99]
	s_add_i32 m0, s23, 0x6000
	s_nop 0
	global_load_lds_dwordx4 v244, s[48:49]
	s_add_u32 s48, s50, s34
	s_addc_u32 s49, s51, s35
	s_add_u32 s98, s48, s10
	s_addc_u32 s99, s49, s11
	s_add_i32 m0, s23, 0x8000
	s_nop 0
	global_load_lds_dwordx4 v245, s[98:99]
	s_add_u32 s98, s48, s4
	s_addc_u32 s99, s49, s5
	s_add_i32 m0, s23, 0xa000
	s_nop 0
	global_load_lds_dwordx4 v245, s[98:99]
	s_add_u32 s98, s48, s92
	s_addc_u32 s99, s49, s93
	s_add_i32 m0, s23, 0xc000
	s_add_u32 s48, s48, s94
	s_addc_u32 s49, s49, s95
	global_load_lds_dwordx4 v245, s[98:99]
	s_add_i32 m0, s23, 0xe000
	s_nop 0
	global_load_lds_dwordx4 v245, s[48:49]
	s_and_b32 s2, s2, 0x10000
	v_or_b32_e32 v142, s2, v137
	v_add_u32_e32 v143, v142, v136
	v_add_u32_e32 v142, v142, v134
	ds_read_b128 v[138:141], v143 offset:32768
	ds_read_b128 v[146:149], v143 offset:34816
	ds_read_b128 v[154:157], v143 offset:36864
	ds_read_b128 v[158:161], v143 offset:38912
	ds_read_b128 v[162:165], v142
	ds_read_b128 v[166:169], v142 offset:2048
	ds_read_b128 v[170:173], v142 offset:4096
	ds_read_b128 v[174:177], v142 offset:6144
	ds_read_b128 v[178:181], v142 offset:8192
	ds_read_b128 v[182:185], v142 offset:10240
	ds_read_b128 v[186:189], v142 offset:12288
	ds_read_b128 v[206:209], v142 offset:14336
	s_waitcnt lgkmcnt(0)
	v_mfma_f32_16x16x32_bf16 v[116:119], v[138:141], v[162:165], 0
	v_mfma_f32_16x16x32_bf16 v[108:111], v[146:149], v[162:165], 0
	v_mfma_f32_16x16x32_bf16 v[100:103], v[154:157], v[162:165], 0
	v_mfma_f32_16x16x32_bf16 v[88:91], v[158:161], v[162:165], 0
	v_mfma_f32_16x16x32_bf16 v[76:79], v[138:141], v[166:169], 0
	v_mfma_f32_16x16x32_bf16 v[68:71], v[146:149], v[166:169], 0
	v_mfma_f32_16x16x32_bf16 v[56:59], v[154:157], v[166:169], 0
	v_mfma_f32_16x16x32_bf16 v[44:47], v[158:161], v[166:169], 0
	v_mfma_f32_16x16x32_bf16 v[36:39], v[138:141], v[170:173], 0
	v_mfma_f32_16x16x32_bf16 v[32:35], v[146:149], v[170:173], 0
	v_mfma_f32_16x16x32_bf16 v[28:31], v[154:157], v[170:173], 0
	v_mfma_f32_16x16x32_bf16 v[24:27], v[158:161], v[170:173], 0
	v_mfma_f32_16x16x32_bf16 v[20:23], v[138:141], v[174:177], 0
	v_mfma_f32_16x16x32_bf16 v[16:19], v[146:149], v[174:177], 0
	v_mfma_f32_16x16x32_bf16 v[12:15], v[154:157], v[174:177], 0
	v_mfma_f32_16x16x32_bf16 v[8:11], v[158:161], v[174:177], 0
	v_or_b32_e32 v142, s2, v135
	v_add_u32_e32 v143, v142, v136
	v_add_u32_e32 v142, v142, v134
	ds_read_b128 v[162:165], v143 offset:32768
	ds_read_b128 v[166:169], v143 offset:34816
	ds_read_b128 v[170:173], v143 offset:36864
	ds_read_b128 v[174:177], v143 offset:38912
	ds_read_b128 v[216:219], v142
	ds_read_b128 v[220:223], v142 offset:2048
	ds_read_b128 v[224:227], v142 offset:4096
	ds_read_b128 v[228:231], v142 offset:6144
	v_mfma_f32_16x16x32_bf16 v[4:7], v[138:141], v[178:181], 0
	v_mfma_f32_16x16x32_bf16 v[0:3], v[146:149], v[178:181], 0
	v_mfma_f32_16x16x32_bf16 v[40:43], v[154:157], v[178:181], 0
	v_mfma_f32_16x16x32_bf16 v[48:51], v[158:161], v[178:181], 0
	v_mfma_f32_16x16x32_bf16 v[52:55], v[138:141], v[182:185], 0
	v_mfma_f32_16x16x32_bf16 v[60:63], v[146:149], v[182:185], 0
	v_mfma_f32_16x16x32_bf16 v[64:67], v[154:157], v[182:185], 0
	v_mfma_f32_16x16x32_bf16 v[72:75], v[158:161], v[182:185], 0
	v_mfma_f32_16x16x32_bf16 v[80:83], v[138:141], v[186:189], 0
	v_mfma_f32_16x16x32_bf16 v[84:87], v[146:149], v[186:189], 0
	v_mfma_f32_16x16x32_bf16 v[92:95], v[154:157], v[186:189], 0
	v_mfma_f32_16x16x32_bf16 v[96:99], v[158:161], v[186:189], 0
	v_mfma_f32_16x16x32_bf16 v[104:107], v[138:141], v[206:209], 0
	v_mfma_f32_16x16x32_bf16 v[112:115], v[146:149], v[206:209], 0
	v_mfma_f32_16x16x32_bf16 v[120:123], v[154:157], v[206:209], 0
	v_mfma_f32_16x16x32_bf16 v[124:127], v[158:161], v[206:209], 0
	ds_read_b128 v[138:141], v142 offset:8192
	ds_read_b128 v[146:149], v142 offset:10240
	ds_read_b128 v[154:157], v142 offset:12288
	ds_read_b128 v[158:161], v142 offset:14336
	s_waitcnt lgkmcnt(0)
	v_mfma_f32_16x16x32_bf16 v[116:119], v[162:165], v[216:219], v[116:119]
	v_mfma_f32_16x16x32_bf16 v[108:111], v[166:169], v[216:219], v[108:111]
	v_mfma_f32_16x16x32_bf16 v[100:103], v[170:173], v[216:219], v[100:103]
	v_mfma_f32_16x16x32_bf16 v[88:91], v[174:177], v[216:219], v[88:91]
	v_mfma_f32_16x16x32_bf16 v[76:79], v[162:165], v[220:223], v[76:79]
	v_mfma_f32_16x16x32_bf16 v[68:71], v[166:169], v[220:223], v[68:71]
	v_mfma_f32_16x16x32_bf16 v[56:59], v[170:173], v[220:223], v[56:59]
	v_mfma_f32_16x16x32_bf16 v[44:47], v[174:177], v[220:223], v[44:47]
	v_mfma_f32_16x16x32_bf16 v[36:39], v[162:165], v[224:227], v[36:39]
	v_mfma_f32_16x16x32_bf16 v[32:35], v[166:169], v[224:227], v[32:35]
	v_mfma_f32_16x16x32_bf16 v[28:31], v[170:173], v[224:227], v[28:31]
	v_mfma_f32_16x16x32_bf16 v[24:27], v[174:177], v[224:227], v[24:27]
	v_mfma_f32_16x16x32_bf16 v[20:23], v[162:165], v[228:231], v[20:23]
	v_mfma_f32_16x16x32_bf16 v[16:19], v[166:169], v[228:231], v[16:19]
	v_mfma_f32_16x16x32_bf16 v[12:15], v[170:173], v[228:231], v[12:15]
	v_mfma_f32_16x16x32_bf16 v[8:11], v[174:177], v[228:231], v[8:11]
	v_mfma_f32_16x16x32_bf16 v[4:7], v[162:165], v[138:141], v[4:7]
	s_add_u32 s34, s34, 0x80
	s_addc_u32 s35, s35, 0
	v_mfma_f32_16x16x32_bf16 v[0:3], v[166:169], v[138:141], v[0:3]
	s_cmpk_eq_i32 s34, 0x780
	s_mov_b32 s2, s3
	s_waitcnt vmcnt(0)
	v_mfma_f32_16x16x32_bf16 v[40:43], v[170:173], v[138:141], v[40:43]
	s_barrier
	v_mfma_f32_16x16x32_bf16 v[48:51], v[174:177], v[138:141], v[48:51]
	v_mfma_f32_16x16x32_bf16 v[52:55], v[162:165], v[146:149], v[52:55]
	v_mfma_f32_16x16x32_bf16 v[60:63], v[166:169], v[146:149], v[60:63]
	v_mfma_f32_16x16x32_bf16 v[64:67], v[170:173], v[146:149], v[64:67]
	v_mfma_f32_16x16x32_bf16 v[72:75], v[174:177], v[146:149], v[72:75]
	v_mfma_f32_16x16x32_bf16 v[80:83], v[162:165], v[154:157], v[80:83]
	v_mfma_f32_16x16x32_bf16 v[84:87], v[166:169], v[154:157], v[84:87]
	v_mfma_f32_16x16x32_bf16 v[92:95], v[170:173], v[154:157], v[92:95]
	v_mfma_f32_16x16x32_bf16 v[96:99], v[174:177], v[154:157], v[96:99]
	v_mfma_f32_16x16x32_bf16 v[104:107], v[162:165], v[158:161], v[104:107]
	v_mfma_f32_16x16x32_bf16 v[112:115], v[166:169], v[158:161], v[112:115]
	v_mfma_f32_16x16x32_bf16 v[120:123], v[170:173], v[158:161], v[120:123]
	v_mfma_f32_16x16x32_bf16 v[124:127], v[174:177], v[158:161], v[124:127]
	s_cbranch_scc1 .Lkx_670
.LBB0_670:
	s_add_i32 s3, s2, 0x10000
	s_and_b32 s23, s3, 0x10000
	s_add_i32 s23, s0, s23
	s_add_u32 s48, s50, s34
	s_addc_u32 s49, s51, s35
	s_add_u32 s98, s48, s10
	s_addc_u32 s99, s49, s11
	s_mov_b32 m0, s23
	s_nop 0
	global_load_lds_dwordx4 v244, s[98:99]
	s_add_u32 s98, s48, s4
	s_addc_u32 s99, s49, s5
	s_add_i32 m0, s23, 0x2000
	s_nop 0
	global_load_lds_dwordx4 v244, s[98:99]
	s_add_u32 s98, s48, s92
	s_addc_u32 s99, s49, s93
	s_add_i32 m0, s23, 0x4000
	s_add_u32 s48, s48, s94
	s_addc_u32 s49, s49, s95
	global_load_lds_dwordx4 v244, s[98:99]
	s_add_i32 m0, s23, 0x6000
	s_nop 0
	global_load_lds_dwordx4 v244, s[48:49]
	s_add_u32 s48, s50, s34
	s_addc_u32 s49, s51, s35
	s_add_u32 s98, s48, s10
	s_addc_u32 s99, s49, s11
	s_add_i32 m0, s23, 0x8000
	s_nop 0
	global_load_lds_dwordx4 v245, s[98:99]
	s_add_u32 s98, s48, s4
	s_addc_u32 s99, s49, s5
	s_add_i32 m0, s23, 0xa000
	s_nop 0
	global_load_lds_dwordx4 v245, s[98:99]
	s_add_u32 s98, s48, s92
	s_addc_u32 s99, s49, s93
	s_add_i32 m0, s23, 0xc000
	s_add_u32 s48, s48, s94
	s_addc_u32 s49, s49, s95
	global_load_lds_dwordx4 v245, s[98:99]
	s_add_i32 m0, s23, 0xe000
	s_nop 0
	global_load_lds_dwordx4 v245, s[48:49]
	s_and_b32 s2, s2, 0x10000
	v_or_b32_e32 v142, s2, v137
	v_add_u32_e32 v143, v142, v136
	v_add_u32_e32 v142, v142, v134
	ds_read_b128 v[138:141], v143 offset:32768
	ds_read_b128 v[146:149], v143 offset:34816
	ds_read_b128 v[154:157], v143 offset:36864
	ds_read_b128 v[158:161], v143 offset:38912
	ds_read_b128 v[162:165], v142
	ds_read_b128 v[166:169], v142 offset:2048
	ds_read_b128 v[170:173], v142 offset:4096
	ds_read_b128 v[174:177], v142 offset:6144
	ds_read_b128 v[178:181], v142 offset:8192
	ds_read_b128 v[182:185], v142 offset:10240
	ds_read_b128 v[186:189], v142 offset:12288
	ds_read_b128 v[206:209], v142 offset:14336
	s_waitcnt lgkmcnt(0)
	v_mfma_f32_16x16x32_bf16 v[116:119], v[138:141], v[162:165], v[116:119]
	v_mfma_f32_16x16x32_bf16 v[108:111], v[146:149], v[162:165], v[108:111]
	v_mfma_f32_16x16x32_bf16 v[100:103], v[154:157], v[162:165], v[100:103]
	v_mfma_f32_16x16x32_bf16 v[88:91], v[158:161], v[162:165], v[88:91]
	v_mfma_f32_16x16x32_bf16 v[76:79], v[138:141], v[166:169], v[76:79]
	v_mfma_f32_16x16x32_bf16 v[68:71], v[146:149], v[166:169], v[68:71]
	v_mfma_f32_16x16x32_bf16 v[56:59], v[154:157], v[166:169], v[56:59]
	v_mfma_f32_16x16x32_bf16 v[44:47], v[158:161], v[166:169], v[44:47]
	v_mfma_f32_16x16x32_bf16 v[36:39], v[138:141], v[170:173], v[36:39]
	v_mfma_f32_16x16x32_bf16 v[32:35], v[146:149], v[170:173], v[32:35]
	v_mfma_f32_16x16x32_bf16 v[28:31], v[154:157], v[170:173], v[28:31]
	v_mfma_f32_16x16x32_bf16 v[24:27], v[158:161], v[170:173], v[24:27]
	v_mfma_f32_16x16x32_bf16 v[20:23], v[138:141], v[174:177], v[20:23]
	v_mfma_f32_16x16x32_bf16 v[16:19], v[146:149], v[174:177], v[16:19]
	v_mfma_f32_16x16x32_bf16 v[12:15], v[154:157], v[174:177], v[12:15]
	v_mfma_f32_16x16x32_bf16 v[8:11], v[158:161], v[174:177], v[8:11]
	v_or_b32_e32 v142, s2, v135
	v_add_u32_e32 v143, v142, v136
	v_add_u32_e32 v142, v142, v134
	ds_read_b128 v[162:165], v143 offset:32768
	ds_read_b128 v[166:169], v143 offset:34816
	ds_read_b128 v[170:173], v143 offset:36864
	ds_read_b128 v[174:177], v143 offset:38912
	ds_read_b128 v[216:219], v142
	ds_read_b128 v[220:223], v142 offset:2048
	ds_read_b128 v[224:227], v142 offset:4096
	ds_read_b128 v[228:231], v142 offset:6144
	v_mfma_f32_16x16x32_bf16 v[4:7], v[138:141], v[178:181], v[4:7]
	v_mfma_f32_16x16x32_bf16 v[0:3], v[146:149], v[178:181], v[0:3]
	v_mfma_f32_16x16x32_bf16 v[40:43], v[154:157], v[178:181], v[40:43]
	v_mfma_f32_16x16x32_bf16 v[48:51], v[158:161], v[178:181], v[48:51]
	v_mfma_f32_16x16x32_bf16 v[52:55], v[138:141], v[182:185], v[52:55]
	v_mfma_f32_16x16x32_bf16 v[60:63], v[146:149], v[182:185], v[60:63]
	v_mfma_f32_16x16x32_bf16 v[64:67], v[154:157], v[182:185], v[64:67]
	v_mfma_f32_16x16x32_bf16 v[72:75], v[158:161], v[182:185], v[72:75]
	v_mfma_f32_16x16x32_bf16 v[80:83], v[138:141], v[186:189], v[80:83]
	v_mfma_f32_16x16x32_bf16 v[84:87], v[146:149], v[186:189], v[84:87]
	v_mfma_f32_16x16x32_bf16 v[92:95], v[154:157], v[186:189], v[92:95]
	v_mfma_f32_16x16x32_bf16 v[96:99], v[158:161], v[186:189], v[96:99]
	v_mfma_f32_16x16x32_bf16 v[104:107], v[138:141], v[206:209], v[104:107]
	v_mfma_f32_16x16x32_bf16 v[112:115], v[146:149], v[206:209], v[112:115]
	v_mfma_f32_16x16x32_bf16 v[120:123], v[154:157], v[206:209], v[120:123]
	v_mfma_f32_16x16x32_bf16 v[124:127], v[158:161], v[206:209], v[124:127]
	ds_read_b128 v[138:141], v142 offset:8192
	ds_read_b128 v[146:149], v142 offset:10240
	ds_read_b128 v[154:157], v142 offset:12288
	ds_read_b128 v[158:161], v142 offset:14336
	s_waitcnt lgkmcnt(0)
	v_mfma_f32_16x16x32_bf16 v[116:119], v[162:165], v[216:219], v[116:119]
	v_mfma_f32_16x16x32_bf16 v[108:111], v[166:169], v[216:219], v[108:111]
	v_mfma_f32_16x16x32_bf16 v[100:103], v[170:173], v[216:219], v[100:103]
	v_mfma_f32_16x16x32_bf16 v[88:91], v[174:177], v[216:219], v[88:91]
	v_mfma_f32_16x16x32_bf16 v[76:79], v[162:165], v[220:223], v[76:79]
	v_mfma_f32_16x16x32_bf16 v[68:71], v[166:169], v[220:223], v[68:71]
	v_mfma_f32_16x16x32_bf16 v[56:59], v[170:173], v[220:223], v[56:59]
	v_mfma_f32_16x16x32_bf16 v[44:47], v[174:177], v[220:223], v[44:47]
	v_mfma_f32_16x16x32_bf16 v[36:39], v[162:165], v[224:227], v[36:39]
	v_mfma_f32_16x16x32_bf16 v[32:35], v[166:169], v[224:227], v[32:35]
	v_mfma_f32_16x16x32_bf16 v[28:31], v[170:173], v[224:227], v[28:31]
	v_mfma_f32_16x16x32_bf16 v[24:27], v[174:177], v[224:227], v[24:27]
	v_mfma_f32_16x16x32_bf16 v[20:23], v[162:165], v[228:231], v[20:23]
	v_mfma_f32_16x16x32_bf16 v[16:19], v[166:169], v[228:231], v[16:19]
	v_mfma_f32_16x16x32_bf16 v[12:15], v[170:173], v[228:231], v[12:15]
	v_mfma_f32_16x16x32_bf16 v[8:11], v[174:177], v[228:231], v[8:11]
	v_mfma_f32_16x16x32_bf16 v[4:7], v[162:165], v[138:141], v[4:7]
	s_add_u32 s34, s34, 0x80
	s_addc_u32 s35, s35, 0
	v_mfma_f32_16x16x32_bf16 v[0:3], v[166:169], v[138:141], v[0:3]
	s_cmpk_eq_i32 s34, 0x780
	s_mov_b32 s2, s3
	s_waitcnt vmcnt(0)
	v_mfma_f32_16x16x32_bf16 v[40:43], v[170:173], v[138:141], v[40:43]
	s_barrier
	v_mfma_f32_16x16x32_bf16 v[48:51], v[174:177], v[138:141], v[48:51]
	v_mfma_f32_16x16x32_bf16 v[52:55], v[162:165], v[146:149], v[52:55]
	v_mfma_f32_16x16x32_bf16 v[60:63], v[166:169], v[146:149], v[60:63]
	v_mfma_f32_16x16x32_bf16 v[64:67], v[170:173], v[146:149], v[64:67]
	v_mfma_f32_16x16x32_bf16 v[72:75], v[174:177], v[146:149], v[72:75]
	v_mfma_f32_16x16x32_bf16 v[80:83], v[162:165], v[154:157], v[80:83]
	v_mfma_f32_16x16x32_bf16 v[84:87], v[166:169], v[154:157], v[84:87]
	v_mfma_f32_16x16x32_bf16 v[92:95], v[170:173], v[154:157], v[92:95]
	v_mfma_f32_16x16x32_bf16 v[96:99], v[174:177], v[154:157], v[96:99]
	v_mfma_f32_16x16x32_bf16 v[104:107], v[162:165], v[158:161], v[104:107]
	v_mfma_f32_16x16x32_bf16 v[112:115], v[166:169], v[158:161], v[112:115]
	v_mfma_f32_16x16x32_bf16 v[120:123], v[170:173], v[158:161], v[120:123]
	v_mfma_f32_16x16x32_bf16 v[124:127], v[174:177], v[158:161], v[124:127]
	s_cbranch_scc0 .LBB0_670
	s_branch .Lkx_670
.Lkb_670:
	s_add_i32 s3, s2, 0x10000
	s_and_b32 s23, s3, 0x10000
	s_add_i32 s23, s0, s23
	s_and_b32 s2, s2, 0x10000
	v_or_b32_e32 v142, s2, v137
	v_add_u32_e32 v143, v142, v136
	v_add_u32_e32 v142, v142, v134
	ds_read_b128 v[138:141], v143 offset:32768
	ds_read_b128 v[146:149], v143 offset:34816
	ds_read_b128 v[154:157], v143 offset:36864
	ds_read_b128 v[158:161], v143 offset:38912
	ds_read_b128 v[162:165], v142
	ds_read_b128 v[166:169], v142 offset:2048
	ds_read_b128 v[170:173], v142 offset:4096
	ds_read_b128 v[174:177], v142 offset:6144
	ds_read_b128 v[178:181], v142 offset:8192
	ds_read_b128 v[182:185], v142 offset:10240
	ds_read_b128 v[186:189], v142 offset:12288
	ds_read_b128 v[206:209], v142 offset:14336
	s_waitcnt lgkmcnt(0)
	v_mfma_f32_16x16x32_bf16 v[116:119], v[138:141], v[162:165], 0
	v_mfma_f32_16x16x32_bf16 v[108:111], v[146:149], v[162:165], 0
	v_mfma_f32_16x16x32_bf16 v[100:103], v[154:157], v[162:165], 0
	v_mfma_f32_16x16x32_bf16 v[88:91], v[158:161], v[162:165], 0
	v_mfma_f32_16x16x32_bf16 v[76:79], v[138:141], v[166:169], 0
	v_mfma_f32_16x16x32_bf16 v[68:71], v[146:149], v[166:169], 0
	v_mfma_f32_16x16x32_bf16 v[56:59], v[154:157], v[166:169], 0
	v_mfma_f32_16x16x32_bf16 v[44:47], v[158:161], v[166:169], 0
	v_mfma_f32_16x16x32_bf16 v[36:39], v[138:141], v[170:173], 0
	v_mfma_f32_16x16x32_bf16 v[32:35], v[146:149], v[170:173], 0
	v_mfma_f32_16x16x32_bf16 v[28:31], v[154:157], v[170:173], 0
	v_mfma_f32_16x16x32_bf16 v[24:27], v[158:161], v[170:173], 0
	v_mfma_f32_16x16x32_bf16 v[20:23], v[138:141], v[174:177], 0
	v_mfma_f32_16x16x32_bf16 v[16:19], v[146:149], v[174:177], 0
	v_mfma_f32_16x16x32_bf16 v[12:15], v[154:157], v[174:177], 0
	v_mfma_f32_16x16x32_bf16 v[8:11], v[158:161], v[174:177], 0
	v_or_b32_e32 v142, s2, v135
	v_add_u32_e32 v143, v142, v136
	v_add_u32_e32 v142, v142, v134
	ds_read_b128 v[162:165], v143 offset:32768
	ds_read_b128 v[166:169], v143 offset:34816
	ds_read_b128 v[170:173], v143 offset:36864
	ds_read_b128 v[174:177], v143 offset:38912
	ds_read_b128 v[216:219], v142
	ds_read_b128 v[220:223], v142 offset:2048
	ds_read_b128 v[224:227], v142 offset:4096
	ds_read_b128 v[228:231], v142 offset:6144
	v_mfma_f32_16x16x32_bf16 v[4:7], v[138:141], v[178:181], 0
	v_mfma_f32_16x16x32_bf16 v[0:3], v[146:149], v[178:181], 0
	v_mfma_f32_16x16x32_bf16 v[40:43], v[154:157], v[178:181], 0
	v_mfma_f32_16x16x32_bf16 v[48:51], v[158:161], v[178:181], 0
	v_mfma_f32_16x16x32_bf16 v[52:55], v[138:141], v[182:185], 0
	v_mfma_f32_16x16x32_bf16 v[60:63], v[146:149], v[182:185], 0
	v_mfma_f32_16x16x32_bf16 v[64:67], v[154:157], v[182:185], 0
	v_mfma_f32_16x16x32_bf16 v[72:75], v[158:161], v[182:185], 0
	v_mfma_f32_16x16x32_bf16 v[80:83], v[138:141], v[186:189], 0
	v_mfma_f32_16x16x32_bf16 v[84:87], v[146:149], v[186:189], 0
	v_mfma_f32_16x16x32_bf16 v[92:95], v[154:157], v[186:189], 0
	v_mfma_f32_16x16x32_bf16 v[96:99], v[158:161], v[186:189], 0
	v_mfma_f32_16x16x32_bf16 v[104:107], v[138:141], v[206:209], 0
	v_mfma_f32_16x16x32_bf16 v[112:115], v[146:149], v[206:209], 0
	v_mfma_f32_16x16x32_bf16 v[120:123], v[154:157], v[206:209], 0
	v_mfma_f32_16x16x32_bf16 v[124:127], v[158:161], v[206:209], 0
	s_add_u32 s48, s50, s34
	s_addc_u32 s49, s51, s35
	s_add_u32 s98, s48, s10
	s_addc_u32 s99, s49, s11
	s_mov_b32 m0, s23
	s_nop 0
	global_load_lds_dwordx4 v244, s[98:99]
	s_add_u32 s98, s48, s4
	s_addc_u32 s99, s49, s5
	s_add_i32 m0, s23, 0x2000
	s_nop 0
	global_load_lds_dwordx4 v244, s[98:99]
	s_add_u32 s98, s48, s92
	s_addc_u32 s99, s49, s93
	s_add_i32 m0, s23, 0x4000
	s_add_u32 s48, s48, s94
	s_addc_u32 s49, s49, s95
	global_load_lds_dwordx4 v244, s[98:99]
	s_add_i32 m0, s23, 0x6000
	s_nop 0
	global_load_lds_dwordx4 v244, s[48:49]
	s_add_u32 s48, s50, s34
	s_addc_u32 s49, s51, s35
	s_add_u32 s98, s48, s10
	s_addc_u32 s99, s49, s11
	s_add_i32 m0, s23, 0x8000
	s_nop 0
	global_load_lds_dwordx4 v245, s[98:99]
	s_add_u32 s98, s48, s4
	s_addc_u32 s99, s49, s5
	s_add_i32 m0, s23, 0xa000
	s_nop 0
	global_load_lds_dwordx4 v245, s[98:99]
	s_add_u32 s98, s48, s92
	s_addc_u32 s99, s49, s93
	s_add_i32 m0, s23, 0xc000
	s_add_u32 s48, s48, s94
	s_addc_u32 s49, s49, s95
	global_load_lds_dwordx4 v245, s[98:99]
	s_add_i32 m0, s23, 0xe000
	s_nop 0
	global_load_lds_dwordx4 v245, s[48:49]
	ds_read_b128 v[138:141], v142 offset:8192
	ds_read_b128 v[146:149], v142 offset:10240
	ds_read_b128 v[154:157], v142 offset:12288
	ds_read_b128 v[158:161], v142 offset:14336
	s_waitcnt lgkmcnt(0)
	v_mfma_f32_16x16x32_bf16 v[116:119], v[162:165], v[216:219], v[116:119]
	v_mfma_f32_16x16x32_bf16 v[108:111], v[166:169], v[216:219], v[108:111]
	v_mfma_f32_16x16x32_bf16 v[100:103], v[170:173], v[216:219], v[100:103]
	v_mfma_f32_16x16x32_bf16 v[88:91], v[174:177], v[216:219], v[88:91]
	v_mfma_f32_16x16x32_bf16 v[76:79], v[162:165], v[220:223], v[76:79]
	v_mfma_f32_16x16x32_bf16 v[68:71], v[166:169], v[220:223], v[68:71]
	v_mfma_f32_16x16x32_bf16 v[56:59], v[170:173], v[220:223], v[56:59]
	v_mfma_f32_16x16x32_bf16 v[44:47], v[174:177], v[220:223], v[44:47]
	v_mfma_f32_16x16x32_bf16 v[36:39], v[162:165], v[224:227], v[36:39]
	v_mfma_f32_16x16x32_bf16 v[32:35], v[166:169], v[224:227], v[32:35]
	v_mfma_f32_16x16x32_bf16 v[28:31], v[170:173], v[224:227], v[28:31]
	v_mfma_f32_16x16x32_bf16 v[24:27], v[174:177], v[224:227], v[24:27]
	v_mfma_f32_16x16x32_bf16 v[20:23], v[162:165], v[228:231], v[20:23]
	v_mfma_f32_16x16x32_bf16 v[16:19], v[166:169], v[228:231], v[16:19]
	v_mfma_f32_16x16x32_bf16 v[12:15], v[170:173], v[228:231], v[12:15]
	v_mfma_f32_16x16x32_bf16 v[8:11], v[174:177], v[228:231], v[8:11]
	v_mfma_f32_16x16x32_bf16 v[4:7], v[162:165], v[138:141], v[4:7]
	s_add_u32 s34, s34, 0x80
	s_addc_u32 s35, s35, 0
	v_mfma_f32_16x16x32_bf16 v[0:3], v[166:169], v[138:141], v[0:3]
	s_cmpk_eq_i32 s34, 0x780
	s_mov_b32 s2, s3
	s_waitcnt vmcnt(0)
	v_mfma_f32_16x16x32_bf16 v[40:43], v[170:173], v[138:141], v[40:43]
	s_barrier
	v_mfma_f32_16x16x32_bf16 v[48:51], v[174:177], v[138:141], v[48:51]
	v_mfma_f32_16x16x32_bf16 v[52:55], v[162:165], v[146:149], v[52:55]
	v_mfma_f32_16x16x32_bf16 v[60:63], v[166:169], v[146:149], v[60:63]
	v_mfma_f32_16x16x32_bf16 v[64:67], v[170:173], v[146:149], v[64:67]
	v_mfma_f32_16x16x32_bf16 v[72:75], v[174:177], v[146:149], v[72:75]
	v_mfma_f32_16x16x32_bf16 v[80:83], v[162:165], v[154:157], v[80:83]
	v_mfma_f32_16x16x32_bf16 v[84:87], v[166:169], v[154:157], v[84:87]
	v_mfma_f32_16x16x32_bf16 v[92:95], v[170:173], v[154:157], v[92:95]
	v_mfma_f32_16x16x32_bf16 v[96:99], v[174:177], v[154:157], v[96:99]
	v_mfma_f32_16x16x32_bf16 v[104:107], v[162:165], v[158:161], v[104:107]
	v_mfma_f32_16x16x32_bf16 v[112:115], v[166:169], v[158:161], v[112:115]
	v_mfma_f32_16x16x32_bf16 v[120:123], v[170:173], v[158:161], v[120:123]
	v_mfma_f32_16x16x32_bf16 v[124:127], v[174:177], v[158:161], v[124:127]
	s_cbranch_scc1 .Lkx_670
.Lkb_670_l:
	s_add_i32 s3, s2, 0x10000
	s_and_b32 s23, s3, 0x10000
	s_add_i32 s23, s0, s23
	s_and_b32 s2, s2, 0x10000
	v_or_b32_e32 v142, s2, v137
	v_add_u32_e32 v143, v142, v136
	v_add_u32_e32 v142, v142, v134
	ds_read_b128 v[138:141], v143 offset:32768
	ds_read_b128 v[146:149], v143 offset:34816
	ds_read_b128 v[154:157], v143 offset:36864
	ds_read_b128 v[158:161], v143 offset:38912
	ds_read_b128 v[162:165], v142
	ds_read_b128 v[166:169], v142 offset:2048
	ds_read_b128 v[170:173], v142 offset:4096
	ds_read_b128 v[174:177], v142 offset:6144
	ds_read_b128 v[178:181], v142 offset:8192
	ds_read_b128 v[182:185], v142 offset:10240
	ds_read_b128 v[186:189], v142 offset:12288
	ds_read_b128 v[206:209], v142 offset:14336
	s_waitcnt lgkmcnt(0)
	v_mfma_f32_16x16x32_bf16 v[116:119], v[138:141], v[162:165], v[116:119]
	v_mfma_f32_16x16x32_bf16 v[108:111], v[146:149], v[162:165], v[108:111]
	v_mfma_f32_16x16x32_bf16 v[100:103], v[154:157], v[162:165], v[100:103]
	v_mfma_f32_16x16x32_bf16 v[88:91], v[158:161], v[162:165], v[88:91]
	v_mfma_f32_16x16x32_bf16 v[76:79], v[138:141], v[166:169], v[76:79]
	v_mfma_f32_16x16x32_bf16 v[68:71], v[146:149], v[166:169], v[68:71]
	v_mfma_f32_16x16x32_bf16 v[56:59], v[154:157], v[166:169], v[56:59]
	v_mfma_f32_16x16x32_bf16 v[44:47], v[158:161], v[166:169], v[44:47]
	v_mfma_f32_16x16x32_bf16 v[36:39], v[138:141], v[170:173], v[36:39]
	v_mfma_f32_16x16x32_bf16 v[32:35], v[146:149], v[170:173], v[32:35]
	v_mfma_f32_16x16x32_bf16 v[28:31], v[154:157], v[170:173], v[28:31]
	v_mfma_f32_16x16x32_bf16 v[24:27], v[158:161], v[170:173], v[24:27]
	v_mfma_f32_16x16x32_bf16 v[20:23], v[138:141], v[174:177], v[20:23]
	v_mfma_f32_16x16x32_bf16 v[16:19], v[146:149], v[174:177], v[16:19]
	v_mfma_f32_16x16x32_bf16 v[12:15], v[154:157], v[174:177], v[12:15]
	v_mfma_f32_16x16x32_bf16 v[8:11], v[158:161], v[174:177], v[8:11]
	v_or_b32_e32 v142, s2, v135
	v_add_u32_e32 v143, v142, v136
	v_add_u32_e32 v142, v142, v134
	ds_read_b128 v[162:165], v143 offset:32768
	ds_read_b128 v[166:169], v143 offset:34816
	ds_read_b128 v[170:173], v143 offset:36864
	ds_read_b128 v[174:177], v143 offset:38912
	ds_read_b128 v[216:219], v142
	ds_read_b128 v[220:223], v142 offset:2048
	ds_read_b128 v[224:227], v142 offset:4096
	ds_read_b128 v[228:231], v142 offset:6144
	v_mfma_f32_16x16x32_bf16 v[4:7], v[138:141], v[178:181], v[4:7]
	v_mfma_f32_16x16x32_bf16 v[0:3], v[146:149], v[178:181], v[0:3]
	v_mfma_f32_16x16x32_bf16 v[40:43], v[154:157], v[178:181], v[40:43]
	v_mfma_f32_16x16x32_bf16 v[48:51], v[158:161], v[178:181], v[48:51]
	v_mfma_f32_16x16x32_bf16 v[52:55], v[138:141], v[182:185], v[52:55]
	v_mfma_f32_16x16x32_bf16 v[60:63], v[146:149], v[182:185], v[60:63]
	v_mfma_f32_16x16x32_bf16 v[64:67], v[154:157], v[182:185], v[64:67]
	v_mfma_f32_16x16x32_bf16 v[72:75], v[158:161], v[182:185], v[72:75]
	v_mfma_f32_16x16x32_bf16 v[80:83], v[138:141], v[186:189], v[80:83]
	v_mfma_f32_16x16x32_bf16 v[84:87], v[146:149], v[186:189], v[84:87]
	v_mfma_f32_16x16x32_bf16 v[92:95], v[154:157], v[186:189], v[92:95]
	v_mfma_f32_16x16x32_bf16 v[96:99], v[158:161], v[186:189], v[96:99]
	v_mfma_f32_16x16x32_bf16 v[104:107], v[138:141], v[206:209], v[104:107]
	v_mfma_f32_16x16x32_bf16 v[112:115], v[146:149], v[206:209], v[112:115]
	v_mfma_f32_16x16x32_bf16 v[120:123], v[154:157], v[206:209], v[120:123]
	v_mfma_f32_16x16x32_bf16 v[124:127], v[158:161], v[206:209], v[124:127]
	s_add_u32 s48, s50, s34
	s_addc_u32 s49, s51, s35
	s_add_u32 s98, s48, s10
	s_addc_u32 s99, s49, s11
	s_mov_b32 m0, s23
	s_nop 0
	global_load_lds_dwordx4 v244, s[98:99]
	s_add_u32 s98, s48, s4
	s_addc_u32 s99, s49, s5
	s_add_i32 m0, s23, 0x2000
	s_nop 0
	global_load_lds_dwordx4 v244, s[98:99]
	s_add_u32 s98, s48, s92
	s_addc_u32 s99, s49, s93
	s_add_i32 m0, s23, 0x4000
	s_add_u32 s48, s48, s94
	s_addc_u32 s49, s49, s95
	global_load_lds_dwordx4 v244, s[98:99]
	s_add_i32 m0, s23, 0x6000
	s_nop 0
	global_load_lds_dwordx4 v244, s[48:49]
	s_add_u32 s48, s50, s34
	s_addc_u32 s49, s51, s35
	s_add_u32 s98, s48, s10
	s_addc_u32 s99, s49, s11
	s_add_i32 m0, s23, 0x8000
	s_nop 0
	global_load_lds_dwordx4 v245, s[98:99]
	s_add_u32 s98, s48, s4
	s_addc_u32 s99, s49, s5
	s_add_i32 m0, s23, 0xa000
	s_nop 0
	global_load_lds_dwordx4 v245, s[98:99]
	s_add_u32 s98, s48, s92
	s_addc_u32 s99, s49, s93
	s_add_i32 m0, s23, 0xc000
	s_add_u32 s48, s48, s94
	s_addc_u32 s49, s49, s95
	global_load_lds_dwordx4 v245, s[98:99]
	s_add_i32 m0, s23, 0xe000
	s_nop 0
	global_load_lds_dwordx4 v245, s[48:49]
	ds_read_b128 v[138:141], v142 offset:8192
	ds_read_b128 v[146:149], v142 offset:10240
	ds_read_b128 v[154:157], v142 offset:12288
	ds_read_b128 v[158:161], v142 offset:14336
	s_waitcnt lgkmcnt(0)
	v_mfma_f32_16x16x32_bf16 v[116:119], v[162:165], v[216:219], v[116:119]
	v_mfma_f32_16x16x32_bf16 v[108:111], v[166:169], v[216:219], v[108:111]
	v_mfma_f32_16x16x32_bf16 v[100:103], v[170:173], v[216:219], v[100:103]
	v_mfma_f32_16x16x32_bf16 v[88:91], v[174:177], v[216:219], v[88:91]
	v_mfma_f32_16x16x32_bf16 v[76:79], v[162:165], v[220:223], v[76:79]
	v_mfma_f32_16x16x32_bf16 v[68:71], v[166:169], v[220:223], v[68:71]
	v_mfma_f32_16x16x32_bf16 v[56:59], v[170:173], v[220:223], v[56:59]
	v_mfma_f32_16x16x32_bf16 v[44:47], v[174:177], v[220:223], v[44:47]
	v_mfma_f32_16x16x32_bf16 v[36:39], v[162:165], v[224:227], v[36:39]
	v_mfma_f32_16x16x32_bf16 v[32:35], v[166:169], v[224:227], v[32:35]
	v_mfma_f32_16x16x32_bf16 v[28:31], v[170:173], v[224:227], v[28:31]
	v_mfma_f32_16x16x32_bf16 v[24:27], v[174:177], v[224:227], v[24:27]
	v_mfma_f32_16x16x32_bf16 v[20:23], v[162:165], v[228:231], v[20:23]
	v_mfma_f32_16x16x32_bf16 v[16:19], v[166:169], v[228:231], v[16:19]
	v_mfma_f32_16x16x32_bf16 v[12:15], v[170:173], v[228:231], v[12:15]
	v_mfma_f32_16x16x32_bf16 v[8:11], v[174:177], v[228:231], v[8:11]
	v_mfma_f32_16x16x32_bf16 v[4:7], v[162:165], v[138:141], v[4:7]
	s_add_u32 s34, s34, 0x80
	s_addc_u32 s35, s35, 0
	v_mfma_f32_16x16x32_bf16 v[0:3], v[166:169], v[138:141], v[0:3]
	s_cmpk_eq_i32 s34, 0x780
	s_mov_b32 s2, s3
	s_waitcnt vmcnt(0)
	v_mfma_f32_16x16x32_bf16 v[40:43], v[170:173], v[138:141], v[40:43]
	s_barrier
	v_mfma_f32_16x16x32_bf16 v[48:51], v[174:177], v[138:141], v[48:51]
	v_mfma_f32_16x16x32_bf16 v[52:55], v[162:165], v[146:149], v[52:55]
	v_mfma_f32_16x16x32_bf16 v[60:63], v[166:169], v[146:149], v[60:63]
	v_mfma_f32_16x16x32_bf16 v[64:67], v[170:173], v[146:149], v[64:67]
	v_mfma_f32_16x16x32_bf16 v[72:75], v[174:177], v[146:149], v[72:75]
	v_mfma_f32_16x16x32_bf16 v[80:83], v[162:165], v[154:157], v[80:83]
	v_mfma_f32_16x16x32_bf16 v[84:87], v[166:169], v[154:157], v[84:87]
	v_mfma_f32_16x16x32_bf16 v[92:95], v[170:173], v[154:157], v[92:95]
	v_mfma_f32_16x16x32_bf16 v[96:99], v[174:177], v[154:157], v[96:99]
	v_mfma_f32_16x16x32_bf16 v[104:107], v[162:165], v[158:161], v[104:107]
	v_mfma_f32_16x16x32_bf16 v[112:115], v[166:169], v[158:161], v[112:115]
	v_mfma_f32_16x16x32_bf16 v[120:123], v[170:173], v[158:161], v[120:123]
	v_mfma_f32_16x16x32_bf16 v[124:127], v[174:177], v[158:161], v[124:127]
	s_cbranch_scc0 .Lkb_670_l
